# S5 jobs also store bf16(Y5) in place over the dead PJ u-columns; GLU full tiles read that bf16 copy with the 16x16x32 swizzled-LDS k-loop (no in-loop f32->bf16 conversion)
# speedup vs baseline: 1.0107x; 1.0107x over previous
.LBB0_478:
	s_or_b64 exec, exec, s[76:77]
	s_waitcnt vmcnt(11)
	v_mul_f32_e32 v4, v77, v77
	v_fma_f32 v81, v78, v78, -v4
	v_mul_f32_e32 v4, v78, v77
	v_fma_f32 v82, v4, 2.0, 0
	v_mul_f32_e32 v4, v77, v82
	v_fma_f32 v4, v78, v81, -v4
	v_add_f32_e32 v83, 0, v4
	v_mul_f32_e32 v4, v78, v82
	v_fmac_f32_e32 v4, v77, v81
	v_add_f32_e32 v84, 0, v4
	v_mul_f32_e32 v4, v82, v82
	v_fma_f32 v85, v81, v81, -v4
	v_mul_f32_e32 v4, v81, v82
	v_fma_f32 v86, v4, 2.0, 0
	s_waitcnt vmcnt(9)
	v_mul_f32_e32 v4, v67, v67
	v_fma_f32 v73, v68, v68, -v4
	v_mul_f32_e32 v4, v68, v67
	v_fma_f32 v74, v4, 2.0, 0
	v_mul_f32_e32 v4, v67, v74
	v_mul_f32_e32 v20, v74, v74
	v_fma_f32 v4, v68, v73, -v4
	v_fma_f32 v71, v73, v73, -v20
	v_mul_f32_e32 v20, v73, v74
	v_cmp_lt_i32_e32 vcc, v152, v117
	v_add_f32_e32 v69, 0, v4
	v_mul_f32_e32 v4, v68, v74
	v_fma_f32 v72, v20, 2.0, 0
	v_cndmask_b32_e32 v20, v103, v152, vcc
	v_fmac_f32_e32 v4, v67, v73
	v_lshlrev_b32_e32 v87, 2, v20
	s_waitcnt vmcnt(0)
	v_mfma_f32_32x32x16_bf16 v[16:31], v[56:59], v[16:19], 0
	v_add_f32_e32 v70, 0, v4
	v_mfma_f32_32x32x16_bf16 v[0:15], v[56:59], v[0:3], 0
	s_nop 9
	v_mul_f32_e32 v64, v77, v16
	s_nop 0
	v_fma_f32 v64, v78, v0, -v64
	v_add_f32_e32 v1, v1, v64
	v_mul_f32_e32 v64, v78, v16
	v_fmac_f32_e32 v64, v77, v0
	v_add_f32_e32 v17, v17, v64
	v_mul_f32_e32 v64, v77, v17
	v_fma_f32 v64, v78, v1, -v64
	v_add_f32_e32 v2, v2, v64
	v_mul_f32_e32 v64, v77, v1
	v_fmac_f32_e32 v64, v78, v17
	v_add_f32_e32 v18, v18, v64
	v_mul_f32_e32 v64, v77, v18
	v_fma_f32 v64, v78, v2, -v64
	v_add_f32_e32 v3, v3, v64
	v_mul_f32_e32 v64, v77, v2
	v_fmac_f32_e32 v64, v78, v18
	v_add_f32_e32 v19, v19, v64
	v_mul_f32_e32 v64, v77, v20
	v_fma_f32 v64, v78, v4, -v64
	v_add_f32_e32 v5, v5, v64
	v_mul_f32_e32 v64, v78, v20
	v_fmac_f32_e32 v64, v77, v4
	v_add_f32_e32 v21, v21, v64
	v_mul_f32_e32 v64, v77, v21
	v_fma_f32 v64, v78, v5, -v64
	v_add_f32_e32 v6, v6, v64
	v_mul_f32_e32 v64, v77, v5
	v_fmac_f32_e32 v64, v78, v21
	v_add_f32_e32 v22, v22, v64
	v_mul_f32_e32 v64, v77, v22
	v_fma_f32 v64, v78, v6, -v64
	v_add_f32_e32 v7, v7, v64
	v_mul_f32_e32 v64, v77, v6
	v_fmac_f32_e32 v64, v78, v22
	v_add_f32_e32 v23, v23, v64
	v_mul_f32_e32 v64, v77, v24
	v_fma_f32 v64, v78, v8, -v64
	v_add_f32_e32 v9, v9, v64
	v_mul_f32_e32 v64, v78, v24
	v_fmac_f32_e32 v64, v77, v8
	v_add_f32_e32 v25, v25, v64
	v_mul_f32_e32 v64, v77, v25
	v_fma_f32 v64, v78, v9, -v64
	v_add_f32_e32 v10, v10, v64
	v_mul_f32_e32 v64, v77, v9
	v_fmac_f32_e32 v64, v78, v25
	v_add_f32_e32 v26, v26, v64
	v_mul_f32_e32 v64, v77, v26
	v_fma_f32 v64, v78, v10, -v64
	v_add_f32_e32 v11, v11, v64
	v_mul_f32_e32 v64, v77, v10
	v_fmac_f32_e32 v64, v78, v26
	v_add_f32_e32 v27, v27, v64
	v_mul_f32_e32 v64, v77, v28
	v_fma_f32 v64, v78, v12, -v64
	v_add_f32_e32 v13, v13, v64
	v_mul_f32_e32 v64, v78, v28
	v_fmac_f32_e32 v64, v77, v12
	v_add_f32_e32 v29, v29, v64
	v_mul_f32_e32 v64, v77, v29
	v_fma_f32 v64, v78, v13, -v64
	v_add_f32_e32 v14, v14, v64
	v_mul_f32_e32 v64, v77, v13
	v_fmac_f32_e32 v64, v78, v29
	v_add_f32_e32 v30, v30, v64
	v_mul_f32_e32 v64, v77, v30
	v_fma_f32 v64, v78, v14, -v64
	v_add_f32_e32 v15, v15, v64
	v_mul_f32_e32 v64, v77, v14
	v_fmac_f32_e32 v64, v78, v30
	ds_bpermute_b32 v65, v87, v19
	v_add_f32_e32 v31, v31, v64
	ds_bpermute_b32 v64, v87, v3
	ds_bpermute_b32 v88, v87, v7
	ds_bpermute_b32 v89, v87, v23
	s_waitcnt lgkmcnt(3)
	v_cndmask_b32_e64 v95, v65, v19, s[4:5]
	v_cndmask_b32_e64 v109, v19, v65, s[4:5]
	v_mul_f32_e32 v65, v80, v86
	s_waitcnt lgkmcnt(2)
	v_cndmask_b32_e64 v94, v64, v3, s[4:5]
	v_fma_f32 v65, v79, v85, -v65
	v_add_f32_e32 v94, v65, v94
	v_mul_f32_e32 v65, v79, v86
	v_fmac_f32_e32 v65, v80, v85
	v_add_f32_e32 v95, v65, v95
	v_mul_f32_e32 v65, v86, v95
	v_cndmask_b32_e64 v64, v3, v64, s[4:5]
	v_fma_f32 v65, v85, v94, -v65
	v_add_f32_e32 v65, v64, v65
	v_mul_f32_e32 v64, v86, v94
	v_fmac_f32_e32 v64, v85, v95
	v_add_f32_e32 v64, v109, v64
	v_mul_f32_e32 v109, v86, v64
	v_cndmask_b32_e64 v79, v94, v79, s[4:5]
	s_waitcnt lgkmcnt(1)
	v_cndmask_b32_e64 v94, v88, v7, s[4:5]
	v_fma_f32 v109, v85, v65, -v109
	v_add_f32_e32 v94, v94, v109
	v_mul_f32_e32 v109, v86, v65
	v_cndmask_b32_e64 v80, v95, v80, s[4:5]
	s_waitcnt lgkmcnt(0)
	v_cndmask_b32_e64 v95, v89, v23, s[4:5]
	v_fmac_f32_e32 v109, v85, v64
	v_add_f32_e32 v95, v95, v109
	v_mul_f32_e32 v109, v86, v95
	ds_bpermute_b32 v90, v87, v11
	v_cndmask_b32_e64 v88, v7, v88, s[4:5]
	v_fma_f32 v109, v85, v94, -v109
	v_add_f32_e32 v88, v88, v109
	v_mul_f32_e32 v109, v86, v94
	ds_bpermute_b32 v91, v87, v27
	v_cndmask_b32_e64 v89, v23, v89, s[4:5]
	v_fmac_f32_e32 v109, v85, v95
	v_add_f32_e32 v89, v89, v109
	v_mul_f32_e32 v143, v86, v89
	s_waitcnt lgkmcnt(1)
	v_cndmask_b32_e64 v109, v90, v11, s[4:5]
	v_fma_f32 v143, v85, v88, -v143
	v_add_f32_e32 v109, v109, v143
	v_mul_f32_e32 v143, v86, v88
	s_waitcnt lgkmcnt(0)
	v_cndmask_b32_e64 v139, v91, v27, s[4:5]
	v_fmac_f32_e32 v143, v85, v89
	v_add_f32_e32 v139, v139, v143
	ds_bpermute_b32 v93, v87, v31
	v_mul_f32_e32 v143, v86, v139
	v_cndmask_b32_e64 v90, v11, v90, s[4:5]
	v_fma_f32 v143, v85, v109, -v143
	ds_bpermute_b32 v92, v87, v15
	v_add_f32_e32 v90, v90, v143
	v_mul_f32_e32 v143, v86, v109
	v_cndmask_b32_e64 v91, v27, v91, s[4:5]
	v_fmac_f32_e32 v143, v85, v139
	v_add_f32_e32 v91, v91, v143
	v_cndmask_b32_e64 v88, v109, v88, s[4:5]
	v_mul_f32_e32 v109, v86, v90
	s_waitcnt lgkmcnt(1)
	v_cndmask_b32_e64 v93, v93, v31, s[4:5]
	v_fmac_f32_e32 v109, v85, v91
	v_add_f32_e32 v93, v93, v109
	v_mul_f32_e32 v109, v86, v91
	s_waitcnt lgkmcnt(0)
	v_cndmask_b32_e64 v92, v92, v15, s[4:5]
	v_fma_f32 v109, v85, v90, -v109
	v_add_f32_e32 v92, v92, v109
	v_cndmask_b32_e64 v90, v92, v90, s[4:5]
	v_mul_f32_e32 v92, v77, v80
	v_fma_f32 v92, v78, v79, -v92
	v_add_f32_e32 v0, v0, v92
	v_mul_f32_e32 v92, v78, v80
	v_fmac_f32_e32 v92, v77, v79
	v_add_f32_e32 v16, v16, v92
	v_bfe_u32 v92, v0, 16, 1
	v_add3_u32 v0, v0, v92, s83
	ds_write_b16_d16_hi v163, v0
	v_bfe_u32 v0, v16, 16, 1
	v_add3_u32 v0, v16, v0, s83
	ds_write_b16_d16_hi v163, v0 offset:128
	v_mul_f32_e32 v0, v82, v80
	v_fma_f32 v0, v81, v79, -v0
	v_add_f32_e32 v0, v1, v0
	v_mul_f32_e32 v1, v81, v80
	v_fmac_f32_e32 v1, v82, v79
	v_bfe_u32 v16, v0, 16, 1
	v_add_f32_e32 v1, v17, v1
	v_add3_u32 v0, v0, v16, s83
	ds_write_b16_d16_hi v163, v0 offset:272
	v_bfe_u32 v0, v1, 16, 1
	v_add3_u32 v0, v1, v0, s83
	ds_write_b16_d16_hi v163, v0 offset:400
	v_mul_f32_e32 v0, v84, v80
	v_fma_f32 v0, v83, v79, -v0
	v_add_f32_e32 v0, v2, v0
	v_mul_f32_e32 v1, v83, v80
	v_fmac_f32_e32 v1, v84, v79
	v_bfe_u32 v2, v0, 16, 1
	v_add_f32_e32 v1, v18, v1
	v_add3_u32 v0, v0, v2, s83
	ds_write_b16_d16_hi v163, v0 offset:544
	v_bfe_u32 v0, v1, 16, 1
	v_add3_u32 v0, v1, v0, s83
	ds_write_b16_d16_hi v163, v0 offset:672
	v_mul_f32_e32 v0, v86, v80
	v_fma_f32 v0, v85, v79, -v0
	v_add_f32_e32 v0, v3, v0
	v_mul_f32_e32 v1, v85, v80
	v_fmac_f32_e32 v1, v86, v79
	v_bfe_u32 v2, v0, 16, 1
	v_add_f32_e32 v1, v19, v1
	v_add3_u32 v0, v0, v2, s83
	ds_write_b16_d16_hi v163, v0 offset:816
	v_bfe_u32 v0, v1, 16, 1
	v_cndmask_b32_e64 v95, v95, v64, s[4:5]
	v_add3_u32 v0, v1, v0, s83
	v_cndmask_b32_e64 v94, v94, v65, s[4:5]
	ds_write_b16_d16_hi v163, v0 offset:944
	v_mul_f32_e32 v0, v77, v95
	v_fma_f32 v0, v78, v94, -v0
	v_add_f32_e32 v0, v4, v0
	v_mul_f32_e32 v1, v78, v95
	v_fmac_f32_e32 v1, v77, v94
	v_bfe_u32 v2, v0, 16, 1
	v_add_f32_e32 v1, v20, v1
	v_add3_u32 v0, v0, v2, s83
	ds_write_b16_d16_hi v163, v0 offset:2176
	v_bfe_u32 v0, v1, 16, 1
	v_add3_u32 v0, v1, v0, s83
	ds_write_b16_d16_hi v163, v0 offset:2304
	v_mul_f32_e32 v0, v82, v95
	v_fma_f32 v0, v81, v94, -v0
	v_add_f32_e32 v0, v5, v0
	v_mul_f32_e32 v1, v81, v95
	v_fmac_f32_e32 v1, v82, v94
	v_bfe_u32 v2, v0, 16, 1
	v_add_f32_e32 v1, v21, v1
	v_add3_u32 v0, v0, v2, s83
	ds_write_b16_d16_hi v163, v0 offset:2448
	v_bfe_u32 v0, v1, 16, 1
	v_add3_u32 v0, v1, v0, s83
	ds_write_b16_d16_hi v163, v0 offset:2576
	v_mul_f32_e32 v0, v84, v95
	v_fma_f32 v0, v83, v94, -v0
	v_add_f32_e32 v0, v6, v0
	v_mul_f32_e32 v1, v83, v95
	v_fmac_f32_e32 v1, v84, v94
	v_bfe_u32 v2, v0, 16, 1
	v_add_f32_e32 v1, v22, v1
	v_add3_u32 v0, v0, v2, s83
	ds_write_b16_d16_hi v163, v0 offset:2720
	v_bfe_u32 v0, v1, 16, 1
	v_add3_u32 v0, v1, v0, s83
	ds_write_b16_d16_hi v163, v0 offset:2848
	v_mul_f32_e32 v0, v86, v95
	v_fma_f32 v0, v85, v94, -v0
	v_add_f32_e32 v0, v7, v0
	v_mul_f32_e32 v1, v85, v95
	v_fmac_f32_e32 v1, v86, v94
	v_bfe_u32 v2, v0, 16, 1
	v_add_f32_e32 v1, v23, v1
	v_add3_u32 v0, v0, v2, s83
	ds_write_b16_d16_hi v163, v0 offset:2992
	v_bfe_u32 v0, v1, 16, 1
	v_cndmask_b32_e64 v89, v139, v89, s[4:5]
	v_add3_u32 v0, v1, v0, s83
	ds_write_b16_d16_hi v163, v0 offset:3120
	v_mul_f32_e32 v0, v77, v89
	v_fma_f32 v0, v78, v88, -v0
	v_add_f32_e32 v0, v8, v0
	v_mul_f32_e32 v1, v78, v89
	v_fmac_f32_e32 v1, v77, v88
	v_bfe_u32 v2, v0, 16, 1
	v_add_f32_e32 v1, v24, v1
	v_add3_u32 v0, v0, v2, s83
	ds_write_b16_d16_hi v163, v0 offset:4352
	v_bfe_u32 v0, v1, 16, 1
	v_add3_u32 v0, v1, v0, s83
	ds_write_b16_d16_hi v163, v0 offset:4480
	v_mul_f32_e32 v0, v82, v89
	v_fma_f32 v0, v81, v88, -v0
	v_add_f32_e32 v0, v9, v0
	v_mul_f32_e32 v1, v81, v89
	v_fmac_f32_e32 v1, v82, v88
	v_bfe_u32 v2, v0, 16, 1
	v_add_f32_e32 v1, v25, v1
	v_add3_u32 v0, v0, v2, s83
	ds_write_b16_d16_hi v163, v0 offset:4624
	v_bfe_u32 v0, v1, 16, 1
	v_add3_u32 v0, v1, v0, s83
	ds_write_b16_d16_hi v163, v0 offset:4752
	v_mul_f32_e32 v0, v84, v89
	v_fma_f32 v0, v83, v88, -v0
	v_add_f32_e32 v0, v10, v0
	v_mul_f32_e32 v1, v83, v89
	v_fmac_f32_e32 v1, v84, v88
	v_bfe_u32 v2, v0, 16, 1
	v_add_f32_e32 v1, v26, v1
	v_add3_u32 v0, v0, v2, s83
	ds_write_b16_d16_hi v163, v0 offset:4896
	v_bfe_u32 v0, v1, 16, 1
	v_add3_u32 v0, v1, v0, s83
	ds_write_b16_d16_hi v163, v0 offset:5024
	v_mul_f32_e32 v0, v86, v89
	v_fma_f32 v0, v85, v88, -v0
	v_add_f32_e32 v0, v11, v0
	v_mul_f32_e32 v1, v85, v89
	v_fmac_f32_e32 v1, v86, v88
	v_bfe_u32 v2, v0, 16, 1
	v_add_f32_e32 v1, v27, v1
	v_add3_u32 v0, v0, v2, s83
	ds_write_b16_d16_hi v163, v0 offset:5168
	v_bfe_u32 v0, v1, 16, 1
	v_cndmask_b32_e64 v91, v93, v91, s[4:5]
	v_add3_u32 v0, v1, v0, s83
	ds_write_b16_d16_hi v163, v0 offset:5296
	v_mul_f32_e32 v0, v77, v91
	v_fma_f32 v0, v78, v90, -v0
	v_add_f32_e32 v0, v12, v0
	v_mul_f32_e32 v1, v78, v91
	v_fmac_f32_e32 v1, v77, v90
	v_bfe_u32 v2, v0, 16, 1
	v_add_f32_e32 v1, v28, v1
	v_add3_u32 v0, v0, v2, s83
	ds_write_b16_d16_hi v163, v0 offset:6528
	v_bfe_u32 v0, v1, 16, 1
	v_add3_u32 v0, v1, v0, s83
	ds_write_b16_d16_hi v163, v0 offset:6656
	v_mul_f32_e32 v0, v82, v91
	v_fma_f32 v0, v81, v90, -v0
	v_add_f32_e32 v0, v13, v0
	v_mul_f32_e32 v1, v81, v91
	v_fmac_f32_e32 v1, v82, v90
	v_bfe_u32 v2, v0, 16, 1
	v_add_f32_e32 v1, v29, v1
	v_add3_u32 v0, v0, v2, s83
	ds_write_b16_d16_hi v163, v0 offset:6800
	v_bfe_u32 v0, v1, 16, 1
	v_add3_u32 v0, v1, v0, s83
	ds_write_b16_d16_hi v163, v0 offset:6928
	v_mul_f32_e32 v0, v84, v91
	v_fma_f32 v0, v83, v90, -v0
	v_add_f32_e32 v0, v14, v0
	v_mul_f32_e32 v1, v83, v91
	v_fmac_f32_e32 v1, v84, v90
	v_bfe_u32 v2, v0, 16, 1
	v_add_f32_e32 v1, v30, v1
	v_add3_u32 v0, v0, v2, s83
	ds_write_b16_d16_hi v163, v0 offset:7072
	v_bfe_u32 v0, v1, 16, 1
	v_add3_u32 v0, v1, v0, s83
	ds_write_b16_d16_hi v163, v0 offset:7200
	v_mul_f32_e32 v0, v86, v91
	v_fma_f32 v0, v85, v90, -v0
	v_add_f32_e32 v16, v15, v0
	v_mul_f32_e32 v17, v85, v91
	v_fmac_f32_e32 v17, v86, v90
	v_bfe_u32 v18, v16, 16, 1
	v_add_f32_e32 v17, v31, v17
	v_add3_u32 v16, v16, v18, s83
	ds_write_b16_d16_hi v163, v16 offset:7344
	v_bfe_u32 v16, v17, 16, 1
	v_add3_u32 v16, v17, v16, s83
	ds_write_b16_d16_hi v163, v16 offset:7472
	v_mfma_f32_32x32x16_bf16 v[16:31], v[56:59], v[48:51], 0
	v_mfma_f32_32x32x16_bf16 v[0:15], v[56:59], v[52:55], 0
	s_nop 10
	v_mul_f32_e32 v48, v67, v16
	v_fma_f32 v48, v68, v0, -v48
	v_add_f32_e32 v1, v1, v48
	v_mul_f32_e32 v48, v68, v16
	v_fmac_f32_e32 v48, v67, v0
	v_add_f32_e32 v17, v17, v48
	v_mul_f32_e32 v48, v67, v17
	v_fma_f32 v48, v68, v1, -v48
	v_add_f32_e32 v2, v2, v48
	v_mul_f32_e32 v48, v67, v1
	v_fmac_f32_e32 v48, v68, v17
	v_add_f32_e32 v18, v18, v48
	v_mul_f32_e32 v48, v67, v18
	v_fma_f32 v48, v68, v2, -v48
	v_add_f32_e32 v3, v3, v48
	v_mul_f32_e32 v48, v67, v2
	v_fmac_f32_e32 v48, v68, v18
	v_add_f32_e32 v19, v19, v48
	v_mul_f32_e32 v48, v67, v20
	v_fma_f32 v48, v68, v4, -v48
	v_add_f32_e32 v5, v5, v48
	v_mul_f32_e32 v48, v68, v20
	v_fmac_f32_e32 v48, v67, v4
	v_add_f32_e32 v21, v21, v48
	v_mul_f32_e32 v48, v67, v21
	v_fma_f32 v48, v68, v5, -v48
	v_add_f32_e32 v6, v6, v48
	v_mul_f32_e32 v48, v67, v5
	v_fmac_f32_e32 v48, v68, v21
	v_add_f32_e32 v22, v22, v48
	v_mul_f32_e32 v48, v67, v22
	v_fma_f32 v48, v68, v6, -v48
	v_add_f32_e32 v7, v7, v48
	v_mul_f32_e32 v48, v67, v6
	v_fmac_f32_e32 v48, v68, v22
	v_add_f32_e32 v23, v23, v48
	v_mul_f32_e32 v48, v67, v24
	v_fma_f32 v48, v68, v8, -v48
	v_add_f32_e32 v48, v9, v48
	v_mul_f32_e32 v9, v68, v24
	v_fmac_f32_e32 v9, v67, v8
	v_add_f32_e32 v25, v25, v9
	v_mul_f32_e32 v9, v67, v25
	v_fma_f32 v9, v68, v48, -v9
	v_add_f32_e32 v49, v10, v9
	v_mul_f32_e32 v9, v67, v48
	v_fmac_f32_e32 v9, v68, v25
	v_add_f32_e32 v26, v26, v9
	v_mul_f32_e32 v9, v67, v26
	v_fma_f32 v9, v68, v49, -v9
	v_add_f32_e32 v11, v11, v9
	v_mul_f32_e32 v9, v67, v49
	v_fmac_f32_e32 v9, v68, v26
	v_add_f32_e32 v27, v27, v9
	v_mul_f32_e32 v9, v67, v28
	v_fma_f32 v9, v68, v12, -v9
	v_add_f32_e32 v13, v13, v9
	v_mul_f32_e32 v9, v68, v28
	v_fmac_f32_e32 v9, v67, v12
	v_add_f32_e32 v29, v29, v9
	v_mul_f32_e32 v9, v67, v29
	v_fma_f32 v9, v68, v13, -v9
	v_add_f32_e32 v14, v14, v9
	v_mul_f32_e32 v9, v67, v13
	v_fmac_f32_e32 v9, v68, v29
	v_add_f32_e32 v30, v30, v9
	v_mul_f32_e32 v9, v67, v30
	v_fma_f32 v9, v68, v14, -v9
	v_add_f32_e32 v15, v15, v9
	v_mul_f32_e32 v9, v67, v14
	v_fmac_f32_e32 v9, v68, v30
	ds_bpermute_b32 v10, v87, v19
	v_add_f32_e32 v31, v31, v9
	ds_bpermute_b32 v9, v87, v3
	ds_bpermute_b32 v50, v87, v7
	ds_bpermute_b32 v51, v87, v23
	s_waitcnt lgkmcnt(3)
	v_cndmask_b32_e64 v57, v10, v19, s[4:5]
	v_cndmask_b32_e64 v58, v19, v10, s[4:5]
	v_mul_f32_e32 v10, v76, v72
	s_waitcnt lgkmcnt(2)
	v_cndmask_b32_e64 v56, v9, v3, s[4:5]
	v_fma_f32 v10, v75, v71, -v10
	v_add_f32_e32 v56, v10, v56
	v_mul_f32_e32 v10, v75, v72
	v_fmac_f32_e32 v10, v76, v71
	v_add_f32_e32 v57, v10, v57
	v_mul_f32_e32 v10, v72, v57
	v_cndmask_b32_e64 v9, v3, v9, s[4:5]
	v_fma_f32 v10, v71, v56, -v10
	v_add_f32_e32 v10, v9, v10
	v_mul_f32_e32 v9, v72, v56
	v_fmac_f32_e32 v9, v71, v57
	v_add_f32_e32 v9, v58, v9
	v_cndmask_b32_e64 v56, v56, v75, s[4:5]
	v_mul_f32_e32 v75, v72, v9
	s_waitcnt lgkmcnt(1)
	v_cndmask_b32_e64 v58, v50, v7, s[4:5]
	v_fma_f32 v75, v71, v10, -v75
	v_add_f32_e32 v58, v58, v75
	v_mul_f32_e32 v75, v72, v10
	s_waitcnt lgkmcnt(0)
	v_cndmask_b32_e64 v59, v51, v23, s[4:5]
	v_fmac_f32_e32 v75, v71, v9
	v_add_f32_e32 v59, v59, v75
	v_mul_f32_e32 v75, v72, v59
	ds_bpermute_b32 v52, v87, v11
	v_cndmask_b32_e64 v50, v7, v50, s[4:5]
	v_fma_f32 v75, v71, v58, -v75
	v_add_f32_e32 v50, v50, v75
	v_mul_f32_e32 v75, v72, v58
	ds_bpermute_b32 v53, v87, v27
	v_cndmask_b32_e64 v51, v23, v51, s[4:5]
	v_fmac_f32_e32 v75, v71, v59
	v_add_f32_e32 v51, v51, v75
	v_mul_f32_e32 v77, v72, v51
	s_waitcnt lgkmcnt(1)
	v_cndmask_b32_e64 v75, v52, v11, s[4:5]
	v_fma_f32 v77, v71, v50, -v77
	v_add_f32_e32 v75, v75, v77
	v_mul_f32_e32 v77, v72, v50
	v_cndmask_b32_e64 v57, v57, v76, s[4:5]
	s_waitcnt lgkmcnt(0)
	v_cndmask_b32_e64 v76, v53, v27, s[4:5]
	v_fmac_f32_e32 v77, v71, v51
	v_add_f32_e32 v76, v76, v77
	ds_bpermute_b32 v55, v87, v31
	v_mul_f32_e32 v77, v72, v76
	v_cndmask_b32_e64 v52, v11, v52, s[4:5]
	v_fma_f32 v77, v71, v75, -v77
	ds_bpermute_b32 v54, v87, v15
	v_add_f32_e32 v52, v52, v77
	v_mul_f32_e32 v77, v72, v75
	v_cndmask_b32_e64 v53, v27, v53, s[4:5]
	v_fmac_f32_e32 v77, v71, v76
	v_add_f32_e32 v53, v53, v77
	v_cndmask_b32_e64 v50, v75, v50, s[4:5]
	v_mul_f32_e32 v75, v72, v52
	s_waitcnt lgkmcnt(1)
	v_cndmask_b32_e64 v55, v55, v31, s[4:5]
	v_fmac_f32_e32 v75, v71, v53
	v_add_f32_e32 v55, v55, v75
	v_mul_f32_e32 v75, v72, v53
	s_waitcnt lgkmcnt(0)
	v_cndmask_b32_e64 v54, v54, v15, s[4:5]
	v_fma_f32 v75, v71, v52, -v75
	v_add_f32_e32 v54, v54, v75
	v_cndmask_b32_e64 v52, v54, v52, s[4:5]
	v_mul_f32_e32 v54, v67, v57
	v_fma_f32 v54, v68, v56, -v54
	v_add_f32_e32 v0, v0, v54
	v_mul_f32_e32 v54, v68, v57
	v_fmac_f32_e32 v54, v67, v56
	v_add_f32_e32 v16, v16, v54
	v_bfe_u32 v54, v0, 16, 1
	v_add3_u32 v0, v0, v54, s83
	ds_write_b16_d16_hi v164, v0
	v_bfe_u32 v0, v16, 16, 1
	v_add3_u32 v0, v16, v0, s83
	ds_write_b16_d16_hi v165, v0
	v_mul_f32_e32 v0, v74, v57
	v_fma_f32 v0, v73, v56, -v0
	v_add_f32_e32 v0, v1, v0
	v_mul_f32_e32 v1, v73, v57
	v_fmac_f32_e32 v1, v74, v56
	v_bfe_u32 v16, v0, 16, 1
	v_add_f32_e32 v1, v17, v1
	v_add3_u32 v0, v0, v16, s83
	ds_write_b16_d16_hi v164, v0 offset:272
	v_bfe_u32 v0, v1, 16, 1
	v_add3_u32 v0, v1, v0, s83
	ds_write_b16_d16_hi v165, v0 offset:272
	v_mul_f32_e32 v0, v70, v57
	v_fma_f32 v0, v69, v56, -v0
	v_add_f32_e32 v0, v2, v0
	v_mul_f32_e32 v1, v69, v57
	v_fmac_f32_e32 v1, v70, v56
	v_bfe_u32 v2, v0, 16, 1
	v_add_f32_e32 v1, v18, v1
	v_add3_u32 v0, v0, v2, s83
	ds_write_b16_d16_hi v164, v0 offset:544
	v_bfe_u32 v0, v1, 16, 1
	v_add3_u32 v0, v1, v0, s83
	ds_write_b16_d16_hi v165, v0 offset:544
	v_mul_f32_e32 v0, v72, v57
	v_fma_f32 v0, v71, v56, -v0
	v_add_f32_e32 v0, v3, v0
	v_mul_f32_e32 v1, v71, v57
	v_fmac_f32_e32 v1, v72, v56
	v_bfe_u32 v2, v0, 16, 1
	v_add_f32_e32 v1, v19, v1
	v_add3_u32 v0, v0, v2, s83
	ds_write_b16_d16_hi v164, v0 offset:816
	v_bfe_u32 v0, v1, 16, 1
	v_cndmask_b32_e64 v59, v59, v9, s[4:5]
	v_add3_u32 v0, v1, v0, s83
	v_cndmask_b32_e64 v58, v58, v10, s[4:5]
	ds_write_b16_d16_hi v165, v0 offset:816
	v_mul_f32_e32 v0, v67, v59
	v_fma_f32 v0, v68, v58, -v0
	v_add_f32_e32 v0, v4, v0
	v_mul_f32_e32 v1, v68, v59
	v_fmac_f32_e32 v1, v67, v58
	v_bfe_u32 v2, v0, 16, 1
	v_add_f32_e32 v1, v20, v1
	v_add3_u32 v0, v0, v2, s83
	ds_write_b16_d16_hi v164, v0 offset:2176
	v_bfe_u32 v0, v1, 16, 1
	v_add3_u32 v0, v1, v0, s83
	ds_write_b16_d16_hi v165, v0 offset:2176
	v_mul_f32_e32 v0, v74, v59
	v_fma_f32 v0, v73, v58, -v0
	v_add_f32_e32 v0, v5, v0
	v_mul_f32_e32 v1, v73, v59
	v_fmac_f32_e32 v1, v74, v58
	v_bfe_u32 v2, v0, 16, 1
	v_add_f32_e32 v1, v21, v1
	v_add3_u32 v0, v0, v2, s83
	ds_write_b16_d16_hi v164, v0 offset:2448
	v_bfe_u32 v0, v1, 16, 1
	v_add3_u32 v0, v1, v0, s83
	ds_write_b16_d16_hi v165, v0 offset:2448
	v_mul_f32_e32 v0, v70, v59
	v_fma_f32 v0, v69, v58, -v0
	v_add_f32_e32 v0, v6, v0
	v_mul_f32_e32 v1, v69, v59
	v_fmac_f32_e32 v1, v70, v58
	v_bfe_u32 v2, v0, 16, 1
	v_add_f32_e32 v1, v22, v1
	v_add3_u32 v0, v0, v2, s83
	ds_write_b16_d16_hi v164, v0 offset:2720
	v_bfe_u32 v0, v1, 16, 1
	v_add3_u32 v0, v1, v0, s83
	ds_write_b16_d16_hi v165, v0 offset:2720
	v_mul_f32_e32 v0, v72, v59
	v_fma_f32 v0, v71, v58, -v0
	v_add_f32_e32 v0, v7, v0
	v_mul_f32_e32 v1, v71, v59
	v_fmac_f32_e32 v1, v72, v58
	v_bfe_u32 v2, v0, 16, 1
	v_add_f32_e32 v1, v23, v1
	v_add3_u32 v0, v0, v2, s83
	ds_write_b16_d16_hi v164, v0 offset:2992
	v_bfe_u32 v0, v1, 16, 1
	v_cndmask_b32_e64 v51, v76, v51, s[4:5]
	v_add3_u32 v0, v1, v0, s83
	ds_write_b16_d16_hi v165, v0 offset:2992
	v_mul_f32_e32 v0, v67, v51
	v_fma_f32 v0, v68, v50, -v0
	v_add_f32_e32 v0, v8, v0
	v_mul_f32_e32 v1, v68, v51
	v_fmac_f32_e32 v1, v67, v50
	v_bfe_u32 v2, v0, 16, 1
	v_add_f32_e32 v1, v24, v1
	v_add3_u32 v0, v0, v2, s83
	ds_write_b16_d16_hi v164, v0 offset:4352
	v_bfe_u32 v0, v1, 16, 1
	v_add3_u32 v0, v1, v0, s83
	ds_write_b16_d16_hi v165, v0 offset:4352
	v_mul_f32_e32 v0, v74, v51
	v_fma_f32 v0, v73, v50, -v0
	v_add_f32_e32 v0, v48, v0
	v_mul_f32_e32 v1, v73, v51
	v_fmac_f32_e32 v1, v74, v50
	v_bfe_u32 v2, v0, 16, 1
	v_add_f32_e32 v1, v25, v1
	v_add3_u32 v0, v0, v2, s83
	ds_write_b16_d16_hi v164, v0 offset:4624
	v_bfe_u32 v0, v1, 16, 1
	v_add3_u32 v0, v1, v0, s83
	ds_write_b16_d16_hi v165, v0 offset:4624
	v_mul_f32_e32 v0, v70, v51
	v_fma_f32 v0, v69, v50, -v0
	v_add_f32_e32 v0, v49, v0
	v_mul_f32_e32 v1, v69, v51
	v_fmac_f32_e32 v1, v70, v50
	v_bfe_u32 v2, v0, 16, 1
	v_add_f32_e32 v1, v26, v1
	v_add3_u32 v0, v0, v2, s83
	ds_write_b16_d16_hi v164, v0 offset:4896
	v_bfe_u32 v0, v1, 16, 1
	v_add3_u32 v0, v1, v0, s83
	ds_write_b16_d16_hi v165, v0 offset:4896
	v_mul_f32_e32 v0, v72, v51
	v_fma_f32 v0, v71, v50, -v0
	v_add_f32_e32 v0, v11, v0
	v_mul_f32_e32 v1, v71, v51
	v_fmac_f32_e32 v1, v72, v50
	v_bfe_u32 v2, v0, 16, 1
	v_add_f32_e32 v1, v27, v1
	v_add3_u32 v0, v0, v2, s83
	ds_write_b16_d16_hi v164, v0 offset:5168
	v_bfe_u32 v0, v1, 16, 1
	v_cndmask_b32_e64 v53, v55, v53, s[4:5]
	v_add3_u32 v0, v1, v0, s83
	ds_write_b16_d16_hi v165, v0 offset:5168
	v_mul_f32_e32 v0, v67, v53
	v_fma_f32 v0, v68, v52, -v0
	v_add_f32_e32 v0, v12, v0
	v_mul_f32_e32 v1, v68, v53
	v_fmac_f32_e32 v1, v67, v52
	v_bfe_u32 v2, v0, 16, 1
	v_add_f32_e32 v1, v28, v1
	v_add3_u32 v0, v0, v2, s83
	ds_write_b16_d16_hi v164, v0 offset:6528
	v_bfe_u32 v0, v1, 16, 1
	v_add3_u32 v0, v1, v0, s83
	ds_write_b16_d16_hi v165, v0 offset:6528
	v_mul_f32_e32 v0, v74, v53
	v_fma_f32 v0, v73, v52, -v0
	v_add_f32_e32 v0, v13, v0
	v_mul_f32_e32 v1, v73, v53
	v_fmac_f32_e32 v1, v74, v52
	v_bfe_u32 v2, v0, 16, 1
	v_add_f32_e32 v1, v29, v1
	v_add3_u32 v0, v0, v2, s83
	ds_write_b16_d16_hi v164, v0 offset:6800
	v_bfe_u32 v0, v1, 16, 1
	v_add3_u32 v0, v1, v0, s83
	ds_write_b16_d16_hi v165, v0 offset:6800
	v_mul_f32_e32 v0, v70, v53
	v_fma_f32 v0, v69, v52, -v0
	v_add_f32_e32 v0, v14, v0
	v_mul_f32_e32 v1, v69, v53
	v_fmac_f32_e32 v1, v70, v52
	v_bfe_u32 v2, v0, 16, 1
	v_add_f32_e32 v1, v30, v1
	v_add3_u32 v0, v0, v2, s83
	ds_write_b16_d16_hi v164, v0 offset:7072
	v_bfe_u32 v0, v1, 16, 1
	v_add3_u32 v0, v1, v0, s83
	ds_write_b16_d16_hi v165, v0 offset:7072
	v_mul_f32_e32 v0, v72, v53
	v_fma_f32 v0, v71, v52, -v0
	v_add_f32_e32 v0, v15, v0
	v_mul_f32_e32 v1, v71, v53
	v_fmac_f32_e32 v1, v72, v52
	v_bfe_u32 v2, v0, 16, 1
	v_add_f32_e32 v1, v31, v1
	v_add3_u32 v0, v0, v2, s83
	ds_write_b16_d16_hi v164, v0 offset:7344
	v_bfe_u32 v0, v1, 16, 1
	v_add3_u32 v0, v1, v0, s83
	ds_write_b16_d16_hi v165, v0 offset:7344
	ds_read_b128 v[0:3], v173
	ds_read_b128 v[4:7], v173 offset:64
	s_waitcnt lgkmcnt(1)
	v_mfma_f32_16x16x32_bf16 v[0:3], v[0:3], v[44:47], 0
	ds_read_b128 v[12:15], v173 offset:128
	s_waitcnt lgkmcnt(1)
	v_mfma_f32_16x16x32_bf16 v[0:3], v[4:7], v[40:43], v[0:3]
	ds_read_b128 v[4:7], v173 offset:192
	s_waitcnt lgkmcnt(1)
	v_mfma_f32_16x16x32_bf16 v[0:3], v[12:15], v[36:39], v[0:3]
	s_waitcnt lgkmcnt(0)
	v_mfma_f32_16x16x32_bf16 v[0:3], v[4:7], v[32:35], v[0:3]
	s_and_saveexec_b64 s[76:77], s[4:5]
	s_cbranch_execz .LBB0_496
	v_lshl_add_u64 v[6:7], v[126:127], 0, v[112:113]
	v_or_b32_e32 v112, v62, v162
	v_mad_u64_u32 v[4:5], s[14:15], v112, s82, v[6:7]
	v_mov_b64_e32 v[240:241], v[4:5]
	global_load_ushort v4, v[4:5], off
	s_waitcnt vmcnt(0)
	v_lshlrev_b32_e32 v4, 16, v4
	v_fma_f32 v0, v63, v4, v0
	v_mul_f32_e32 v8, 0x3f3504f3, v0
	v_cmp_nlt_f32_e64 s[14:15], |v8|, 1.0
	s_and_saveexec_b64 s[36:37], s[14:15]
	s_xor_b64 s[80:81], exec, s[36:37]
	s_cbranch_execz .LBB0_481
	v_fma_f32 v4, |v8|, s94, v176
	v_fma_f32 v4, |v8|, v4, s95
	v_fma_f32 v4, |v8|, v4, s96
	v_fma_f32 v4, |v8|, v4, s97
	v_fma_f32 v4, |v8|, v4, s0
	v_fma_f32 v4, |v8|, v4, s1
	v_fma_f32 v4, |v8|, v4, |v8|
	v_mul_f32_e32 v5, 0xbfb8aa3b, v4
	v_fma_f32 v11, v4, s10, -v5
	v_rndne_f32_e32 v12, v5
	v_fmac_f32_e32 v11, 0xb2a5705f, v4
	v_sub_f32_e32 v5, v5, v12
	v_add_f32_e32 v5, v5, v11
	v_cvt_i32_f32_e32 v11, v12
	v_exp_f32_e32 v5, v5
	v_cmp_nlt_f32_e32 vcc, s11, v4
	v_ldexp_f32 v5, v5, v11
	s_nop 0
	v_cndmask_b32_e32 v5, 0, v5, vcc
	v_cmp_ngt_f32_e32 vcc, s12, v4
	s_nop 1
	v_cndmask_b32_e32 v4, v177, v5, vcc
	v_sub_f32_e32 v11, 1.0, v4
.LBB0_481:
	s_andn2_saveexec_b64 s[80:81], s[80:81]
	v_mul_f32_e32 v4, v8, v8
	v_fmamk_f32 v5, v4, 0xba1345e1, v174
	v_fmaak_f32 v5, v4, v5, 0xbcdac9b8
	v_fmaak_f32 v5, v4, v5, 0x3de703be
	v_fmaak_f32 v5, v4, v5, 0xbec09330
	v_fmaak_f32 v4, v4, v5, 0x3e0375d0
	v_fma_f32 v11, |v8|, v4, |v8|
	s_or_b64 exec, exec, s[80:81]
	v_lshlrev_b32_e32 v4, 2, v66
	v_mov_b32_e32 v5, v113
	v_bfi_b32 v8, s13, v11, v8
	v_lshl_add_u64 v[4:5], v[128:129], 0, v[4:5]
	v_mul_f32_e32 v0, 0.5, v0
	v_add_f32_e32 v8, 1.0, v8
	v_lshlrev_b64 v[12:13], 11, v[112:113]
	v_mul_f32_e32 v0, v0, v8
	v_lshl_add_u64 v[12:13], v[4:5], 0, v[12:13]
	global_store_dword v[12:13], v0, off
	v_cvt_pk_bf16_f32 v248, v0, v0
	global_store_short v[240:241], v248, off
	v_or_b32_e32 v0, 1, v112
	v_mad_u64_u32 v[12:13], s[14:15], v0, s82, v[6:7]
	v_mov_b64_e32 v[242:243], v[12:13]
	global_load_ushort v8, v[12:13], off
	s_waitcnt vmcnt(0)
	v_lshlrev_b32_e32 v8, 16, v8
	v_fma_f32 v8, v63, v8, v1
	v_mul_f32_e32 v11, 0x3f3504f3, v8
	v_cmp_nlt_f32_e64 s[14:15], |v11|, 1.0
	s_and_saveexec_b64 s[36:37], s[14:15]
	s_xor_b64 s[80:81], exec, s[36:37]
	s_cbranch_execz .LBB0_485
	v_fma_f32 v1, |v11|, s94, v176
	v_fma_f32 v1, |v11|, v1, s95
	v_fma_f32 v1, |v11|, v1, s96
	v_fma_f32 v1, |v11|, v1, s97
	v_fma_f32 v1, |v11|, v1, s0
	v_fma_f32 v1, |v11|, v1, s1
	v_fma_f32 v1, |v11|, v1, |v11|
	v_mul_f32_e32 v12, 0xbfb8aa3b, v1
	v_fma_f32 v13, v1, s10, -v12
	v_rndne_f32_e32 v14, v12
	v_fmac_f32_e32 v13, 0xb2a5705f, v1
	v_sub_f32_e32 v12, v12, v14
	v_add_f32_e32 v12, v12, v13
	v_cvt_i32_f32_e32 v13, v14
	v_exp_f32_e32 v12, v12
	v_cmp_nlt_f32_e32 vcc, s11, v1
	v_ldexp_f32 v12, v12, v13
	s_nop 0
	v_cndmask_b32_e32 v12, 0, v12, vcc
	v_cmp_ngt_f32_e32 vcc, s12, v1
	s_nop 1
	v_cndmask_b32_e32 v1, v177, v12, vcc
	v_sub_f32_e32 v12, 1.0, v1
.LBB0_485:
	s_andn2_saveexec_b64 s[80:81], s[80:81]
	v_mul_f32_e32 v1, v11, v11
	v_fmamk_f32 v12, v1, 0xba1345e1, v174
	v_fmaak_f32 v12, v1, v12, 0xbcdac9b8
	v_fmaak_f32 v12, v1, v12, 0x3de703be
	v_fmaak_f32 v12, v1, v12, 0xbec09330
	v_fmaak_f32 v1, v1, v12, 0x3e0375d0
	v_fma_f32 v12, |v11|, v1, |v11|
	s_or_b64 exec, exec, s[80:81]
	v_mov_b32_e32 v1, v113
	v_bfi_b32 v11, s13, v12, v11
	v_mul_f32_e32 v8, 0.5, v8
	v_add_f32_e32 v11, 1.0, v11
	v_lshlrev_b64 v[0:1], 11, v[0:1]
	v_mul_f32_e32 v8, v8, v11
	v_lshl_add_u64 v[0:1], v[4:5], 0, v[0:1]
	v_or_b32_e32 v112, 2, v112
	global_store_dword v[0:1], v8, off
	v_cvt_pk_bf16_f32 v248, v8, v8
	global_store_short v[242:243], v248, off
	v_mad_u64_u32 v[0:1], s[14:15], v112, s82, v[6:7]
	v_mov_b64_e32 v[244:245], v[0:1]
	global_load_ushort v0, v[0:1], off
	s_waitcnt vmcnt(0)
	v_lshlrev_b32_e32 v0, 16, v0
	v_fma_f32 v0, v63, v0, v2
	v_mul_f32_e32 v1, 0x3f3504f3, v0
	v_cmp_nlt_f32_e64 s[14:15], |v1|, 1.0
	s_and_saveexec_b64 s[36:37], s[14:15]
	s_xor_b64 s[80:81], exec, s[36:37]
	s_cbranch_execz .LBB0_489
	v_fma_f32 v2, |v1|, s94, v176
	v_fma_f32 v2, |v1|, v2, s95
	v_fma_f32 v2, |v1|, v2, s96
	v_fma_f32 v2, |v1|, v2, s97
	v_fma_f32 v2, |v1|, v2, s0
	v_fma_f32 v2, |v1|, v2, s1
	v_fma_f32 v2, |v1|, v2, |v1|
	v_mul_f32_e32 v8, 0xbfb8aa3b, v2
	v_fma_f32 v11, v2, s10, -v8
	v_rndne_f32_e32 v12, v8
	v_fmac_f32_e32 v11, 0xb2a5705f, v2
	v_sub_f32_e32 v8, v8, v12
	v_add_f32_e32 v8, v8, v11
	v_cvt_i32_f32_e32 v11, v12
	v_exp_f32_e32 v8, v8
	v_cmp_nlt_f32_e32 vcc, s11, v2
	v_ldexp_f32 v8, v8, v11
	s_nop 0
	v_cndmask_b32_e32 v8, 0, v8, vcc
	v_cmp_ngt_f32_e32 vcc, s12, v2
	s_nop 1
	v_cndmask_b32_e32 v2, v177, v8, vcc
	v_sub_f32_e32 v2, 1.0, v2
.LBB0_489:
	s_andn2_saveexec_b64 s[80:81], s[80:81]
	v_mul_f32_e32 v2, v1, v1
	v_fmamk_f32 v8, v2, 0xba1345e1, v174
	v_fmaak_f32 v8, v2, v8, 0xbcdac9b8
	v_fmaak_f32 v8, v2, v8, 0x3de703be
	v_fmaak_f32 v8, v2, v8, 0xbec09330
	v_fmaak_f32 v2, v2, v8, 0x3e0375d0
	v_fma_f32 v2, |v1|, v2, |v1|
	s_or_b64 exec, exec, s[80:81]
	v_bfi_b32 v1, s13, v2, v1
	v_mul_f32_e32 v0, 0.5, v0
	v_add_f32_e32 v1, 1.0, v1
	v_mul_f32_e32 v2, v0, v1
	v_lshlrev_b64 v[0:1], 11, v[112:113]
	v_lshl_add_u64 v[0:1], v[4:5], 0, v[0:1]
	v_or_b32_e32 v112, v62, v167
	global_store_dword v[0:1], v2, off
	v_cvt_pk_bf16_f32 v248, v2, v2
	global_store_short v[244:245], v248, off
	v_mad_u64_u32 v[0:1], s[14:15], v112, s82, v[6:7]
	v_mov_b64_e32 v[246:247], v[0:1]
	global_load_ushort v0, v[0:1], off
	s_waitcnt vmcnt(0)
	v_lshlrev_b32_e32 v0, 16, v0
	v_fmac_f32_e32 v3, v63, v0
	v_mul_f32_e32 v0, 0x3f3504f3, v3
	v_cmp_nlt_f32_e64 s[14:15], |v0|, 1.0
	s_and_saveexec_b64 s[36:37], s[14:15]
	s_xor_b64 s[80:81], exec, s[36:37]
	s_cbranch_execz .LBB0_493
	v_fma_f32 v1, |v0|, s94, v176
	v_fma_f32 v1, |v0|, v1, s95
	v_fma_f32 v1, |v0|, v1, s96
	v_fma_f32 v1, |v0|, v1, s97
	v_fma_f32 v1, |v0|, v1, s0
	v_fma_f32 v1, |v0|, v1, s1
	v_fma_f32 v1, |v0|, v1, |v0|
	v_mul_f32_e32 v2, 0xbfb8aa3b, v1
	v_fma_f32 v6, v1, s10, -v2
	v_rndne_f32_e32 v7, v2
	v_fmac_f32_e32 v6, 0xb2a5705f, v1
	v_sub_f32_e32 v2, v2, v7
	v_add_f32_e32 v2, v2, v6
	v_cvt_i32_f32_e32 v6, v7
	v_exp_f32_e32 v2, v2
	v_cmp_nlt_f32_e32 vcc, s11, v1
	v_ldexp_f32 v2, v2, v6
	s_nop 0
	v_cndmask_b32_e32 v2, 0, v2, vcc
	v_cmp_ngt_f32_e32 vcc, s12, v1
	s_nop 1
	v_cndmask_b32_e32 v1, v177, v2, vcc
	v_sub_f32_e32 v1, 1.0, v1
.LBB0_493:
	s_andn2_saveexec_b64 s[80:81], s[80:81]
	v_mul_f32_e32 v1, v0, v0
	v_fmamk_f32 v2, v1, 0xba1345e1, v174
	v_fmaak_f32 v2, v1, v2, 0xbcdac9b8
	v_fmaak_f32 v2, v1, v2, 0x3de703be
	v_fmaak_f32 v2, v1, v2, 0xbec09330
	v_fmaak_f32 v1, v1, v2, 0x3e0375d0
	v_fma_f32 v1, |v0|, v1, |v0|
	s_or_b64 exec, exec, s[80:81]
	v_bfi_b32 v0, s13, v1, v0
	v_mul_f32_e32 v2, 0.5, v3
	v_add_f32_e32 v0, 1.0, v0
	v_mul_f32_e32 v2, v2, v0
	v_lshlrev_b64 v[0:1], 11, v[112:113]
	v_lshl_add_u64 v[0:1], v[4:5], 0, v[0:1]
	global_store_dword v[0:1], v2, off
	v_cvt_pk_bf16_f32 v248, v2, v2
	global_store_short v[246:247], v248, off

.LBB0_516:
	s_or_b64 exec, exec, s[74:75]
	v_lshlrev_b32_e32 v0, 1, v8
	v_lshlrev_b32_e32 v2, 11, v6
	v_and_b32_e32 v76, 0xfffff800, v0
	v_or_b32_e32 v0, v2, v98
	v_readlane_b32 s16, v238, 32
	v_lshl_or_b32 v72, v75, 6, v76
	v_lshlrev_b32_e32 v112, 1, v0
	v_or_b32_e32 v2, v2, v161
	v_readlane_b32 s17, v238, 33
	global_load_dword v90, v7, s[84:85]
	global_load_dword v89, v7, s[86:87]
	global_load_dword v83, v7, s[84:85] offset:128
	global_load_dword v82, v7, s[86:87] offset:128
	v_lshl_add_u64 v[0:1], v[120:121], 0, v[112:113]
	v_lshlrev_b32_e32 v112, 1, v2
	v_or_b32_e32 v95, v72, v101
	v_mov_b64_e32 v[4:5], s[16:17]
	v_lshl_add_u64 v[2:3], v[122:123], 0, v[112:113]
	v_mad_i64_i32 v[4:5], s[14:15], v95, s82, v[4:5]
	v_lshlrev_b32_e32 v112, 5, v6
	v_lshl_add_u64 v[4:5], v[4:5], 0, v[112:113]
	v_mov_b32_e32 v109, v113
	v_lshl_add_u64 v[4:5], v[4:5], 0, v[108:109]
	global_load_dwordx4 v[64:67], v[4:5], off
	global_load_dwordx4 v[60:63], v[0:1], off
	global_load_dwordx4 v[56:59], v[0:1], off offset:2048
	v_lshlrev_b32_e32 v109, 4, v6
	v_cmp_lt_i32_e32 vcc, v152, v117
	v_or_b32_e32 v5, v109, v155
	v_readlane_b32 s36, v236, 32
	v_cndmask_b32_e32 v4, v103, v152, vcc
	v_lshlrev_b32_e32 v88, 2, v4
	v_lshlrev_b32_e32 v4, 2, v5
	v_readlane_b32 s46, v236, 42
	v_readlane_b32 s47, v236, 43
	s_nop 4
	global_load_dword v81, v4, s[46:47]
	global_load_dwordx4 v[52:55], v[0:1], off offset:1024
	global_load_dwordx4 v[48:51], v[0:1], off offset:3072
	global_load_dwordx4 v[44:47], v[2:3], off
	global_load_dwordx4 v[40:43], v[2:3], off offset:64
	global_load_dwordx4 v[36:39], v[2:3], off offset:128
	global_load_dwordx4 v[32:35], v[2:3], off offset:192
	v_readlane_b32 s18, v238, 34
	v_readlane_b32 s19, v238, 35
	v_readlane_b32 s20, v238, 36
	v_readlane_b32 s21, v238, 37
	v_readlane_b32 s22, v238, 38
	v_readlane_b32 s23, v238, 39
	v_readlane_b32 s24, v238, 40
	v_readlane_b32 s25, v238, 41
	v_readlane_b32 s26, v238, 42
	v_readlane_b32 s27, v238, 43
	v_readlane_b32 s28, v238, 44
	v_readlane_b32 s29, v238, 45
	v_readlane_b32 s30, v238, 46
	v_readlane_b32 s31, v238, 47
	v_readlane_b32 s37, v236, 33
	v_readlane_b32 s38, v236, 34
	v_readlane_b32 s39, v236, 35
	v_readlane_b32 s40, v236, 36
	v_readlane_b32 s41, v236, 37
	v_readlane_b32 s42, v236, 38
	v_readlane_b32 s43, v236, 39
	v_readlane_b32 s44, v236, 40
	v_readlane_b32 s45, v236, 41
	v_readlane_b32 s48, v236, 44
	v_readlane_b32 s49, v236, 45
	v_readlane_b32 s50, v236, 46
	v_readlane_b32 s51, v236, 47
	s_waitcnt vmcnt(12)
	v_mul_f32_e32 v1, v90, v89
	v_mul_f32_e32 v0, v89, v89
	s_waitcnt vmcnt(10)
	v_mul_f32_e32 v3, v83, v82
	v_mul_f32_e32 v2, v82, v82
	v_fma_f32 v91, v1, 2.0, 0
	v_fma_f32 v84, v3, 2.0, 0
	v_fma_f32 v92, v90, v90, -v0
	v_fma_f32 v85, v83, v83, -v2
	v_mul_f32_e32 v0, v89, v91
	v_mul_f32_e32 v16, v90, v91
	v_mul_f32_e32 v3, v82, v84
	v_mul_f32_e32 v17, v83, v84
	v_mul_f32_e32 v18, v84, v84
	v_mul_f32_e32 v19, v85, v84
	v_fma_f32 v20, v90, v92, -v0
	v_fmac_f32_e32 v16, v89, v92
	v_fma_f32 v21, v83, v85, -v3
	v_fmac_f32_e32 v17, v82, v85
	v_mul_f32_e32 v1, v91, v91
	v_mul_f32_e32 v2, v92, v91
	v_fma_f32 v77, v85, v85, -v18
	v_fma_f32 v78, v19, 2.0, 0
	v_add_f32_e32 v94, 0, v20
	v_add_f32_e32 v93, 0, v16
	v_add_f32_e32 v87, 0, v21
	v_add_f32_e32 v86, 0, v17
	s_waitcnt vmcnt(7)
	v_mfma_f32_32x32x16_bf16 v[16:31], v[64:67], v[56:59], 0
	v_fma_f32 v79, v92, v92, -v1
	v_fma_f32 v80, v2, 2.0, 0
	v_mul_f32_e32 v183, v68, v80
	v_fma_f32 v183, v70, v79, -v183
	v_mfma_f32_32x32x16_bf16 v[0:15], v[64:67], v[60:63], 0
	s_nop 6
	v_mul_f32_e32 v73, v89, v16
	v_mul_f32_e32 v139, v90, v16
	v_mul_f32_e32 v178, v90, v24
	v_mul_f32_e32 v145, v89, v24
	v_mul_f32_e32 v143, v89, v20
	v_mul_f32_e32 v144, v90, v20
	v_fma_f32 v73, v90, v0, -v73
	v_fmac_f32_e32 v139, v89, v0
	v_add_f32_e32 v1, v1, v73
	v_add_f32_e32 v17, v17, v139
	v_mul_f32_e32 v139, v89, v1
	v_mul_f32_e32 v73, v89, v17
	v_fmac_f32_e32 v139, v90, v17
	v_fma_f32 v73, v90, v1, -v73
	v_add_f32_e32 v18, v18, v139
	v_add_f32_e32 v2, v2, v73
	v_mul_f32_e32 v73, v89, v18
	v_fmac_f32_e32 v178, v89, v8
	v_fma_f32 v145, v90, v8, -v145
	v_fma_f32 v73, v90, v2, -v73
	v_add_f32_e32 v25, v25, v178
	v_add_f32_e32 v9, v9, v145
	v_add_f32_e32 v3, v3, v73
	v_mul_f32_e32 v73, v89, v25
	v_fma_f32 v73, v90, v9, -v73
	v_add_f32_e32 v10, v10, v73
	v_mul_f32_e32 v73, v89, v9
	v_fmac_f32_e32 v73, v90, v25
	v_add_f32_e32 v26, v26, v73
	v_mul_f32_e32 v73, v89, v26
	v_fma_f32 v73, v90, v10, -v73
	v_add_f32_e32 v11, v11, v73
	v_mul_f32_e32 v73, v89, v10
	v_fmac_f32_e32 v73, v90, v26
	v_add_f32_e32 v27, v27, v73
	v_mul_f32_e32 v73, v89, v28
	v_fma_f32 v73, v90, v12, -v73
	v_add_f32_e32 v13, v13, v73
	v_mul_f32_e32 v73, v90, v28
	v_fmac_f32_e32 v73, v89, v12
	v_add_f32_e32 v29, v29, v73
	v_mul_f32_e32 v73, v89, v29
	v_fma_f32 v73, v90, v13, -v73
	v_fma_f32 v143, v90, v4, -v143
	v_add_f32_e32 v14, v14, v73
	v_mul_f32_e32 v73, v89, v13
	v_fmac_f32_e32 v144, v89, v4
	v_add_f32_e32 v5, v5, v143
	v_fmac_f32_e32 v73, v90, v29
	v_add_f32_e32 v21, v21, v144
	v_mul_f32_e32 v144, v89, v5
	v_add_f32_e32 v30, v30, v73
	v_mul_f32_e32 v143, v89, v21
	v_fmac_f32_e32 v144, v90, v21
	v_mul_f32_e32 v139, v89, v2
	v_mul_f32_e32 v73, v89, v30
	v_fma_f32 v143, v90, v5, -v143
	v_add_f32_e32 v22, v22, v144
	v_fmac_f32_e32 v139, v90, v18
	v_fma_f32 v73, v90, v14, -v73
	v_add_f32_e32 v6, v6, v143
	v_mul_f32_e32 v143, v89, v22
	v_add_f32_e32 v19, v19, v139
	v_add_f32_e32 v139, v15, v73
	v_mul_f32_e32 v15, v89, v14
	v_fma_f32 v143, v90, v6, -v143
	v_fmac_f32_e32 v15, v90, v30
	v_add_f32_e32 v7, v7, v143
	v_add_f32_e32 v143, v31, v15
	ds_bpermute_b32 v15, v88, v3
	ds_bpermute_b32 v31, v88, v19
	v_mul_f32_e32 v144, v89, v6
	v_fmac_f32_e32 v144, v90, v22
	ds_bpermute_b32 v73, v88, v7
	s_waitcnt lgkmcnt(2)
	v_cndmask_b32_e64 v181, v15, v3, s[4:5]
	v_add_f32_e32 v181, v183, v181
	v_mul_f32_e32 v183, v70, v80
	s_waitcnt lgkmcnt(1)
	v_cndmask_b32_e64 v182, v31, v19, s[4:5]
	v_fmac_f32_e32 v183, v68, v79
	v_add_f32_e32 v182, v183, v182
	v_mul_f32_e32 v183, v80, v182
	v_cndmask_b32_e64 v15, v3, v15, s[4:5]
	v_fma_f32 v183, v79, v181, -v183
	v_add_f32_e32 v23, v23, v144
	v_add_f32_e32 v15, v15, v183
	v_mul_f32_e32 v183, v80, v181
	ds_bpermute_b32 v178, v88, v23
	v_cndmask_b32_e64 v31, v19, v31, s[4:5]
	v_fmac_f32_e32 v183, v79, v182
	v_add_f32_e32 v31, v31, v183
	v_mul_f32_e32 v183, v80, v31
	v_cndmask_b32_e64 v70, v181, v70, s[4:5]
	s_waitcnt lgkmcnt(1)
	v_cndmask_b32_e64 v181, v73, v7, s[4:5]
	v_fma_f32 v183, v79, v15, -v183
	v_add_f32_e32 v181, v181, v183
	v_mul_f32_e32 v183, v80, v15
	v_cndmask_b32_e64 v68, v182, v68, s[4:5]
	s_waitcnt lgkmcnt(0)
	v_cndmask_b32_e64 v182, v178, v23, s[4:5]
	v_fmac_f32_e32 v183, v79, v31
	v_add_f32_e32 v182, v182, v183
	v_mul_f32_e32 v183, v80, v182
	ds_bpermute_b32 v179, v88, v11
	v_cndmask_b32_e64 v73, v7, v73, s[4:5]
	v_fma_f32 v183, v79, v181, -v183
	v_add_f32_e32 v73, v73, v183
	v_mul_f32_e32 v183, v80, v181
	ds_bpermute_b32 v180, v88, v27
	v_cndmask_b32_e64 v178, v23, v178, s[4:5]
	v_fmac_f32_e32 v183, v79, v182
	v_add_f32_e32 v178, v178, v183
	v_mul_f32_e32 v183, v80, v178
	v_cndmask_b32_e64 v15, v181, v15, s[4:5]
	s_waitcnt lgkmcnt(1)
	v_cndmask_b32_e64 v181, v179, v11, s[4:5]
	v_fma_f32 v183, v79, v73, -v183
	v_add_f32_e32 v181, v181, v183
	v_mul_f32_e32 v183, v80, v73
	v_cndmask_b32_e64 v31, v182, v31, s[4:5]
	s_waitcnt lgkmcnt(0)
	v_cndmask_b32_e64 v182, v180, v27, s[4:5]
	v_fmac_f32_e32 v183, v79, v178
	v_add_f32_e32 v182, v182, v183
	ds_bpermute_b32 v145, v88, v143
	v_mul_f32_e32 v183, v80, v182
	ds_bpermute_b32 v144, v88, v139
	v_cndmask_b32_e64 v179, v11, v179, s[4:5]
	v_fma_f32 v183, v79, v181, -v183
	v_add_f32_e32 v183, v179, v183
	v_mul_f32_e32 v179, v80, v181
	v_cndmask_b32_e64 v180, v27, v180, s[4:5]
	v_fmac_f32_e32 v179, v79, v182
	v_add_f32_e32 v180, v180, v179
	v_mul_f32_e32 v179, v80, v183
	v_cndmask_b32_e64 v73, v181, v73, s[4:5]
	v_cndmask_b32_e64 v181, v182, v178, s[4:5]
	s_waitcnt lgkmcnt(1)
	v_cndmask_b32_e64 v178, v145, v143, s[4:5]
	v_fmac_f32_e32 v179, v79, v180
	v_mul_f32_e32 v182, v80, v180
	v_add_f32_e32 v178, v178, v179
	s_waitcnt lgkmcnt(0)
	v_cndmask_b32_e64 v179, v144, v139, s[4:5]
	v_fma_f32 v182, v79, v183, -v182
	v_add_f32_e32 v179, v179, v182
	v_cndmask_b32_e64 v182, v179, v183, s[4:5]
	v_mul_f32_e32 v183, v89, v68
	v_fma_f32 v183, v90, v70, -v183
	v_add_f32_e32 v0, v0, v183
	v_mul_f32_e32 v183, v90, v68
	v_fmac_f32_e32 v183, v89, v70
	v_add_f32_e32 v16, v16, v183
	v_bfe_u32 v183, v0, 16, 1
	v_add3_u32 v0, v0, v183, s83
	ds_write_b16_d16_hi v163, v0
	v_bfe_u32 v0, v16, 16, 1
	v_add3_u32 v0, v16, v0, s83
	ds_write_b16_d16_hi v163, v0 offset:128
	v_mul_f32_e32 v0, v91, v68
	v_fma_f32 v0, v92, v70, -v0
	v_add_f32_e32 v0, v1, v0
	v_mul_f32_e32 v1, v92, v68
	v_fmac_f32_e32 v1, v91, v70
	v_bfe_u32 v16, v0, 16, 1
	v_add_f32_e32 v1, v17, v1
	v_add3_u32 v0, v0, v16, s83
	ds_write_b16_d16_hi v163, v0 offset:272
	v_bfe_u32 v0, v1, 16, 1
	v_add3_u32 v0, v1, v0, s83
	ds_write_b16_d16_hi v163, v0 offset:400
	v_mul_f32_e32 v0, v93, v68
	v_fma_f32 v0, v94, v70, -v0
	v_add_f32_e32 v0, v2, v0
	v_mul_f32_e32 v1, v94, v68
	v_fmac_f32_e32 v1, v93, v70
	v_bfe_u32 v2, v0, 16, 1
	v_add_f32_e32 v1, v18, v1
	v_add3_u32 v0, v0, v2, s83
	ds_write_b16_d16_hi v163, v0 offset:544
	v_bfe_u32 v0, v1, 16, 1
	v_add3_u32 v0, v1, v0, s83
	ds_write_b16_d16_hi v163, v0 offset:672
	v_mul_f32_e32 v0, v80, v68
	v_fma_f32 v0, v79, v70, -v0
	v_add_f32_e32 v0, v3, v0
	v_mul_f32_e32 v1, v79, v68
	v_fmac_f32_e32 v1, v80, v70
	v_bfe_u32 v2, v0, 16, 1
	v_add_f32_e32 v1, v19, v1
	v_add3_u32 v0, v0, v2, s83
	ds_write_b16_d16_hi v163, v0 offset:816
	v_bfe_u32 v0, v1, 16, 1
	v_add3_u32 v0, v1, v0, s83
	ds_write_b16_d16_hi v163, v0 offset:944
	v_mul_f32_e32 v0, v89, v31
	v_fma_f32 v0, v90, v15, -v0
	v_add_f32_e32 v0, v4, v0
	v_mul_f32_e32 v1, v90, v31
	v_fmac_f32_e32 v1, v89, v15
	v_bfe_u32 v2, v0, 16, 1
	v_add_f32_e32 v1, v20, v1
	v_add3_u32 v0, v0, v2, s83
	ds_write_b16_d16_hi v163, v0 offset:2176
	v_bfe_u32 v0, v1, 16, 1
	v_add3_u32 v0, v1, v0, s83
	ds_write_b16_d16_hi v163, v0 offset:2304
	v_mul_f32_e32 v0, v91, v31
	v_fma_f32 v0, v92, v15, -v0
	v_add_f32_e32 v0, v5, v0
	v_mul_f32_e32 v1, v92, v31
	v_fmac_f32_e32 v1, v91, v15
	v_bfe_u32 v2, v0, 16, 1
	v_add_f32_e32 v1, v21, v1
	v_add3_u32 v0, v0, v2, s83
	ds_write_b16_d16_hi v163, v0 offset:2448
	v_bfe_u32 v0, v1, 16, 1
	v_add3_u32 v0, v1, v0, s83
	ds_write_b16_d16_hi v163, v0 offset:2576
	v_mul_f32_e32 v0, v93, v31
	v_fma_f32 v0, v94, v15, -v0
	v_add_f32_e32 v0, v6, v0
	v_mul_f32_e32 v1, v94, v31
	v_fmac_f32_e32 v1, v93, v15
	v_bfe_u32 v2, v0, 16, 1
	v_add_f32_e32 v1, v22, v1
	v_add3_u32 v0, v0, v2, s83
	ds_write_b16_d16_hi v163, v0 offset:2720
	v_bfe_u32 v0, v1, 16, 1
	v_add3_u32 v0, v1, v0, s83
	ds_write_b16_d16_hi v163, v0 offset:2848
	v_mul_f32_e32 v0, v80, v31
	v_fma_f32 v0, v79, v15, -v0
	v_add_f32_e32 v0, v7, v0
	v_mul_f32_e32 v1, v79, v31
	v_fmac_f32_e32 v1, v80, v15
	v_bfe_u32 v2, v0, 16, 1
	v_add_f32_e32 v1, v23, v1
	v_add3_u32 v0, v0, v2, s83
	ds_write_b16_d16_hi v163, v0 offset:2992
	v_bfe_u32 v0, v1, 16, 1
	v_add3_u32 v0, v1, v0, s83
	ds_write_b16_d16_hi v163, v0 offset:3120
	v_mul_f32_e32 v0, v89, v181
	v_fma_f32 v0, v90, v73, -v0
	v_add_f32_e32 v0, v8, v0
	v_mul_f32_e32 v1, v90, v181
	v_fmac_f32_e32 v1, v89, v73
	v_bfe_u32 v2, v0, 16, 1
	v_add_f32_e32 v1, v24, v1
	v_add3_u32 v0, v0, v2, s83
	ds_write_b16_d16_hi v163, v0 offset:4352
	v_bfe_u32 v0, v1, 16, 1
	v_add3_u32 v0, v1, v0, s83
	ds_write_b16_d16_hi v163, v0 offset:4480
	v_mul_f32_e32 v0, v91, v181
	v_fma_f32 v0, v92, v73, -v0
	v_add_f32_e32 v0, v9, v0
	v_mul_f32_e32 v1, v92, v181
	v_fmac_f32_e32 v1, v91, v73
	v_bfe_u32 v2, v0, 16, 1
	v_add_f32_e32 v1, v25, v1
	v_add3_u32 v0, v0, v2, s83
	ds_write_b16_d16_hi v163, v0 offset:4624
	v_bfe_u32 v0, v1, 16, 1
	v_add3_u32 v0, v1, v0, s83
	ds_write_b16_d16_hi v163, v0 offset:4752
	v_mul_f32_e32 v0, v93, v181
	v_fma_f32 v0, v94, v73, -v0
	v_add_f32_e32 v0, v10, v0
	v_mul_f32_e32 v1, v94, v181
	v_fmac_f32_e32 v1, v93, v73
	v_bfe_u32 v2, v0, 16, 1
	v_add_f32_e32 v1, v26, v1
	v_add3_u32 v0, v0, v2, s83
	ds_write_b16_d16_hi v163, v0 offset:4896
	v_bfe_u32 v0, v1, 16, 1
	v_add3_u32 v0, v1, v0, s83
	ds_write_b16_d16_hi v163, v0 offset:5024
	v_mul_f32_e32 v0, v80, v181
	v_fma_f32 v0, v79, v73, -v0
	v_add_f32_e32 v0, v11, v0
	v_mul_f32_e32 v1, v79, v181
	v_fmac_f32_e32 v1, v80, v73
	v_bfe_u32 v2, v0, 16, 1
	v_add_f32_e32 v1, v27, v1
	v_add3_u32 v0, v0, v2, s83
	ds_write_b16_d16_hi v163, v0 offset:5168
	v_bfe_u32 v0, v1, 16, 1
	v_cndmask_b32_e64 v180, v178, v180, s[4:5]
	v_add3_u32 v0, v1, v0, s83
	ds_write_b16_d16_hi v163, v0 offset:5296
	v_mul_f32_e32 v0, v89, v180
	v_fma_f32 v0, v90, v182, -v0
	v_add_f32_e32 v0, v12, v0
	v_mul_f32_e32 v1, v90, v180
	v_fmac_f32_e32 v1, v89, v182
	v_bfe_u32 v2, v0, 16, 1
	v_add_f32_e32 v1, v28, v1
	v_add3_u32 v0, v0, v2, s83
	ds_write_b16_d16_hi v163, v0 offset:6528
	v_bfe_u32 v0, v1, 16, 1
	v_add3_u32 v0, v1, v0, s83
	ds_write_b16_d16_hi v163, v0 offset:6656
	v_mul_f32_e32 v0, v91, v180
	v_fma_f32 v0, v92, v182, -v0
	v_add_f32_e32 v0, v13, v0
	v_mul_f32_e32 v1, v92, v180
	v_fmac_f32_e32 v1, v91, v182
	v_bfe_u32 v2, v0, 16, 1
	v_add_f32_e32 v1, v29, v1
	v_add3_u32 v0, v0, v2, s83
	ds_write_b16_d16_hi v163, v0 offset:6800
	v_bfe_u32 v0, v1, 16, 1
	v_add3_u32 v0, v1, v0, s83
	ds_write_b16_d16_hi v163, v0 offset:6928
	v_mul_f32_e32 v0, v93, v180
	v_fma_f32 v0, v94, v182, -v0
	v_add_f32_e32 v0, v14, v0
	v_mul_f32_e32 v1, v94, v180
	v_fmac_f32_e32 v1, v93, v182
	v_bfe_u32 v2, v0, 16, 1
	v_add_f32_e32 v1, v30, v1
	v_add3_u32 v0, v0, v2, s83
	ds_write_b16_d16_hi v163, v0 offset:7072
	v_bfe_u32 v0, v1, 16, 1
	v_add3_u32 v0, v1, v0, s83
	ds_write_b16_d16_hi v163, v0 offset:7200
	v_mul_f32_e32 v0, v80, v180
	v_fma_f32 v0, v79, v182, -v0
	v_add_f32_e32 v16, v139, v0
	v_mul_f32_e32 v17, v79, v180
	v_fmac_f32_e32 v17, v80, v182
	v_bfe_u32 v18, v16, 16, 1
	v_add_f32_e32 v17, v143, v17
	v_add3_u32 v16, v16, v18, s83
	ds_write_b16_d16_hi v163, v16 offset:7344
	v_bfe_u32 v16, v17, 16, 1
	v_add3_u32 v16, v17, v16, s83
	ds_write_b16_d16_hi v163, v16 offset:7472
	s_waitcnt vmcnt(4)
	v_mfma_f32_32x32x16_bf16 v[16:31], v[64:67], v[48:51], 0
	v_mul_f32_e32 v183, v69, v78
	v_fma_f32 v183, v71, v77, -v183
	v_mfma_f32_32x32x16_bf16 v[0:15], v[64:67], v[52:55], 0
	s_nop 8
	v_mul_f32_e32 v64, v82, v16
	s_nop 1
	v_fma_f32 v64, v83, v0, -v64
	v_add_f32_e32 v1, v1, v64
	v_mul_f32_e32 v64, v83, v16
	v_fmac_f32_e32 v64, v82, v0
	v_add_f32_e32 v64, v17, v64
	v_mul_f32_e32 v17, v82, v64
	v_fma_f32 v17, v83, v1, -v17
	v_add_f32_e32 v2, v2, v17
	v_mul_f32_e32 v17, v82, v1
	v_fmac_f32_e32 v17, v83, v64
	v_add_f32_e32 v65, v18, v17
	v_mul_f32_e32 v17, v82, v65
	v_fma_f32 v17, v83, v2, -v17
	v_add_f32_e32 v3, v3, v17
	v_mul_f32_e32 v17, v82, v2
	v_fmac_f32_e32 v17, v83, v65
	v_add_f32_e32 v19, v19, v17
	v_mul_f32_e32 v17, v82, v20
	v_fma_f32 v17, v83, v4, -v17
	v_add_f32_e32 v5, v5, v17
	v_mul_f32_e32 v17, v83, v20
	v_fmac_f32_e32 v17, v82, v4
	v_add_f32_e32 v21, v21, v17
	v_mul_f32_e32 v17, v82, v21
	v_fma_f32 v17, v83, v5, -v17
	v_add_f32_e32 v66, v6, v17
	v_mul_f32_e32 v6, v82, v5
	v_fmac_f32_e32 v6, v83, v21
	v_add_f32_e32 v22, v22, v6
	v_mul_f32_e32 v6, v82, v22
	v_fma_f32 v6, v83, v66, -v6
	v_add_f32_e32 v67, v7, v6
	v_mul_f32_e32 v6, v82, v66
	v_fmac_f32_e32 v6, v83, v22
	v_add_f32_e32 v23, v23, v6
	v_mul_f32_e32 v6, v82, v24
	v_fma_f32 v6, v83, v8, -v6
	v_add_f32_e32 v68, v9, v6
	v_mul_f32_e32 v6, v83, v24
	v_fmac_f32_e32 v6, v82, v8
	v_add_f32_e32 v25, v25, v6
	v_mul_f32_e32 v6, v82, v25
	v_fma_f32 v6, v83, v68, -v6
	v_add_f32_e32 v70, v10, v6
	v_mul_f32_e32 v6, v82, v68
	v_fmac_f32_e32 v6, v83, v25
	v_add_f32_e32 v26, v26, v6
	v_mul_f32_e32 v6, v82, v26
	v_fma_f32 v6, v83, v70, -v6
	v_add_f32_e32 v11, v11, v6
	v_mul_f32_e32 v6, v82, v70
	v_fmac_f32_e32 v6, v83, v26
	v_add_f32_e32 v27, v27, v6
	v_mul_f32_e32 v6, v82, v28
	v_fma_f32 v6, v83, v12, -v6
	v_add_f32_e32 v13, v13, v6
	v_mul_f32_e32 v6, v83, v28
	v_fmac_f32_e32 v6, v82, v12
	v_add_f32_e32 v29, v29, v6
	v_mul_f32_e32 v6, v82, v29
	v_fma_f32 v6, v83, v13, -v6
	v_add_f32_e32 v14, v14, v6
	v_mul_f32_e32 v6, v82, v13
	v_fmac_f32_e32 v6, v83, v29
	v_add_f32_e32 v30, v30, v6
	v_mul_f32_e32 v6, v82, v30
	v_fma_f32 v6, v83, v14, -v6
	v_add_f32_e32 v6, v15, v6
	ds_bpermute_b32 v15, v88, v3
	ds_bpermute_b32 v17, v88, v19
	v_mul_f32_e32 v7, v82, v14
	ds_bpermute_b32 v18, v88, v67
	v_fmac_f32_e32 v7, v83, v30
	s_waitcnt lgkmcnt(2)
	v_cndmask_b32_e64 v181, v15, v3, s[4:5]
	v_add_f32_e32 v181, v183, v181
	v_mul_f32_e32 v183, v71, v78
	s_waitcnt lgkmcnt(1)
	v_cndmask_b32_e64 v182, v17, v19, s[4:5]
	v_fmac_f32_e32 v183, v69, v77
	v_add_f32_e32 v182, v183, v182
	v_mul_f32_e32 v183, v78, v182
	v_cndmask_b32_e64 v15, v3, v15, s[4:5]
	v_fma_f32 v183, v77, v181, -v183
	v_add_f32_e32 v15, v15, v183
	v_mul_f32_e32 v183, v78, v181
	v_add_f32_e32 v7, v31, v7
	ds_bpermute_b32 v31, v88, v23
	v_cndmask_b32_e64 v17, v19, v17, s[4:5]
	v_fmac_f32_e32 v183, v77, v182
	v_add_f32_e32 v17, v17, v183
	v_mul_f32_e32 v183, v78, v17
	v_cndmask_b32_e64 v71, v181, v71, s[4:5]
	s_waitcnt lgkmcnt(1)
	v_cndmask_b32_e64 v181, v18, v67, s[4:5]
	v_fma_f32 v183, v77, v15, -v183
	v_add_f32_e32 v181, v181, v183
	v_mul_f32_e32 v183, v78, v15
	v_cndmask_b32_e64 v69, v182, v69, s[4:5]
	s_waitcnt lgkmcnt(0)
	v_cndmask_b32_e64 v182, v31, v23, s[4:5]
	v_fmac_f32_e32 v183, v77, v17
	v_add_f32_e32 v182, v182, v183
	v_mul_f32_e32 v183, v78, v182
	ds_bpermute_b32 v73, v88, v11
	v_cndmask_b32_e64 v18, v67, v18, s[4:5]
	v_fma_f32 v183, v77, v181, -v183
	v_add_f32_e32 v18, v18, v183
	v_mul_f32_e32 v183, v78, v181
	ds_bpermute_b32 v180, v88, v27
	v_cndmask_b32_e64 v31, v23, v31, s[4:5]
	v_fmac_f32_e32 v183, v77, v182
	v_add_f32_e32 v31, v31, v183
	v_mul_f32_e32 v183, v78, v31
	v_cndmask_b32_e64 v15, v181, v15, s[4:5]
	v_cndmask_b32_e64 v181, v182, v17, s[4:5]
	s_waitcnt lgkmcnt(1)
	v_cndmask_b32_e64 v17, v73, v11, s[4:5]
	v_fma_f32 v183, v77, v18, -v183
	v_add_f32_e32 v17, v17, v183
	v_mul_f32_e32 v183, v78, v18
	s_waitcnt lgkmcnt(0)
	v_cndmask_b32_e64 v182, v180, v27, s[4:5]
	v_fmac_f32_e32 v183, v77, v31
	v_add_f32_e32 v182, v182, v183
	ds_bpermute_b32 v10, v88, v7
	v_mul_f32_e32 v183, v78, v182
	ds_bpermute_b32 v9, v88, v6
	v_cndmask_b32_e64 v73, v11, v73, s[4:5]
	v_fma_f32 v183, v77, v17, -v183
	v_add_f32_e32 v73, v73, v183
	v_mul_f32_e32 v183, v78, v17
	v_cndmask_b32_e64 v180, v27, v180, s[4:5]
	v_fmac_f32_e32 v183, v77, v182
	v_add_f32_e32 v180, v180, v183
	v_cndmask_b32_e64 v183, v17, v18, s[4:5]
	v_mul_f32_e32 v18, v78, v73
	v_cndmask_b32_e64 v31, v182, v31, s[4:5]
	s_waitcnt lgkmcnt(1)
	v_cndmask_b32_e64 v17, v10, v7, s[4:5]
	v_fmac_f32_e32 v18, v77, v180
	v_mul_f32_e32 v182, v78, v180
	v_add_f32_e32 v17, v17, v18
	s_waitcnt lgkmcnt(0)
	v_cndmask_b32_e64 v18, v9, v6, s[4:5]
	v_fma_f32 v182, v77, v73, -v182
	v_add_f32_e32 v18, v18, v182
	v_mul_f32_e32 v182, v82, v69
	v_fma_f32 v182, v83, v71, -v182
	v_add_f32_e32 v0, v0, v182
	v_mul_f32_e32 v182, v83, v69
	v_fmac_f32_e32 v182, v82, v71
	v_add_f32_e32 v16, v16, v182
	v_bfe_u32 v182, v0, 16, 1
	v_add3_u32 v0, v0, v182, s83
	ds_write_b16_d16_hi v164, v0
	v_bfe_u32 v0, v16, 16, 1
	v_add3_u32 v0, v16, v0, s83
	ds_write_b16_d16_hi v165, v0
	v_mul_f32_e32 v0, v84, v69
	v_fma_f32 v0, v85, v71, -v0
	v_add_f32_e32 v0, v1, v0
	v_mul_f32_e32 v1, v85, v69
	v_fmac_f32_e32 v1, v84, v71
	v_bfe_u32 v16, v0, 16, 1
	v_add_f32_e32 v1, v64, v1
	v_add3_u32 v0, v0, v16, s83
	ds_write_b16_d16_hi v164, v0 offset:272
	v_bfe_u32 v0, v1, 16, 1
	v_add3_u32 v0, v1, v0, s83
	ds_write_b16_d16_hi v165, v0 offset:272
	v_mul_f32_e32 v0, v86, v69
	v_fma_f32 v0, v87, v71, -v0
	v_add_f32_e32 v0, v2, v0
	v_mul_f32_e32 v1, v87, v69
	v_fmac_f32_e32 v1, v86, v71
	v_bfe_u32 v2, v0, 16, 1
	v_add_f32_e32 v1, v65, v1
	v_add3_u32 v0, v0, v2, s83
	ds_write_b16_d16_hi v164, v0 offset:544
	v_bfe_u32 v0, v1, 16, 1
	v_add3_u32 v0, v1, v0, s83
	ds_write_b16_d16_hi v165, v0 offset:544
	v_mul_f32_e32 v0, v78, v69
	v_fma_f32 v0, v77, v71, -v0
	v_add_f32_e32 v0, v3, v0
	v_mul_f32_e32 v1, v77, v69
	v_fmac_f32_e32 v1, v78, v71
	v_bfe_u32 v2, v0, 16, 1
	v_add_f32_e32 v1, v19, v1
	v_add3_u32 v0, v0, v2, s83
	ds_write_b16_d16_hi v164, v0 offset:816
	v_bfe_u32 v0, v1, 16, 1
	v_add3_u32 v0, v1, v0, s83
	ds_write_b16_d16_hi v165, v0 offset:816
	v_mul_f32_e32 v0, v82, v181
	v_fma_f32 v0, v83, v15, -v0
	v_add_f32_e32 v0, v4, v0
	v_mul_f32_e32 v1, v83, v181
	v_fmac_f32_e32 v1, v82, v15
	v_bfe_u32 v2, v0, 16, 1
	v_add_f32_e32 v1, v20, v1
	v_add3_u32 v0, v0, v2, s83
	ds_write_b16_d16_hi v164, v0 offset:2176
	v_bfe_u32 v0, v1, 16, 1
	v_add3_u32 v0, v1, v0, s83
	ds_write_b16_d16_hi v165, v0 offset:2176
	v_mul_f32_e32 v0, v84, v181
	v_fma_f32 v0, v85, v15, -v0
	v_add_f32_e32 v0, v5, v0
	v_mul_f32_e32 v1, v85, v181
	v_fmac_f32_e32 v1, v84, v15
	v_bfe_u32 v2, v0, 16, 1
	v_add_f32_e32 v1, v21, v1
	v_add3_u32 v0, v0, v2, s83
	ds_write_b16_d16_hi v164, v0 offset:2448
	v_bfe_u32 v0, v1, 16, 1
	v_add3_u32 v0, v1, v0, s83
	ds_write_b16_d16_hi v165, v0 offset:2448
	v_mul_f32_e32 v0, v86, v181
	v_fma_f32 v0, v87, v15, -v0
	v_add_f32_e32 v0, v66, v0
	v_mul_f32_e32 v1, v87, v181
	v_fmac_f32_e32 v1, v86, v15
	v_bfe_u32 v2, v0, 16, 1
	v_add_f32_e32 v1, v22, v1
	v_add3_u32 v0, v0, v2, s83
	ds_write_b16_d16_hi v164, v0 offset:2720
	v_bfe_u32 v0, v1, 16, 1
	v_add3_u32 v0, v1, v0, s83
	ds_write_b16_d16_hi v165, v0 offset:2720
	v_mul_f32_e32 v0, v78, v181
	v_fma_f32 v0, v77, v15, -v0
	v_add_f32_e32 v0, v67, v0
	v_mul_f32_e32 v1, v77, v181
	v_fmac_f32_e32 v1, v78, v15
	v_bfe_u32 v2, v0, 16, 1
	v_add_f32_e32 v1, v23, v1
	v_add3_u32 v0, v0, v2, s83
	ds_write_b16_d16_hi v164, v0 offset:2992
	v_bfe_u32 v0, v1, 16, 1
	v_add3_u32 v0, v1, v0, s83
	ds_write_b16_d16_hi v165, v0 offset:2992
	v_mul_f32_e32 v0, v82, v31
	v_fma_f32 v0, v83, v183, -v0
	v_add_f32_e32 v0, v8, v0
	v_mul_f32_e32 v1, v83, v31
	v_fmac_f32_e32 v1, v82, v183
	v_bfe_u32 v2, v0, 16, 1
	v_add_f32_e32 v1, v24, v1
	v_add3_u32 v0, v0, v2, s83
	ds_write_b16_d16_hi v164, v0 offset:4352
	v_bfe_u32 v0, v1, 16, 1
	v_add3_u32 v0, v1, v0, s83
	ds_write_b16_d16_hi v165, v0 offset:4352
	v_mul_f32_e32 v0, v84, v31
	v_fma_f32 v0, v85, v183, -v0
	v_add_f32_e32 v0, v68, v0
	v_mul_f32_e32 v1, v85, v31
	v_fmac_f32_e32 v1, v84, v183
	v_bfe_u32 v2, v0, 16, 1
	v_add_f32_e32 v1, v25, v1
	v_add3_u32 v0, v0, v2, s83
	ds_write_b16_d16_hi v164, v0 offset:4624
	v_bfe_u32 v0, v1, 16, 1
	v_add3_u32 v0, v1, v0, s83
	ds_write_b16_d16_hi v165, v0 offset:4624
	v_mul_f32_e32 v0, v86, v31
	v_fma_f32 v0, v87, v183, -v0
	v_add_f32_e32 v0, v70, v0
	v_mul_f32_e32 v1, v87, v31
	v_fmac_f32_e32 v1, v86, v183
	v_bfe_u32 v2, v0, 16, 1
	v_add_f32_e32 v1, v26, v1
	v_add3_u32 v0, v0, v2, s83
	ds_write_b16_d16_hi v164, v0 offset:4896
	v_bfe_u32 v0, v1, 16, 1
	v_add3_u32 v0, v1, v0, s83
	ds_write_b16_d16_hi v165, v0 offset:4896
	v_mul_f32_e32 v0, v78, v31
	v_fma_f32 v0, v77, v183, -v0
	v_add_f32_e32 v0, v11, v0
	v_mul_f32_e32 v1, v77, v31
	v_fmac_f32_e32 v1, v78, v183
	v_bfe_u32 v2, v0, 16, 1
	v_add_f32_e32 v1, v27, v1
	v_add3_u32 v0, v0, v2, s83
	ds_write_b16_d16_hi v164, v0 offset:5168
	v_bfe_u32 v0, v1, 16, 1
	v_cndmask_b32_e64 v180, v17, v180, s[4:5]
	v_add3_u32 v0, v1, v0, s83
	v_cndmask_b32_e64 v73, v18, v73, s[4:5]
	ds_write_b16_d16_hi v165, v0 offset:5168
	v_mul_f32_e32 v0, v82, v180
	v_fma_f32 v0, v83, v73, -v0
	v_add_f32_e32 v0, v12, v0
	v_mul_f32_e32 v1, v83, v180
	v_fmac_f32_e32 v1, v82, v73
	v_bfe_u32 v2, v0, 16, 1
	v_add_f32_e32 v1, v28, v1
	v_add3_u32 v0, v0, v2, s83
	ds_write_b16_d16_hi v164, v0 offset:6528
	v_bfe_u32 v0, v1, 16, 1
	v_add3_u32 v0, v1, v0, s83
	ds_write_b16_d16_hi v165, v0 offset:6528
	v_mul_f32_e32 v0, v84, v180
	v_fma_f32 v0, v85, v73, -v0
	v_add_f32_e32 v0, v13, v0
	v_mul_f32_e32 v1, v85, v180
	v_fmac_f32_e32 v1, v84, v73
	v_bfe_u32 v2, v0, 16, 1
	v_add_f32_e32 v1, v29, v1
	v_add3_u32 v0, v0, v2, s83
	ds_write_b16_d16_hi v164, v0 offset:6800
	v_bfe_u32 v0, v1, 16, 1
	v_add3_u32 v0, v1, v0, s83
	ds_write_b16_d16_hi v165, v0 offset:6800
	v_mul_f32_e32 v0, v86, v180
	v_fma_f32 v0, v87, v73, -v0
	v_add_f32_e32 v0, v14, v0
	v_mul_f32_e32 v1, v87, v180
	v_fmac_f32_e32 v1, v86, v73
	v_bfe_u32 v2, v0, 16, 1
	v_add_f32_e32 v1, v30, v1
	v_add3_u32 v0, v0, v2, s83
	ds_write_b16_d16_hi v164, v0 offset:7072
	v_bfe_u32 v0, v1, 16, 1
	v_add3_u32 v0, v1, v0, s83
	ds_write_b16_d16_hi v165, v0 offset:7072
	v_mul_f32_e32 v0, v78, v180
	v_fma_f32 v0, v77, v73, -v0
	v_add_f32_e32 v0, v6, v0
	v_mul_f32_e32 v1, v77, v180
	v_fmac_f32_e32 v1, v78, v73
	v_bfe_u32 v2, v0, 16, 1
	v_add_f32_e32 v1, v7, v1
	v_add3_u32 v0, v0, v2, s83
	ds_write_b16_d16_hi v164, v0 offset:7344
	v_bfe_u32 v0, v1, 16, 1
	v_or_b32_e32 v70, v72, v166
	v_lshl_add_u64 v[68:69], v[126:127], 0, v[112:113]
	v_add3_u32 v0, v1, v0, s83
	v_mad_i64_i32 v[4:5], s[14:15], v70, s82, v[68:69]
	ds_write_b16_d16_hi v165, v0 offset:7344
	ds_read_b128 v[0:3], v173
	ds_read_b128 v[12:15], v173 offset:64
	v_mov_b64_e32 v[240:241], v[4:5]
	global_load_ushort v4, v[4:5], off
	s_waitcnt vmcnt(4) lgkmcnt(1)
	v_mfma_f32_16x16x32_bf16 v[0:3], v[0:3], v[44:47], 0
	ds_read_b128 v[20:23], v173 offset:128
	s_waitcnt vmcnt(0)
	v_lshlrev_b32_e32 v4, 16, v4
	s_waitcnt lgkmcnt(1)
	v_mfma_f32_16x16x32_bf16 v[0:3], v[12:15], v[40:43], v[0:3]
	ds_read_b128 v[12:15], v173 offset:192
	s_waitcnt lgkmcnt(1)
	v_mfma_f32_16x16x32_bf16 v[0:3], v[20:23], v[36:39], v[0:3]
	s_waitcnt lgkmcnt(0)
	v_mfma_f32_16x16x32_bf16 v[0:3], v[12:15], v[32:35], v[0:3]
	s_nop 7
	v_fma_f32 v0, v81, v4, v0
	v_mul_f32_e32 v4, 0x3f3504f3, v0
	v_cmp_nlt_f32_e64 s[14:15], |v4|, 1.0
	s_and_saveexec_b64 s[36:37], s[14:15]
	s_xor_b64 s[74:75], exec, s[36:37]
	s_cbranch_execz .LBB0_518
	v_fma_f32 v5, |v4|, s94, v176
	v_fma_f32 v5, |v4|, v5, s95
	v_fma_f32 v5, |v4|, v5, s96
	v_fma_f32 v5, |v4|, v5, s97
	v_fma_f32 v5, |v4|, v5, s0
	v_fma_f32 v5, |v4|, v5, s1
	v_fma_f32 v5, |v4|, v5, |v4|
	v_mul_f32_e32 v8, 0xbfb8aa3b, v5
	v_fma_f32 v11, v5, s10, -v8
	v_rndne_f32_e32 v12, v8
	v_fmac_f32_e32 v11, 0xb2a5705f, v5
	v_sub_f32_e32 v8, v8, v12
	v_add_f32_e32 v8, v8, v11
	v_cvt_i32_f32_e32 v11, v12
	v_exp_f32_e32 v8, v8
	v_cmp_nlt_f32_e32 vcc, s11, v5
	v_ldexp_f32 v8, v8, v11
	s_nop 0
	v_cndmask_b32_e32 v8, 0, v8, vcc
	v_cmp_ngt_f32_e32 vcc, s12, v5
	s_nop 1
	v_cndmask_b32_e32 v5, v177, v8, vcc
	v_sub_f32_e32 v5, 1.0, v5
.LBB0_518:
	s_andn2_saveexec_b64 s[74:75], s[74:75]
	v_mul_f32_e32 v5, v4, v4
	v_fmamk_f32 v8, v5, 0xba1345e1, v174
	v_fmaak_f32 v8, v5, v8, 0xbcdac9b8
	v_fmaak_f32 v8, v5, v8, 0x3de703be
	v_fmaak_f32 v8, v5, v8, 0xbec09330
	v_fmaak_f32 v5, v5, v8, 0x3e0375d0
	v_fma_f32 v5, |v4|, v5, |v4|
	s_or_b64 exec, exec, s[74:75]
	v_bfi_b32 v4, s13, v5, v4
	v_ashrrev_i32_e32 v71, 31, v70
	v_lshlrev_b32_e32 v112, 2, v109
	v_mul_f32_e32 v0, 0.5, v0
	v_add_f32_e32 v4, 1.0, v4
	v_lshl_add_u64 v[72:73], v[128:129], 0, v[112:113]
	v_mul_f32_e32 v0, v0, v4
	v_lshlrev_b64 v[4:5], 11, v[70:71]
	v_lshl_add_u64 v[4:5], v[72:73], 0, v[4:5]
	global_store_dword v[4:5], v0, off
	v_cvt_pk_bf16_f32 v248, v0, v0
	global_store_short v[240:241], v248, off
	v_or_b32_e32 v0, 1, v70
	v_mad_i64_i32 v[4:5], s[14:15], v0, s82, v[68:69]
	v_mov_b64_e32 v[242:243], v[4:5]
	global_load_ushort v4, v[4:5], off
	s_waitcnt vmcnt(0)
	v_lshlrev_b32_e32 v4, 16, v4
	v_fma_f32 v4, v81, v4, v1
	v_mul_f32_e32 v5, 0x3f3504f3, v4
	v_cmp_nlt_f32_e64 s[14:15], |v5|, 1.0
	s_and_saveexec_b64 s[36:37], s[14:15]
	s_xor_b64 s[74:75], exec, s[36:37]
	s_cbranch_execz .LBB0_522
	v_fma_f32 v1, |v5|, s94, v176
	v_fma_f32 v1, |v5|, v1, s95
	v_fma_f32 v1, |v5|, v1, s96
	v_fma_f32 v1, |v5|, v1, s97
	v_fma_f32 v1, |v5|, v1, s0
	v_fma_f32 v1, |v5|, v1, s1
	v_fma_f32 v1, |v5|, v1, |v5|
	v_mul_f32_e32 v8, 0xbfb8aa3b, v1
	v_fma_f32 v11, v1, s10, -v8
	v_rndne_f32_e32 v12, v8
	v_fmac_f32_e32 v11, 0xb2a5705f, v1
	v_sub_f32_e32 v8, v8, v12
	v_add_f32_e32 v8, v8, v11
	v_cvt_i32_f32_e32 v11, v12
	v_exp_f32_e32 v8, v8
	v_cmp_nlt_f32_e32 vcc, s11, v1
	v_ldexp_f32 v8, v8, v11
	s_nop 0
	v_cndmask_b32_e32 v8, 0, v8, vcc
	v_cmp_ngt_f32_e32 vcc, s12, v1
	s_nop 1
	v_cndmask_b32_e32 v1, v177, v8, vcc
	v_sub_f32_e32 v8, 1.0, v1
.LBB0_522:
	s_andn2_saveexec_b64 s[74:75], s[74:75]
	v_mul_f32_e32 v1, v5, v5
	v_fmamk_f32 v8, v1, 0xba1345e1, v174
	v_fmaak_f32 v8, v1, v8, 0xbcdac9b8
	v_fmaak_f32 v8, v1, v8, 0x3de703be
	v_fmaak_f32 v8, v1, v8, 0xbec09330
	v_fmaak_f32 v1, v1, v8, 0x3e0375d0
	v_fma_f32 v8, |v5|, v1, |v5|
	s_or_b64 exec, exec, s[74:75]
	v_ashrrev_i32_e32 v1, 31, v0
	v_bfi_b32 v5, s13, v8, v5
	v_mul_f32_e32 v4, 0.5, v4
	v_add_f32_e32 v5, 1.0, v5
	v_lshlrev_b64 v[0:1], 11, v[0:1]
	v_mul_f32_e32 v4, v4, v5
	v_lshl_add_u64 v[0:1], v[72:73], 0, v[0:1]
	global_store_dword v[0:1], v4, off
	v_cvt_pk_bf16_f32 v248, v4, v4
	global_store_short v[242:243], v248, off
	v_or_b32_e32 v0, 2, v70
	v_mad_i64_i32 v[4:5], s[14:15], v0, s82, v[68:69]
	v_mov_b64_e32 v[244:245], v[4:5]
	global_load_ushort v1, v[4:5], off
	s_waitcnt vmcnt(0)
	v_lshlrev_b32_e32 v1, 16, v1
	v_fma_f32 v2, v81, v1, v2
	v_mul_f32_e32 v4, 0x3f3504f3, v2
	v_cmp_nlt_f32_e64 s[14:15], |v4|, 1.0
	s_and_saveexec_b64 s[36:37], s[14:15]
	s_xor_b64 s[74:75], exec, s[36:37]
	s_cbranch_execz .LBB0_526
	v_fma_f32 v1, |v4|, s94, v176
	v_fma_f32 v1, |v4|, v1, s95
	v_fma_f32 v1, |v4|, v1, s96
	v_fma_f32 v1, |v4|, v1, s97
	v_fma_f32 v1, |v4|, v1, s0
	v_fma_f32 v1, |v4|, v1, s1
	v_fma_f32 v1, |v4|, v1, |v4|
	v_mul_f32_e32 v5, 0xbfb8aa3b, v1
	v_fma_f32 v8, v1, s10, -v5
	v_rndne_f32_e32 v11, v5
	v_fmac_f32_e32 v8, 0xb2a5705f, v1
	v_sub_f32_e32 v5, v5, v11
	v_add_f32_e32 v5, v5, v8
	v_cvt_i32_f32_e32 v8, v11
	v_exp_f32_e32 v5, v5
	v_cmp_nlt_f32_e32 vcc, s11, v1
	v_ldexp_f32 v5, v5, v8
	s_nop 0
	v_cndmask_b32_e32 v5, 0, v5, vcc
	v_cmp_ngt_f32_e32 vcc, s12, v1
	s_nop 1
	v_cndmask_b32_e32 v1, v177, v5, vcc
	v_sub_f32_e32 v5, 1.0, v1
.LBB0_526:
	s_andn2_saveexec_b64 s[74:75], s[74:75]
	v_mul_f32_e32 v1, v4, v4
	v_fmamk_f32 v5, v1, 0xba1345e1, v174
	v_fmaak_f32 v5, v1, v5, 0xbcdac9b8
	v_fmaak_f32 v5, v1, v5, 0x3de703be
	v_fmaak_f32 v5, v1, v5, 0xbec09330
	v_fmaak_f32 v1, v1, v5, 0x3e0375d0
	v_fma_f32 v5, |v4|, v1, |v4|
	s_or_b64 exec, exec, s[74:75]
	v_ashrrev_i32_e32 v1, 31, v0
	v_bfi_b32 v4, s13, v5, v4
	v_mul_f32_e32 v2, 0.5, v2
	v_add_f32_e32 v4, 1.0, v4
	v_lshlrev_b64 v[0:1], 11, v[0:1]
	v_mul_f32_e32 v2, v2, v4
	v_lshl_add_u64 v[0:1], v[72:73], 0, v[0:1]
	global_store_dword v[0:1], v2, off
	v_cvt_pk_bf16_f32 v248, v2, v2
	global_store_short v[244:245], v248, off
	v_or_b32_e32 v0, 3, v70
	v_mad_i64_i32 v[4:5], s[14:15], v0, s82, v[68:69]
	v_mov_b64_e32 v[246:247], v[4:5]
	global_load_ushort v1, v[4:5], off
	s_waitcnt vmcnt(0)
	v_lshlrev_b32_e32 v1, 16, v1
	v_fmac_f32_e32 v3, v81, v1
	v_mul_f32_e32 v2, 0x3f3504f3, v3
	v_cmp_nlt_f32_e64 s[14:15], |v2|, 1.0
	s_and_saveexec_b64 s[36:37], s[14:15]
	s_xor_b64 s[74:75], exec, s[36:37]
	s_cbranch_execz .LBB0_530
	v_fma_f32 v1, |v2|, s94, v176
	v_fma_f32 v1, |v2|, v1, s95
	v_fma_f32 v1, |v2|, v1, s96
	v_fma_f32 v1, |v2|, v1, s97
	v_fma_f32 v1, |v2|, v1, s0
	v_fma_f32 v1, |v2|, v1, s1
	v_fma_f32 v1, |v2|, v1, |v2|
	v_mul_f32_e32 v4, 0xbfb8aa3b, v1
	v_fma_f32 v5, v1, s10, -v4
	v_rndne_f32_e32 v8, v4
	v_fmac_f32_e32 v5, 0xb2a5705f, v1
	v_sub_f32_e32 v4, v4, v8
	v_add_f32_e32 v4, v4, v5
	v_cvt_i32_f32_e32 v5, v8
	v_exp_f32_e32 v4, v4
	v_cmp_nlt_f32_e32 vcc, s11, v1
	v_ldexp_f32 v4, v4, v5
	s_nop 0
	v_cndmask_b32_e32 v4, 0, v4, vcc
	v_cmp_ngt_f32_e32 vcc, s12, v1
	s_nop 1
	v_cndmask_b32_e32 v1, v177, v4, vcc
	v_sub_f32_e32 v4, 1.0, v1
.LBB0_530:
	s_andn2_saveexec_b64 s[74:75], s[74:75]
	v_mul_f32_e32 v1, v2, v2
	v_fmamk_f32 v4, v1, 0xba1345e1, v174
	v_fmaak_f32 v4, v1, v4, 0xbcdac9b8
	v_fmaak_f32 v4, v1, v4, 0x3de703be
	v_fmaak_f32 v4, v1, v4, 0xbec09330
	v_fmaak_f32 v1, v1, v4, 0x3e0375d0
	v_fma_f32 v4, |v2|, v1, |v2|
	s_or_b64 exec, exec, s[74:75]
	v_ashrrev_i32_e32 v1, 31, v0
	v_bfi_b32 v2, s13, v4, v2
	v_mul_f32_e32 v3, 0.5, v3
	v_add_f32_e32 v2, 1.0, v2
	v_lshlrev_b64 v[0:1], 11, v[0:1]
	v_mul_f32_e32 v2, v3, v2
	v_lshl_add_u64 v[0:1], v[72:73], 0, v[0:1]
	global_store_dword v[0:1], v2, off
	v_cvt_pk_bf16_f32 v248, v2, v2
	global_store_short v[246:247], v248, off
	ds_read_b128 v[0:3], v173 offset:4352
	ds_read_b128 v[12:15], v173 offset:4416
	v_or_b32_e32 v4, 16, v70
	s_waitcnt lgkmcnt(1)
	v_mfma_f32_16x16x32_bf16 v[0:3], v[0:3], v[44:47], 0
	s_waitcnt lgkmcnt(0)
	v_mfma_f32_16x16x32_bf16 v[0:3], v[12:15], v[40:43], v[0:3]
	ds_read_b128 v[12:15], v173 offset:4480
	s_waitcnt lgkmcnt(0)
	v_mfma_f32_16x16x32_bf16 v[0:3], v[12:15], v[36:39], v[0:3]
	ds_read_b128 v[12:15], v173 offset:4544
	s_waitcnt lgkmcnt(0)
	v_mfma_f32_16x16x32_bf16 v[0:3], v[12:15], v[32:35], v[0:3]
	v_mad_i64_i32 v[12:13], s[14:15], v4, s82, v[68:69]
	v_mov_b64_e32 v[240:241], v[12:13]
	global_load_ushort v5, v[12:13], off
	s_waitcnt vmcnt(0)
	v_lshlrev_b32_e32 v5, 16, v5
	s_nop 3
	v_fma_f32 v0, v81, v5, v0
	v_mul_f32_e32 v8, 0x3f3504f3, v0
	v_cmp_nlt_f32_e64 s[14:15], |v8|, 1.0
	s_and_saveexec_b64 s[36:37], s[14:15]
	s_xor_b64 s[74:75], exec, s[36:37]
	s_cbranch_execz .LBB0_534
	v_fma_f32 v5, |v8|, s94, v176
	v_fma_f32 v5, |v8|, v5, s95
	v_fma_f32 v5, |v8|, v5, s96
	v_fma_f32 v5, |v8|, v5, s97
	v_fma_f32 v5, |v8|, v5, s0
	v_fma_f32 v5, |v8|, v5, s1
	v_fma_f32 v5, |v8|, v5, |v8|
	v_mul_f32_e32 v11, 0xbfb8aa3b, v5
	v_fma_f32 v12, v5, s10, -v11
	v_rndne_f32_e32 v13, v11
	v_fmac_f32_e32 v12, 0xb2a5705f, v5
	v_sub_f32_e32 v11, v11, v13
	v_add_f32_e32 v11, v11, v12
	v_cvt_i32_f32_e32 v12, v13
	v_exp_f32_e32 v11, v11
	v_cmp_nlt_f32_e32 vcc, s11, v5
	v_ldexp_f32 v11, v11, v12
	s_nop 0
	v_cndmask_b32_e32 v11, 0, v11, vcc
	v_cmp_ngt_f32_e32 vcc, s12, v5
	s_nop 1
	v_cndmask_b32_e32 v5, v177, v11, vcc
	v_sub_f32_e32 v11, 1.0, v5
.LBB0_534:
	s_andn2_saveexec_b64 s[74:75], s[74:75]
	v_mul_f32_e32 v5, v8, v8
	v_fmamk_f32 v11, v5, 0xba1345e1, v174
	v_fmaak_f32 v11, v5, v11, 0xbcdac9b8
	v_fmaak_f32 v11, v5, v11, 0x3de703be
	v_fmaak_f32 v11, v5, v11, 0xbec09330
	v_fmaak_f32 v5, v5, v11, 0x3e0375d0
	v_fma_f32 v11, |v8|, v5, |v8|
	s_or_b64 exec, exec, s[74:75]
	v_ashrrev_i32_e32 v5, 31, v4
	v_bfi_b32 v8, s13, v11, v8
	v_mul_f32_e32 v0, 0.5, v0
	v_add_f32_e32 v8, 1.0, v8
	v_lshlrev_b64 v[4:5], 11, v[4:5]
	v_mul_f32_e32 v0, v0, v8
	v_lshl_add_u64 v[4:5], v[72:73], 0, v[4:5]
	global_store_dword v[4:5], v0, off
	v_cvt_pk_bf16_f32 v248, v0, v0
	global_store_short v[240:241], v248, off
	v_or_b32_e32 v0, 17, v70
	v_mad_i64_i32 v[4:5], s[14:15], v0, s82, v[68:69]
	v_mov_b64_e32 v[242:243], v[4:5]
	global_load_ushort v4, v[4:5], off
	s_waitcnt vmcnt(0)
	v_lshlrev_b32_e32 v4, 16, v4
	v_fma_f32 v4, v81, v4, v1
	v_mul_f32_e32 v5, 0x3f3504f3, v4
	v_cmp_nlt_f32_e64 s[14:15], |v5|, 1.0
	s_and_saveexec_b64 s[36:37], s[14:15]
	s_xor_b64 s[74:75], exec, s[36:37]
	s_cbranch_execz .LBB0_538
	v_fma_f32 v1, |v5|, s94, v176
	v_fma_f32 v1, |v5|, v1, s95
	v_fma_f32 v1, |v5|, v1, s96
	v_fma_f32 v1, |v5|, v1, s97
	v_fma_f32 v1, |v5|, v1, s0
	v_fma_f32 v1, |v5|, v1, s1
	v_fma_f32 v1, |v5|, v1, |v5|
	v_mul_f32_e32 v8, 0xbfb8aa3b, v1
	v_fma_f32 v11, v1, s10, -v8
	v_rndne_f32_e32 v12, v8
	v_fmac_f32_e32 v11, 0xb2a5705f, v1
	v_sub_f32_e32 v8, v8, v12
	v_add_f32_e32 v8, v8, v11
	v_cvt_i32_f32_e32 v11, v12
	v_exp_f32_e32 v8, v8
	v_cmp_nlt_f32_e32 vcc, s11, v1
	v_ldexp_f32 v8, v8, v11
	s_nop 0
	v_cndmask_b32_e32 v8, 0, v8, vcc
	v_cmp_ngt_f32_e32 vcc, s12, v1
	s_nop 1
	v_cndmask_b32_e32 v1, v177, v8, vcc
	v_sub_f32_e32 v8, 1.0, v1
.LBB0_538:
	s_andn2_saveexec_b64 s[74:75], s[74:75]
	v_mul_f32_e32 v1, v5, v5
	v_fmamk_f32 v8, v1, 0xba1345e1, v174
	v_fmaak_f32 v8, v1, v8, 0xbcdac9b8
	v_fmaak_f32 v8, v1, v8, 0x3de703be
	v_fmaak_f32 v8, v1, v8, 0xbec09330
	v_fmaak_f32 v1, v1, v8, 0x3e0375d0
	v_fma_f32 v8, |v5|, v1, |v5|
	s_or_b64 exec, exec, s[74:75]
	v_ashrrev_i32_e32 v1, 31, v0
	v_bfi_b32 v5, s13, v8, v5
	v_mul_f32_e32 v4, 0.5, v4
	v_add_f32_e32 v5, 1.0, v5
	v_lshlrev_b64 v[0:1], 11, v[0:1]
	v_mul_f32_e32 v4, v4, v5
	v_lshl_add_u64 v[0:1], v[72:73], 0, v[0:1]
	global_store_dword v[0:1], v4, off
	v_cvt_pk_bf16_f32 v248, v4, v4
	global_store_short v[242:243], v248, off
	v_or_b32_e32 v0, 18, v70
	v_mad_i64_i32 v[4:5], s[14:15], v0, s82, v[68:69]
	v_mov_b64_e32 v[244:245], v[4:5]
	global_load_ushort v1, v[4:5], off
	s_waitcnt vmcnt(0)
	v_lshlrev_b32_e32 v1, 16, v1
	v_fma_f32 v2, v81, v1, v2
	v_mul_f32_e32 v4, 0x3f3504f3, v2
	v_cmp_nlt_f32_e64 s[14:15], |v4|, 1.0
	s_and_saveexec_b64 s[36:37], s[14:15]
	s_xor_b64 s[74:75], exec, s[36:37]
	s_cbranch_execz .LBB0_542
	v_fma_f32 v1, |v4|, s94, v176
	v_fma_f32 v1, |v4|, v1, s95
	v_fma_f32 v1, |v4|, v1, s96
	v_fma_f32 v1, |v4|, v1, s97
	v_fma_f32 v1, |v4|, v1, s0
	v_fma_f32 v1, |v4|, v1, s1
	v_fma_f32 v1, |v4|, v1, |v4|
	v_mul_f32_e32 v5, 0xbfb8aa3b, v1
	v_fma_f32 v8, v1, s10, -v5
	v_rndne_f32_e32 v11, v5
	v_fmac_f32_e32 v8, 0xb2a5705f, v1
	v_sub_f32_e32 v5, v5, v11
	v_add_f32_e32 v5, v5, v8
	v_cvt_i32_f32_e32 v8, v11
	v_exp_f32_e32 v5, v5
	v_cmp_nlt_f32_e32 vcc, s11, v1
	v_ldexp_f32 v5, v5, v8
	s_nop 0
	v_cndmask_b32_e32 v5, 0, v5, vcc
	v_cmp_ngt_f32_e32 vcc, s12, v1
	s_nop 1
	v_cndmask_b32_e32 v1, v177, v5, vcc
	v_sub_f32_e32 v5, 1.0, v1
.LBB0_542:
	s_andn2_saveexec_b64 s[74:75], s[74:75]
	v_mul_f32_e32 v1, v4, v4
	v_fmamk_f32 v5, v1, 0xba1345e1, v174
	v_fmaak_f32 v5, v1, v5, 0xbcdac9b8
	v_fmaak_f32 v5, v1, v5, 0x3de703be
	v_fmaak_f32 v5, v1, v5, 0xbec09330
	v_fmaak_f32 v1, v1, v5, 0x3e0375d0
	v_fma_f32 v5, |v4|, v1, |v4|
	s_or_b64 exec, exec, s[74:75]
	v_ashrrev_i32_e32 v1, 31, v0
	v_bfi_b32 v4, s13, v5, v4
	v_mul_f32_e32 v2, 0.5, v2
	v_add_f32_e32 v4, 1.0, v4
	v_lshlrev_b64 v[0:1], 11, v[0:1]
	v_mul_f32_e32 v2, v2, v4
	v_lshl_add_u64 v[0:1], v[72:73], 0, v[0:1]
	global_store_dword v[0:1], v2, off
	v_cvt_pk_bf16_f32 v248, v2, v2
	global_store_short v[244:245], v248, off
	v_or_b32_e32 v0, 19, v70
	v_mad_i64_i32 v[4:5], s[14:15], v0, s82, v[68:69]
	v_mov_b64_e32 v[246:247], v[4:5]
	global_load_ushort v1, v[4:5], off
	s_waitcnt vmcnt(0)
	v_lshlrev_b32_e32 v1, 16, v1
	v_fmac_f32_e32 v3, v81, v1
	v_mul_f32_e32 v2, 0x3f3504f3, v3
	v_cmp_nlt_f32_e64 s[14:15], |v2|, 1.0
	s_and_saveexec_b64 s[36:37], s[14:15]
	s_xor_b64 s[74:75], exec, s[36:37]
	s_cbranch_execz .LBB0_546
	v_fma_f32 v1, |v2|, s94, v176
	v_fma_f32 v1, |v2|, v1, s95
	v_fma_f32 v1, |v2|, v1, s96
	v_fma_f32 v1, |v2|, v1, s97
	v_fma_f32 v1, |v2|, v1, s0
	v_fma_f32 v1, |v2|, v1, s1
	v_fma_f32 v1, |v2|, v1, |v2|
	v_mul_f32_e32 v4, 0xbfb8aa3b, v1
	v_fma_f32 v5, v1, s10, -v4
	v_rndne_f32_e32 v8, v4
	v_fmac_f32_e32 v5, 0xb2a5705f, v1
	v_sub_f32_e32 v4, v4, v8
	v_add_f32_e32 v4, v4, v5
	v_cvt_i32_f32_e32 v5, v8
	v_exp_f32_e32 v4, v4
	v_cmp_nlt_f32_e32 vcc, s11, v1
	v_ldexp_f32 v4, v4, v5
	s_nop 0
	v_cndmask_b32_e32 v4, 0, v4, vcc
	v_cmp_ngt_f32_e32 vcc, s12, v1
	s_nop 1
	v_cndmask_b32_e32 v1, v177, v4, vcc
	v_sub_f32_e32 v4, 1.0, v1
.LBB0_546:
	s_andn2_saveexec_b64 s[74:75], s[74:75]
	v_mul_f32_e32 v1, v2, v2
	v_fmamk_f32 v4, v1, 0xba1345e1, v174
	v_fmaak_f32 v4, v1, v4, 0xbcdac9b8
	v_fmaak_f32 v4, v1, v4, 0x3de703be
	v_fmaak_f32 v4, v1, v4, 0xbec09330
	v_fmaak_f32 v1, v1, v4, 0x3e0375d0
	v_fma_f32 v4, |v2|, v1, |v2|
	s_or_b64 exec, exec, s[74:75]
	v_ashrrev_i32_e32 v1, 31, v0
	v_bfi_b32 v2, s13, v4, v2
	v_mul_f32_e32 v3, 0.5, v3
	v_add_f32_e32 v2, 1.0, v2
	v_lshlrev_b64 v[0:1], 11, v[0:1]
	v_readlane_b32 s16, v238, 32
	v_mul_f32_e32 v2, v3, v2
	v_lshl_add_u64 v[0:1], v[72:73], 0, v[0:1]
	v_readlane_b32 s17, v238, 33
	global_store_dword v[0:1], v2, off
	v_cvt_pk_bf16_f32 v248, v2, v2
	global_store_short v[246:247], v248, off
	v_or_b32_e32 v2, 32, v95
	v_mov_b64_e32 v[0:1], s[16:17]
	v_mad_i64_i32 v[0:1], s[14:15], v2, s82, v[0:1]
	v_lshlrev_b32_e32 v112, 1, v109
	v_lshl_add_u64 v[0:1], v[0:1], 0, v[112:113]
	v_mov_b32_e32 v109, v113
	v_lshl_add_u64 v[0:1], v[0:1], 0, v[108:109]
	global_load_dwordx4 v[64:67], v[0:1], off
	v_mul_f32_e32 v19, v80, v179
	v_mul_f32_e32 v21, v80, v178
	v_mul_f32_e32 v23, v78, v18
	v_mul_f32_e32 v25, v78, v17
	v_cndmask_b32_e64 v16, v143, v145, s[4:5]
	v_cndmask_b32_e64 v20, v139, v144, s[4:5]
	v_cndmask_b32_e64 v22, v7, v10, s[4:5]
	v_cndmask_b32_e64 v24, v6, v9, s[4:5]
	v_fmac_f32_e32 v19, v79, v178
	v_fma_f32 v21, v79, v179, -v21
	v_fmac_f32_e32 v23, v77, v17
	v_fma_f32 v17, v77, v18, -v25
	v_readlane_b32 s18, v238, 34
	v_readlane_b32 s19, v238, 35
	v_readlane_b32 s20, v238, 36
	v_readlane_b32 s21, v238, 37
	v_readlane_b32 s22, v238, 38
	v_readlane_b32 s23, v238, 39
	v_readlane_b32 s24, v238, 40
	v_readlane_b32 s25, v238, 41
	v_readlane_b32 s26, v238, 42
	v_readlane_b32 s27, v238, 43
	v_readlane_b32 s28, v238, 44
	v_readlane_b32 s29, v238, 45
	v_readlane_b32 s30, v238, 46
	v_readlane_b32 s31, v238, 47
	s_waitcnt vmcnt(0)
	v_mfma_f32_32x32x16_bf16 v[0:15], v[64:67], v[60:63], 0
	v_add_f32_e32 v60, v16, v19
	v_add_f32_e32 v61, v20, v21
	v_add_f32_e32 v62, v22, v23
	v_add_f32_e32 v63, v24, v17
	v_mul_f32_e32 v144, v80, v60
	v_fma_f32 v144, v79, v61, -v144
	v_mfma_f32_32x32x16_bf16 v[16:31], v[64:67], v[56:59], 0
	s_nop 11
	v_mul_f32_e32 v56, v89, v16
	v_mul_f32_e32 v57, v90, v16
	v_mul_f32_e32 v109, v89, v28
	v_fma_f32 v56, v90, v0, -v56
	v_mul_f32_e32 v112, v90, v28
	v_fmac_f32_e32 v57, v89, v0
	v_fma_f32 v109, v90, v12, -v109
	v_add_f32_e32 v1, v1, v56
	v_fmac_f32_e32 v112, v89, v12
	v_add_f32_e32 v17, v17, v57
	v_add_f32_e32 v13, v13, v109
	v_mul_f32_e32 v57, v89, v1
	v_add_f32_e32 v29, v29, v112
	v_mul_f32_e32 v56, v89, v17
	v_mul_f32_e32 v112, v89, v13
	v_fmac_f32_e32 v57, v90, v17
	v_mul_f32_e32 v109, v89, v29
	v_fma_f32 v56, v90, v1, -v56
	v_fmac_f32_e32 v112, v90, v29
	v_add_f32_e32 v18, v18, v57
	v_fma_f32 v109, v90, v13, -v109
	v_add_f32_e32 v2, v2, v56
	v_add_f32_e32 v30, v30, v112
	v_mul_f32_e32 v56, v89, v18
	v_add_f32_e32 v14, v14, v109
	v_mul_f32_e32 v109, v89, v30
	v_fma_f32 v56, v90, v2, -v56
	v_mul_f32_e32 v57, v89, v2
	v_fma_f32 v109, v90, v14, -v109
	v_add_f32_e32 v3, v3, v56
	v_mul_f32_e32 v112, v89, v14
	v_fmac_f32_e32 v57, v90, v18
	v_add_f32_e32 v56, v15, v109
	ds_bpermute_b32 v15, v88, v3
	v_mul_f32_e32 v58, v89, v20
	v_add_f32_e32 v19, v19, v57
	v_fmac_f32_e32 v112, v90, v30
	v_mul_f32_e32 v59, v90, v20
	v_mul_f32_e32 v71, v89, v24
	v_fma_f32 v58, v90, v4, -v58
	v_add_f32_e32 v57, v31, v112
	ds_bpermute_b32 v31, v88, v19
	v_mul_f32_e32 v95, v90, v24
	v_fmac_f32_e32 v59, v89, v4
	v_fma_f32 v71, v90, v8, -v71
	v_add_f32_e32 v5, v5, v58
	v_fmac_f32_e32 v95, v89, v8
	v_add_f32_e32 v21, v21, v59
	v_add_f32_e32 v9, v9, v71
	v_mul_f32_e32 v59, v89, v5
	v_add_f32_e32 v25, v25, v95
	v_mul_f32_e32 v58, v89, v21
	v_mul_f32_e32 v95, v89, v9
	v_fmac_f32_e32 v59, v90, v21
	s_waitcnt lgkmcnt(1)
	v_cndmask_b32_e64 v139, v15, v3, s[4:5]
	v_mul_f32_e32 v71, v89, v25
	v_fma_f32 v58, v90, v5, -v58
	v_fmac_f32_e32 v95, v90, v25
	v_add_f32_e32 v22, v22, v59
	v_add_f32_e32 v139, v144, v139
	v_mul_f32_e32 v144, v79, v60
	v_fma_f32 v71, v90, v9, -v71
	v_add_f32_e32 v6, v6, v58
	v_add_f32_e32 v26, v26, v95
	v_mul_f32_e32 v58, v89, v22
	s_waitcnt lgkmcnt(0)
	v_cndmask_b32_e64 v143, v31, v19, s[4:5]
	v_fmac_f32_e32 v144, v80, v61
	v_add_f32_e32 v10, v10, v71
	v_mul_f32_e32 v71, v89, v26
	v_fma_f32 v58, v90, v6, -v58
	v_add_f32_e32 v143, v144, v143
	v_mul_f32_e32 v59, v89, v6
	v_fma_f32 v71, v90, v10, -v71
	v_add_f32_e32 v7, v7, v58
	v_mul_f32_e32 v144, v80, v143
	v_mul_f32_e32 v95, v89, v10
	v_fmac_f32_e32 v59, v90, v22
	v_add_f32_e32 v11, v11, v71
	ds_bpermute_b32 v71, v88, v7
	v_cndmask_b32_e64 v15, v3, v15, s[4:5]
	v_fma_f32 v144, v79, v139, -v144
	v_fmac_f32_e32 v95, v90, v26
	v_add_f32_e32 v23, v23, v59
	v_add_f32_e32 v15, v15, v144
	v_mul_f32_e32 v144, v80, v139
	v_add_f32_e32 v27, v27, v95
	ds_bpermute_b32 v95, v88, v23
	v_cndmask_b32_e64 v31, v19, v31, s[4:5]
	v_fmac_f32_e32 v144, v79, v143
	v_add_f32_e32 v31, v31, v144
	v_mul_f32_e32 v144, v80, v31
	v_cndmask_b32_e64 v143, v143, v60, s[4:5]
	s_waitcnt lgkmcnt(1)
	v_cndmask_b32_e64 v60, v71, v7, s[4:5]
	v_fma_f32 v144, v79, v15, -v144
	v_add_f32_e32 v60, v60, v144
	v_mul_f32_e32 v144, v80, v15
	v_cndmask_b32_e64 v139, v139, v61, s[4:5]
	s_waitcnt lgkmcnt(0)
	v_cndmask_b32_e64 v61, v95, v23, s[4:5]
	v_fmac_f32_e32 v144, v79, v31
	v_add_f32_e32 v61, v61, v144
	v_mul_f32_e32 v144, v80, v61
	ds_bpermute_b32 v109, v88, v11
	v_cndmask_b32_e64 v71, v7, v71, s[4:5]
	v_fma_f32 v144, v79, v60, -v144
	v_add_f32_e32 v71, v71, v144
	v_mul_f32_e32 v144, v80, v60
	ds_bpermute_b32 v112, v88, v27
	v_cndmask_b32_e64 v95, v23, v95, s[4:5]
	v_fmac_f32_e32 v144, v79, v61
	v_add_f32_e32 v95, v95, v144
	v_mul_f32_e32 v144, v80, v95
	v_cndmask_b32_e64 v15, v60, v15, s[4:5]
	s_waitcnt lgkmcnt(1)
	v_cndmask_b32_e64 v60, v109, v11, s[4:5]
	v_fma_f32 v144, v79, v71, -v144
	v_add_f32_e32 v60, v60, v144
	v_mul_f32_e32 v144, v80, v71
	v_cndmask_b32_e64 v31, v61, v31, s[4:5]
	s_waitcnt lgkmcnt(0)
	v_cndmask_b32_e64 v61, v112, v27, s[4:5]
	v_fmac_f32_e32 v144, v79, v95
	v_add_f32_e32 v61, v61, v144
	v_mul_f32_e32 v144, v80, v61
	ds_bpermute_b32 v58, v88, v56
	v_cndmask_b32_e64 v109, v11, v109, s[4:5]
	v_fma_f32 v144, v79, v60, -v144
	v_add_f32_e32 v109, v109, v144
	v_mul_f32_e32 v144, v80, v60
	ds_bpermute_b32 v59, v88, v57
	v_cndmask_b32_e64 v112, v27, v112, s[4:5]
	v_fmac_f32_e32 v144, v79, v61
	v_add_f32_e32 v112, v112, v144
	v_mul_f32_e32 v144, v80, v112
	v_cndmask_b32_e64 v71, v60, v71, s[4:5]
	s_waitcnt lgkmcnt(1)
	v_cndmask_b32_e64 v60, v58, v56, s[4:5]
	v_fma_f32 v144, v79, v109, -v144
	v_add_f32_e32 v60, v60, v144
	v_mul_f32_e32 v144, v80, v109
	v_cndmask_b32_e64 v95, v61, v95, s[4:5]
	s_waitcnt lgkmcnt(0)
	v_cndmask_b32_e64 v61, v59, v57, s[4:5]
	v_fmac_f32_e32 v144, v79, v112
	v_add_f32_e32 v61, v61, v144
	v_mul_f32_e32 v144, v89, v143
	v_fma_f32 v144, v90, v139, -v144
	v_add_f32_e32 v0, v0, v144
	v_mul_f32_e32 v144, v90, v143
	v_fmac_f32_e32 v144, v89, v139
	v_add_f32_e32 v16, v16, v144
	v_bfe_u32 v144, v0, 16, 1
	v_add3_u32 v0, v0, v144, s83
	ds_write_b16_d16_hi v163, v0
	v_bfe_u32 v0, v16, 16, 1
	v_add3_u32 v0, v16, v0, s83
	ds_write_b16_d16_hi v163, v0 offset:128
	v_mul_f32_e32 v0, v91, v143
	v_fma_f32 v0, v92, v139, -v0
	v_add_f32_e32 v0, v1, v0
	v_mul_f32_e32 v1, v92, v143
	v_fmac_f32_e32 v1, v91, v139
	v_bfe_u32 v16, v0, 16, 1
	v_add_f32_e32 v1, v17, v1
	v_add3_u32 v0, v0, v16, s83
	ds_write_b16_d16_hi v163, v0 offset:272
	v_bfe_u32 v0, v1, 16, 1
	v_add3_u32 v0, v1, v0, s83
	ds_write_b16_d16_hi v163, v0 offset:400
	v_mul_f32_e32 v0, v93, v143
	v_fma_f32 v0, v94, v139, -v0
	v_add_f32_e32 v0, v2, v0
	v_mul_f32_e32 v1, v94, v143
	v_fmac_f32_e32 v1, v93, v139
	v_bfe_u32 v2, v0, 16, 1
	v_add_f32_e32 v1, v18, v1
	v_add3_u32 v0, v0, v2, s83
	ds_write_b16_d16_hi v163, v0 offset:544
	v_bfe_u32 v0, v1, 16, 1
	v_add3_u32 v0, v1, v0, s83
	ds_write_b16_d16_hi v163, v0 offset:672
	v_mul_f32_e32 v0, v80, v143
	v_fma_f32 v0, v79, v139, -v0
	v_add_f32_e32 v0, v3, v0
	v_mul_f32_e32 v1, v79, v143
	v_fmac_f32_e32 v1, v80, v139
	v_bfe_u32 v2, v0, 16, 1
	v_add_f32_e32 v1, v19, v1
	v_add3_u32 v0, v0, v2, s83
	ds_write_b16_d16_hi v163, v0 offset:816
	v_bfe_u32 v0, v1, 16, 1
	v_add3_u32 v0, v1, v0, s83
	ds_write_b16_d16_hi v163, v0 offset:944
	v_mul_f32_e32 v0, v89, v31
	v_fma_f32 v0, v90, v15, -v0
	v_add_f32_e32 v0, v4, v0
	v_mul_f32_e32 v1, v90, v31
	v_fmac_f32_e32 v1, v89, v15
	v_bfe_u32 v2, v0, 16, 1
	v_add_f32_e32 v1, v20, v1
	v_add3_u32 v0, v0, v2, s83
	ds_write_b16_d16_hi v163, v0 offset:2176
	v_bfe_u32 v0, v1, 16, 1
	v_add3_u32 v0, v1, v0, s83
	ds_write_b16_d16_hi v163, v0 offset:2304
	v_mul_f32_e32 v0, v91, v31
	v_fma_f32 v0, v92, v15, -v0
	v_add_f32_e32 v0, v5, v0
	v_mul_f32_e32 v1, v92, v31
	v_fmac_f32_e32 v1, v91, v15
	v_bfe_u32 v2, v0, 16, 1
	v_add_f32_e32 v1, v21, v1
	v_add3_u32 v0, v0, v2, s83
	ds_write_b16_d16_hi v163, v0 offset:2448
	v_bfe_u32 v0, v1, 16, 1
	v_add3_u32 v0, v1, v0, s83
	ds_write_b16_d16_hi v163, v0 offset:2576
	v_mul_f32_e32 v0, v93, v31
	v_fma_f32 v0, v94, v15, -v0
	v_add_f32_e32 v0, v6, v0
	v_mul_f32_e32 v1, v94, v31
	v_fmac_f32_e32 v1, v93, v15
	v_bfe_u32 v2, v0, 16, 1
	v_add_f32_e32 v1, v22, v1
	v_add3_u32 v0, v0, v2, s83
	ds_write_b16_d16_hi v163, v0 offset:2720
	v_bfe_u32 v0, v1, 16, 1
	v_add3_u32 v0, v1, v0, s83
	ds_write_b16_d16_hi v163, v0 offset:2848
	v_mul_f32_e32 v0, v80, v31
	v_fma_f32 v0, v79, v15, -v0
	v_add_f32_e32 v0, v7, v0
	v_mul_f32_e32 v1, v79, v31
	v_fmac_f32_e32 v1, v80, v15
	v_bfe_u32 v2, v0, 16, 1
	v_add_f32_e32 v1, v23, v1
	v_add3_u32 v0, v0, v2, s83
	ds_write_b16_d16_hi v163, v0 offset:2992
	v_bfe_u32 v0, v1, 16, 1
	v_add3_u32 v0, v1, v0, s83
	ds_write_b16_d16_hi v163, v0 offset:3120
	v_mul_f32_e32 v0, v89, v95
	v_fma_f32 v0, v90, v71, -v0
	v_add_f32_e32 v0, v8, v0
	v_mul_f32_e32 v1, v90, v95
	v_fmac_f32_e32 v1, v89, v71
	v_bfe_u32 v2, v0, 16, 1
	v_add_f32_e32 v1, v24, v1
	v_add3_u32 v0, v0, v2, s83
	ds_write_b16_d16_hi v163, v0 offset:4352
	v_bfe_u32 v0, v1, 16, 1
	v_add3_u32 v0, v1, v0, s83
	ds_write_b16_d16_hi v163, v0 offset:4480
	v_mul_f32_e32 v0, v91, v95
	v_fma_f32 v0, v92, v71, -v0
	v_add_f32_e32 v0, v9, v0
	v_mul_f32_e32 v1, v92, v95
	v_fmac_f32_e32 v1, v91, v71
	v_bfe_u32 v2, v0, 16, 1
	v_add_f32_e32 v1, v25, v1
	v_add3_u32 v0, v0, v2, s83
	ds_write_b16_d16_hi v163, v0 offset:4624
	v_bfe_u32 v0, v1, 16, 1
	v_add3_u32 v0, v1, v0, s83
	ds_write_b16_d16_hi v163, v0 offset:4752
	v_mul_f32_e32 v0, v93, v95
	v_fma_f32 v0, v94, v71, -v0
	v_add_f32_e32 v0, v10, v0
	v_mul_f32_e32 v1, v94, v95
	v_fmac_f32_e32 v1, v93, v71
	v_bfe_u32 v2, v0, 16, 1
	v_add_f32_e32 v1, v26, v1
	v_add3_u32 v0, v0, v2, s83
	ds_write_b16_d16_hi v163, v0 offset:4896
	v_bfe_u32 v0, v1, 16, 1
	v_add3_u32 v0, v1, v0, s83
	ds_write_b16_d16_hi v163, v0 offset:5024
	v_mul_f32_e32 v0, v80, v95
	v_fma_f32 v0, v79, v71, -v0
	v_add_f32_e32 v0, v11, v0
	v_mul_f32_e32 v1, v79, v95
	v_fmac_f32_e32 v1, v80, v71
	v_bfe_u32 v2, v0, 16, 1
	v_add_f32_e32 v1, v27, v1
	v_add3_u32 v0, v0, v2, s83
	ds_write_b16_d16_hi v163, v0 offset:5168
	v_bfe_u32 v0, v1, 16, 1
	v_cndmask_b32_e64 v112, v61, v112, s[4:5]
	v_add3_u32 v0, v1, v0, s83
	v_cndmask_b32_e64 v109, v60, v109, s[4:5]
	ds_write_b16_d16_hi v163, v0 offset:5296
	v_mul_f32_e32 v0, v89, v112
	v_fma_f32 v0, v90, v109, -v0
	v_add_f32_e32 v0, v12, v0
	v_mul_f32_e32 v1, v90, v112
	v_fmac_f32_e32 v1, v89, v109
	v_bfe_u32 v2, v0, 16, 1
	v_add_f32_e32 v1, v28, v1
	v_add3_u32 v0, v0, v2, s83
	ds_write_b16_d16_hi v163, v0 offset:6528
	v_bfe_u32 v0, v1, 16, 1
	v_add3_u32 v0, v1, v0, s83
	ds_write_b16_d16_hi v163, v0 offset:6656
	v_mul_f32_e32 v0, v91, v112
	v_fma_f32 v0, v92, v109, -v0
	v_add_f32_e32 v0, v13, v0
	v_mul_f32_e32 v1, v92, v112
	v_fmac_f32_e32 v1, v91, v109
	v_bfe_u32 v2, v0, 16, 1
	v_add_f32_e32 v1, v29, v1
	v_add3_u32 v0, v0, v2, s83
	ds_write_b16_d16_hi v163, v0 offset:6800
	v_bfe_u32 v0, v1, 16, 1
	v_add3_u32 v0, v1, v0, s83
	ds_write_b16_d16_hi v163, v0 offset:6928
	v_mul_f32_e32 v0, v93, v112
	v_fma_f32 v0, v94, v109, -v0
	v_add_f32_e32 v0, v14, v0
	v_mul_f32_e32 v1, v94, v112
	v_fmac_f32_e32 v1, v93, v109
	v_bfe_u32 v2, v0, 16, 1
	v_add_f32_e32 v1, v30, v1
	v_add3_u32 v0, v0, v2, s83
	ds_write_b16_d16_hi v163, v0 offset:7072
	v_bfe_u32 v0, v1, 16, 1
	v_add3_u32 v0, v1, v0, s83
	ds_write_b16_d16_hi v163, v0 offset:7200
	v_mul_f32_e32 v0, v80, v112
	v_fma_f32 v0, v79, v109, -v0
	v_add_f32_e32 v16, v56, v0
	v_mul_f32_e32 v17, v79, v112
	v_fmac_f32_e32 v17, v80, v109
	v_bfe_u32 v18, v16, 16, 1
	v_add_f32_e32 v17, v57, v17
	v_add3_u32 v16, v16, v18, s83
	ds_write_b16_d16_hi v163, v16 offset:7344
	v_bfe_u32 v16, v17, 16, 1
	v_add3_u32 v16, v17, v16, s83
	ds_write_b16_d16_hi v163, v16 offset:7472
	v_mfma_f32_32x32x16_bf16 v[16:31], v[64:67], v[48:51], 0
	v_mfma_f32_32x32x16_bf16 v[0:15], v[64:67], v[52:55], 0
	s_nop 10
	v_mul_f32_e32 v48, v82, v16
	v_mul_f32_e32 v66, v78, v62
	v_fma_f32 v66, v77, v63, -v66
	v_fma_f32 v48, v83, v0, -v48
	v_add_f32_e32 v1, v1, v48
	v_mul_f32_e32 v48, v83, v16
	v_fmac_f32_e32 v48, v82, v0
	v_add_f32_e32 v17, v17, v48
	v_mul_f32_e32 v48, v82, v17
	v_fma_f32 v48, v83, v1, -v48
	v_add_f32_e32 v2, v2, v48
	v_mul_f32_e32 v48, v82, v1
	v_fmac_f32_e32 v48, v83, v17
	v_add_f32_e32 v18, v18, v48
	v_mul_f32_e32 v48, v82, v18
	v_fma_f32 v48, v83, v2, -v48
	v_add_f32_e32 v3, v3, v48
	v_mul_f32_e32 v48, v82, v2
	v_fmac_f32_e32 v48, v83, v18
	v_add_f32_e32 v19, v19, v48
	v_mul_f32_e32 v48, v82, v20
	v_fma_f32 v48, v83, v4, -v48
	v_add_f32_e32 v5, v5, v48
	v_mul_f32_e32 v48, v83, v20
	v_fmac_f32_e32 v48, v82, v4
	v_add_f32_e32 v21, v21, v48
	v_mul_f32_e32 v48, v82, v21
	v_fma_f32 v48, v83, v5, -v48
	v_add_f32_e32 v48, v6, v48
	v_mul_f32_e32 v6, v82, v5
	v_fmac_f32_e32 v6, v83, v21
	v_add_f32_e32 v22, v22, v6
	v_mul_f32_e32 v6, v82, v22
	v_fma_f32 v6, v83, v48, -v6
	v_add_f32_e32 v49, v7, v6
	v_mul_f32_e32 v6, v82, v48
	v_fmac_f32_e32 v6, v83, v22
	v_add_f32_e32 v23, v23, v6
	v_mul_f32_e32 v6, v82, v24
	v_fma_f32 v6, v83, v8, -v6
	v_add_f32_e32 v50, v9, v6
	v_mul_f32_e32 v6, v83, v24
	v_fmac_f32_e32 v6, v82, v8
	v_add_f32_e32 v25, v25, v6
	v_mul_f32_e32 v6, v82, v25
	v_fma_f32 v6, v83, v50, -v6
	v_add_f32_e32 v51, v10, v6
	v_mul_f32_e32 v6, v82, v50
	v_fmac_f32_e32 v6, v83, v25
	v_add_f32_e32 v26, v26, v6
	v_mul_f32_e32 v6, v82, v26
	v_fma_f32 v6, v83, v51, -v6
	v_add_f32_e32 v52, v11, v6
	v_mul_f32_e32 v6, v82, v51
	v_fmac_f32_e32 v6, v83, v26
	v_add_f32_e32 v27, v27, v6
	v_mul_f32_e32 v6, v82, v28
	v_fma_f32 v6, v83, v12, -v6
	v_add_f32_e32 v53, v13, v6
	v_mul_f32_e32 v6, v83, v28
	ds_bpermute_b32 v11, v88, v3
	v_fmac_f32_e32 v6, v82, v12
	v_add_f32_e32 v29, v29, v6
	ds_bpermute_b32 v13, v88, v19
	v_mul_f32_e32 v6, v82, v29
	v_fma_f32 v6, v83, v53, -v6
	v_add_f32_e32 v14, v14, v6
	v_mul_f32_e32 v6, v82, v53
	s_waitcnt lgkmcnt(1)
	v_cndmask_b32_e64 v64, v11, v3, s[4:5]
	v_fmac_f32_e32 v6, v83, v29
	v_add_f32_e32 v64, v66, v64
	v_mul_f32_e32 v66, v77, v62
	v_add_f32_e32 v30, v30, v6
	s_waitcnt lgkmcnt(0)
	v_cndmask_b32_e64 v65, v13, v19, s[4:5]
	v_fmac_f32_e32 v66, v78, v63
	v_mul_f32_e32 v6, v82, v30
	v_add_f32_e32 v65, v66, v65
	v_fma_f32 v6, v83, v14, -v6
	v_mul_f32_e32 v66, v78, v65
	v_add_f32_e32 v6, v15, v6
	v_mul_f32_e32 v7, v82, v14
	ds_bpermute_b32 v15, v88, v49
	v_cndmask_b32_e64 v11, v3, v11, s[4:5]
	v_fma_f32 v66, v77, v64, -v66
	v_fmac_f32_e32 v7, v83, v30
	v_add_f32_e32 v11, v11, v66
	v_mul_f32_e32 v66, v78, v64
	v_add_f32_e32 v7, v31, v7
	ds_bpermute_b32 v31, v88, v23
	v_cndmask_b32_e64 v13, v19, v13, s[4:5]
	v_fmac_f32_e32 v66, v77, v65
	v_add_f32_e32 v13, v13, v66
	v_mul_f32_e32 v66, v78, v13
	v_cndmask_b32_e64 v63, v64, v63, s[4:5]
	s_waitcnt lgkmcnt(1)
	v_cndmask_b32_e64 v64, v15, v49, s[4:5]
	v_fma_f32 v66, v77, v11, -v66
	v_add_f32_e32 v64, v64, v66
	v_mul_f32_e32 v66, v78, v11
	v_cndmask_b32_e64 v62, v65, v62, s[4:5]
	s_waitcnt lgkmcnt(0)
	v_cndmask_b32_e64 v65, v31, v23, s[4:5]
	v_fmac_f32_e32 v66, v77, v13
	v_add_f32_e32 v65, v65, v66
	v_mul_f32_e32 v66, v78, v65
	ds_bpermute_b32 v54, v88, v52
	v_cndmask_b32_e64 v15, v49, v15, s[4:5]
	v_fma_f32 v66, v77, v64, -v66
	v_add_f32_e32 v15, v15, v66
	v_mul_f32_e32 v66, v78, v64
	ds_bpermute_b32 v55, v88, v27
	v_cndmask_b32_e64 v31, v23, v31, s[4:5]
	v_fmac_f32_e32 v66, v77, v65
	v_add_f32_e32 v31, v31, v66
	v_mul_f32_e32 v66, v78, v31
	v_cndmask_b32_e64 v64, v64, v11, s[4:5]
	s_waitcnt lgkmcnt(1)
	v_cndmask_b32_e64 v11, v54, v52, s[4:5]
	v_fma_f32 v66, v77, v15, -v66
	v_add_f32_e32 v11, v11, v66
	v_mul_f32_e32 v66, v78, v15
	v_cndmask_b32_e64 v65, v65, v13, s[4:5]
	s_waitcnt lgkmcnt(0)
	v_cndmask_b32_e64 v13, v55, v27, s[4:5]
	v_fmac_f32_e32 v66, v77, v31
	v_add_f32_e32 v13, v13, v66
	v_mul_f32_e32 v66, v78, v13
	ds_bpermute_b32 v9, v88, v6
	v_cndmask_b32_e64 v54, v52, v54, s[4:5]
	v_fma_f32 v66, v77, v11, -v66
	v_add_f32_e32 v54, v54, v66
	v_mul_f32_e32 v66, v78, v11
	ds_bpermute_b32 v10, v88, v7
	v_cndmask_b32_e64 v55, v27, v55, s[4:5]
	v_fmac_f32_e32 v66, v77, v13
	v_add_f32_e32 v55, v55, v66
	v_mul_f32_e32 v66, v78, v55
	v_cndmask_b32_e64 v15, v11, v15, s[4:5]
	s_waitcnt lgkmcnt(1)
	v_cndmask_b32_e64 v11, v9, v6, s[4:5]
	v_fma_f32 v66, v77, v54, -v66
	v_add_f32_e32 v11, v11, v66
	v_mul_f32_e32 v66, v78, v54
	v_cndmask_b32_e64 v31, v13, v31, s[4:5]
	s_waitcnt lgkmcnt(0)
	v_cndmask_b32_e64 v13, v10, v7, s[4:5]
	v_fmac_f32_e32 v66, v77, v55
	v_add_f32_e32 v13, v13, v66
	v_mul_f32_e32 v66, v82, v62
	v_fma_f32 v66, v83, v63, -v66
	v_add_f32_e32 v0, v0, v66
	v_mul_f32_e32 v66, v83, v62
	v_fmac_f32_e32 v66, v82, v63
	v_add_f32_e32 v16, v16, v66
	v_bfe_u32 v66, v0, 16, 1
	v_add3_u32 v0, v0, v66, s83
	ds_write_b16_d16_hi v164, v0
	v_bfe_u32 v0, v16, 16, 1
	v_add3_u32 v0, v16, v0, s83
	ds_write_b16_d16_hi v165, v0
	v_mul_f32_e32 v0, v84, v62
	v_fma_f32 v0, v85, v63, -v0
	v_add_f32_e32 v0, v1, v0
	v_mul_f32_e32 v1, v85, v62
	v_fmac_f32_e32 v1, v84, v63
	v_bfe_u32 v16, v0, 16, 1
	v_add_f32_e32 v1, v17, v1
	v_add3_u32 v0, v0, v16, s83
	ds_write_b16_d16_hi v164, v0 offset:272
	v_bfe_u32 v0, v1, 16, 1
	v_add3_u32 v0, v1, v0, s83
	ds_write_b16_d16_hi v165, v0 offset:272
	v_mul_f32_e32 v0, v86, v62
	v_fma_f32 v0, v87, v63, -v0
	v_add_f32_e32 v0, v2, v0
	v_mul_f32_e32 v1, v87, v62
	v_fmac_f32_e32 v1, v86, v63
	v_bfe_u32 v2, v0, 16, 1
	v_add_f32_e32 v1, v18, v1
	v_add3_u32 v0, v0, v2, s83
	ds_write_b16_d16_hi v164, v0 offset:544
	v_bfe_u32 v0, v1, 16, 1
	v_add3_u32 v0, v1, v0, s83
	ds_write_b16_d16_hi v165, v0 offset:544
	v_mul_f32_e32 v0, v78, v62
	v_fma_f32 v0, v77, v63, -v0
	v_add_f32_e32 v0, v3, v0
	v_mul_f32_e32 v1, v77, v62
	v_fmac_f32_e32 v1, v78, v63
	v_bfe_u32 v2, v0, 16, 1
	v_add_f32_e32 v1, v19, v1
	v_add3_u32 v0, v0, v2, s83
	ds_write_b16_d16_hi v164, v0 offset:816
	v_bfe_u32 v0, v1, 16, 1
	v_add3_u32 v0, v1, v0, s83
	ds_write_b16_d16_hi v165, v0 offset:816
	v_mul_f32_e32 v0, v82, v65
	v_fma_f32 v0, v83, v64, -v0
	v_add_f32_e32 v0, v4, v0
	v_mul_f32_e32 v1, v83, v65
	v_fmac_f32_e32 v1, v82, v64
	v_bfe_u32 v2, v0, 16, 1
	v_add_f32_e32 v1, v20, v1
	v_add3_u32 v0, v0, v2, s83
	ds_write_b16_d16_hi v164, v0 offset:2176
	v_bfe_u32 v0, v1, 16, 1
	v_add3_u32 v0, v1, v0, s83
	ds_write_b16_d16_hi v165, v0 offset:2176
	v_mul_f32_e32 v0, v84, v65
	v_fma_f32 v0, v85, v64, -v0
	v_add_f32_e32 v0, v5, v0
	v_mul_f32_e32 v1, v85, v65
	v_fmac_f32_e32 v1, v84, v64
	v_bfe_u32 v2, v0, 16, 1
	v_add_f32_e32 v1, v21, v1
	v_add3_u32 v0, v0, v2, s83
	ds_write_b16_d16_hi v164, v0 offset:2448
	v_bfe_u32 v0, v1, 16, 1
	v_add3_u32 v0, v1, v0, s83
	ds_write_b16_d16_hi v165, v0 offset:2448
	v_mul_f32_e32 v0, v86, v65
	v_fma_f32 v0, v87, v64, -v0
	v_add_f32_e32 v0, v48, v0
	v_mul_f32_e32 v1, v87, v65
	v_fmac_f32_e32 v1, v86, v64
	v_bfe_u32 v2, v0, 16, 1
	v_add_f32_e32 v1, v22, v1
	v_add3_u32 v0, v0, v2, s83
	ds_write_b16_d16_hi v164, v0 offset:2720
	v_bfe_u32 v0, v1, 16, 1
	v_add3_u32 v0, v1, v0, s83
	ds_write_b16_d16_hi v165, v0 offset:2720
	v_mul_f32_e32 v0, v78, v65
	v_fma_f32 v0, v77, v64, -v0
	v_add_f32_e32 v0, v49, v0
	v_mul_f32_e32 v1, v77, v65
	v_fmac_f32_e32 v1, v78, v64
	v_bfe_u32 v2, v0, 16, 1
	v_add_f32_e32 v1, v23, v1
	v_add3_u32 v0, v0, v2, s83
	ds_write_b16_d16_hi v164, v0 offset:2992
	v_bfe_u32 v0, v1, 16, 1
	v_add3_u32 v0, v1, v0, s83
	ds_write_b16_d16_hi v165, v0 offset:2992
	v_mul_f32_e32 v0, v82, v31
	v_fma_f32 v0, v83, v15, -v0
	v_add_f32_e32 v0, v8, v0
	v_mul_f32_e32 v1, v83, v31
	v_fmac_f32_e32 v1, v82, v15
	v_bfe_u32 v2, v0, 16, 1
	v_add_f32_e32 v1, v24, v1
	v_add3_u32 v0, v0, v2, s83
	ds_write_b16_d16_hi v164, v0 offset:4352
	v_bfe_u32 v0, v1, 16, 1
	v_add3_u32 v0, v1, v0, s83
	ds_write_b16_d16_hi v165, v0 offset:4352
	v_mul_f32_e32 v0, v84, v31
	v_fma_f32 v0, v85, v15, -v0
	v_add_f32_e32 v0, v50, v0
	v_mul_f32_e32 v1, v85, v31
	v_fmac_f32_e32 v1, v84, v15
	v_bfe_u32 v2, v0, 16, 1
	v_add_f32_e32 v1, v25, v1
	v_add3_u32 v0, v0, v2, s83
	ds_write_b16_d16_hi v164, v0 offset:4624
	v_bfe_u32 v0, v1, 16, 1
	v_add3_u32 v0, v1, v0, s83
	ds_write_b16_d16_hi v165, v0 offset:4624
	v_mul_f32_e32 v0, v86, v31
	v_fma_f32 v0, v87, v15, -v0
	v_add_f32_e32 v0, v51, v0
	v_mul_f32_e32 v1, v87, v31
	v_fmac_f32_e32 v1, v86, v15
	v_bfe_u32 v2, v0, 16, 1
	v_add_f32_e32 v1, v26, v1
	v_add3_u32 v0, v0, v2, s83
	ds_write_b16_d16_hi v164, v0 offset:4896
	v_bfe_u32 v0, v1, 16, 1
	v_add3_u32 v0, v1, v0, s83
	ds_write_b16_d16_hi v165, v0 offset:4896
	v_mul_f32_e32 v0, v78, v31
	v_fma_f32 v0, v77, v15, -v0
	v_add_f32_e32 v0, v52, v0
	v_mul_f32_e32 v1, v77, v31
	v_fmac_f32_e32 v1, v78, v15
	v_bfe_u32 v2, v0, 16, 1
	v_add_f32_e32 v1, v27, v1
	v_add3_u32 v0, v0, v2, s83
	ds_write_b16_d16_hi v164, v0 offset:5168
	v_bfe_u32 v0, v1, 16, 1
	v_cndmask_b32_e64 v55, v13, v55, s[4:5]
	v_add3_u32 v0, v1, v0, s83
	v_cndmask_b32_e64 v54, v11, v54, s[4:5]
	ds_write_b16_d16_hi v165, v0 offset:5168
	v_mul_f32_e32 v0, v82, v55
	v_fma_f32 v0, v83, v54, -v0
	v_add_f32_e32 v0, v12, v0
	v_mul_f32_e32 v1, v83, v55
	v_fmac_f32_e32 v1, v82, v54
	v_bfe_u32 v2, v0, 16, 1
	v_add_f32_e32 v1, v28, v1
	v_add3_u32 v0, v0, v2, s83
	ds_write_b16_d16_hi v164, v0 offset:6528
	v_bfe_u32 v0, v1, 16, 1
	v_add3_u32 v0, v1, v0, s83
	ds_write_b16_d16_hi v165, v0 offset:6528
	v_mul_f32_e32 v0, v84, v55
	v_fma_f32 v0, v85, v54, -v0
	v_add_f32_e32 v0, v53, v0
	v_mul_f32_e32 v1, v85, v55
	v_fmac_f32_e32 v1, v84, v54
	v_bfe_u32 v2, v0, 16, 1
	v_add_f32_e32 v1, v29, v1
	v_add3_u32 v0, v0, v2, s83
	ds_write_b16_d16_hi v164, v0 offset:6800
	v_bfe_u32 v0, v1, 16, 1
	v_add3_u32 v0, v1, v0, s83
	ds_write_b16_d16_hi v165, v0 offset:6800
	v_mul_f32_e32 v0, v86, v55
	v_fma_f32 v0, v87, v54, -v0
	v_add_f32_e32 v0, v14, v0
	v_mul_f32_e32 v1, v87, v55
	v_fmac_f32_e32 v1, v86, v54
	v_bfe_u32 v2, v0, 16, 1
	v_add_f32_e32 v1, v30, v1
	v_add3_u32 v0, v0, v2, s83
	ds_write_b16_d16_hi v164, v0 offset:7072
	v_bfe_u32 v0, v1, 16, 1
	v_add3_u32 v0, v1, v0, s83
	ds_write_b16_d16_hi v165, v0 offset:7072
	v_mul_f32_e32 v0, v78, v55
	v_fma_f32 v0, v77, v54, -v0
	v_add_f32_e32 v0, v6, v0
	v_mul_f32_e32 v1, v77, v55
	v_fmac_f32_e32 v1, v78, v54
	v_bfe_u32 v2, v0, 16, 1
	v_add_f32_e32 v1, v7, v1
	v_add3_u32 v0, v0, v2, s83
	ds_write_b16_d16_hi v164, v0 offset:7344
	v_bfe_u32 v0, v1, 16, 1
	v_add3_u32 v0, v1, v0, s83
	ds_write_b16_d16_hi v165, v0 offset:7344
	ds_read_b128 v[0:3], v173
	ds_read_b128 v[14:17], v173 offset:64
	s_waitcnt lgkmcnt(1)
	v_mfma_f32_16x16x32_bf16 v[0:3], v[0:3], v[44:47], 0
	v_or_b32_e32 v4, 32, v70
	ds_read_b128 v[18:21], v173 offset:192
	s_waitcnt lgkmcnt(1)
	v_mfma_f32_16x16x32_bf16 v[0:3], v[14:17], v[40:43], v[0:3]
	ds_read_b128 v[14:17], v173 offset:128
	s_waitcnt lgkmcnt(0)
	v_mfma_f32_16x16x32_bf16 v[0:3], v[14:17], v[36:39], v[0:3]
	v_mad_i64_i32 v[14:15], s[14:15], v4, s82, v[68:69]
	v_mov_b64_e32 v[240:241], v[14:15]
	global_load_ushort v5, v[14:15], off
	v_mfma_f32_16x16x32_bf16 v[0:3], v[18:21], v[32:35], v[0:3]
	s_waitcnt vmcnt(0)
	v_lshlrev_b32_e32 v5, 16, v5
	s_nop 5
	v_fma_f32 v0, v81, v5, v0
	v_mul_f32_e32 v8, 0x3f3504f3, v0
	v_cmp_nlt_f32_e64 s[14:15], |v8|, 1.0
	s_and_saveexec_b64 s[36:37], s[14:15]
	s_xor_b64 s[74:75], exec, s[36:37]
	s_cbranch_execz .LBB0_550
	v_fma_f32 v5, |v8|, s94, v176
	v_fma_f32 v5, |v8|, v5, s95
	v_fma_f32 v5, |v8|, v5, s96
	v_fma_f32 v5, |v8|, v5, s97
	v_fma_f32 v5, |v8|, v5, s0
	v_fma_f32 v5, |v8|, v5, s1
	v_fma_f32 v5, |v8|, v5, |v8|
	v_mul_f32_e32 v12, 0xbfb8aa3b, v5
	v_fma_f32 v14, v5, s10, -v12
	v_rndne_f32_e32 v15, v12
	v_fmac_f32_e32 v14, 0xb2a5705f, v5
	v_sub_f32_e32 v12, v12, v15
	v_add_f32_e32 v12, v12, v14
	v_cvt_i32_f32_e32 v14, v15
	v_exp_f32_e32 v12, v12
	v_cmp_nlt_f32_e32 vcc, s11, v5
	v_ldexp_f32 v12, v12, v14
	s_nop 0
	v_cndmask_b32_e32 v12, 0, v12, vcc
	v_cmp_ngt_f32_e32 vcc, s12, v5
	s_nop 1
	v_cndmask_b32_e32 v5, v177, v12, vcc
	v_sub_f32_e32 v12, 1.0, v5
.LBB0_550:
	s_andn2_saveexec_b64 s[74:75], s[74:75]
	v_mul_f32_e32 v5, v8, v8
	v_fmamk_f32 v12, v5, 0xba1345e1, v174
	v_fmaak_f32 v12, v5, v12, 0xbcdac9b8
	v_fmaak_f32 v12, v5, v12, 0x3de703be
	v_fmaak_f32 v12, v5, v12, 0xbec09330
	v_fmaak_f32 v5, v5, v12, 0x3e0375d0
	v_fma_f32 v12, |v8|, v5, |v8|
	s_or_b64 exec, exec, s[74:75]
	v_ashrrev_i32_e32 v5, 31, v4
	v_bfi_b32 v8, s13, v12, v8
	v_mul_f32_e32 v0, 0.5, v0
	v_add_f32_e32 v8, 1.0, v8
	v_lshlrev_b64 v[4:5], 11, v[4:5]
	v_mul_f32_e32 v0, v0, v8
	v_lshl_add_u64 v[4:5], v[72:73], 0, v[4:5]
	global_store_dword v[4:5], v0, off
	v_cvt_pk_bf16_f32 v248, v0, v0
	global_store_short v[240:241], v248, off
	v_or_b32_e32 v0, 33, v70
	v_mad_i64_i32 v[4:5], s[14:15], v0, s82, v[68:69]
	v_mov_b64_e32 v[242:243], v[4:5]
	global_load_ushort v4, v[4:5], off
	s_waitcnt vmcnt(0)
	v_lshlrev_b32_e32 v4, 16, v4
	v_fma_f32 v4, v81, v4, v1
	v_mul_f32_e32 v5, 0x3f3504f3, v4
	v_cmp_nlt_f32_e64 s[14:15], |v5|, 1.0
	s_and_saveexec_b64 s[36:37], s[14:15]
	s_xor_b64 s[74:75], exec, s[36:37]
	s_cbranch_execz .LBB0_554
	v_fma_f32 v1, |v5|, s94, v176
	v_fma_f32 v1, |v5|, v1, s95
	v_fma_f32 v1, |v5|, v1, s96
	v_fma_f32 v1, |v5|, v1, s97
	v_fma_f32 v1, |v5|, v1, s0
	v_fma_f32 v1, |v5|, v1, s1
	v_fma_f32 v1, |v5|, v1, |v5|
	v_mul_f32_e32 v8, 0xbfb8aa3b, v1
	v_fma_f32 v12, v1, s10, -v8
	v_rndne_f32_e32 v14, v8
	v_fmac_f32_e32 v12, 0xb2a5705f, v1
	v_sub_f32_e32 v8, v8, v14
	v_add_f32_e32 v8, v8, v12
	v_cvt_i32_f32_e32 v12, v14
	v_exp_f32_e32 v8, v8
	v_cmp_nlt_f32_e32 vcc, s11, v1
	v_ldexp_f32 v8, v8, v12
	s_nop 0
	v_cndmask_b32_e32 v8, 0, v8, vcc
	v_cmp_ngt_f32_e32 vcc, s12, v1
	s_nop 1
	v_cndmask_b32_e32 v1, v177, v8, vcc
	v_sub_f32_e32 v8, 1.0, v1
.LBB0_554:
	s_andn2_saveexec_b64 s[74:75], s[74:75]
	v_mul_f32_e32 v1, v5, v5
	v_fmamk_f32 v8, v1, 0xba1345e1, v174
	v_fmaak_f32 v8, v1, v8, 0xbcdac9b8
	v_fmaak_f32 v8, v1, v8, 0x3de703be
	v_fmaak_f32 v8, v1, v8, 0xbec09330
	v_fmaak_f32 v1, v1, v8, 0x3e0375d0
	v_fma_f32 v8, |v5|, v1, |v5|
	s_or_b64 exec, exec, s[74:75]
	v_ashrrev_i32_e32 v1, 31, v0
	v_bfi_b32 v5, s13, v8, v5
	v_mul_f32_e32 v4, 0.5, v4
	v_add_f32_e32 v5, 1.0, v5
	v_lshlrev_b64 v[0:1], 11, v[0:1]
	v_mul_f32_e32 v4, v4, v5
	v_lshl_add_u64 v[0:1], v[72:73], 0, v[0:1]
	global_store_dword v[0:1], v4, off
	v_cvt_pk_bf16_f32 v248, v4, v4
	global_store_short v[242:243], v248, off
	v_or_b32_e32 v0, 34, v70
	v_mad_i64_i32 v[4:5], s[14:15], v0, s82, v[68:69]
	v_mov_b64_e32 v[244:245], v[4:5]
	global_load_ushort v1, v[4:5], off
	s_waitcnt vmcnt(0)
	v_lshlrev_b32_e32 v1, 16, v1
	v_fma_f32 v2, v81, v1, v2
	v_mul_f32_e32 v4, 0x3f3504f3, v2
	v_cmp_nlt_f32_e64 s[14:15], |v4|, 1.0
	s_and_saveexec_b64 s[36:37], s[14:15]
	s_xor_b64 s[74:75], exec, s[36:37]
	s_cbranch_execz .LBB0_558
	v_fma_f32 v1, |v4|, s94, v176
	v_fma_f32 v1, |v4|, v1, s95
	v_fma_f32 v1, |v4|, v1, s96
	v_fma_f32 v1, |v4|, v1, s97
	v_fma_f32 v1, |v4|, v1, s0
	v_fma_f32 v1, |v4|, v1, s1
	v_fma_f32 v1, |v4|, v1, |v4|
	v_mul_f32_e32 v5, 0xbfb8aa3b, v1
	v_fma_f32 v8, v1, s10, -v5
	v_rndne_f32_e32 v12, v5
	v_fmac_f32_e32 v8, 0xb2a5705f, v1
	v_sub_f32_e32 v5, v5, v12
	v_add_f32_e32 v5, v5, v8
	v_cvt_i32_f32_e32 v8, v12
	v_exp_f32_e32 v5, v5
	v_cmp_nlt_f32_e32 vcc, s11, v1
	v_ldexp_f32 v5, v5, v8
	s_nop 0
	v_cndmask_b32_e32 v5, 0, v5, vcc
	v_cmp_ngt_f32_e32 vcc, s12, v1
	s_nop 1
	v_cndmask_b32_e32 v1, v177, v5, vcc
	v_sub_f32_e32 v5, 1.0, v1
.LBB0_558:
	s_andn2_saveexec_b64 s[74:75], s[74:75]
	v_mul_f32_e32 v1, v4, v4
	v_fmamk_f32 v5, v1, 0xba1345e1, v174
	v_fmaak_f32 v5, v1, v5, 0xbcdac9b8
	v_fmaak_f32 v5, v1, v5, 0x3de703be
	v_fmaak_f32 v5, v1, v5, 0xbec09330
	v_fmaak_f32 v1, v1, v5, 0x3e0375d0
	v_fma_f32 v5, |v4|, v1, |v4|
	s_or_b64 exec, exec, s[74:75]
	v_ashrrev_i32_e32 v1, 31, v0
	v_bfi_b32 v4, s13, v5, v4
	v_mul_f32_e32 v2, 0.5, v2
	v_add_f32_e32 v4, 1.0, v4
	v_lshlrev_b64 v[0:1], 11, v[0:1]
	v_mul_f32_e32 v2, v2, v4
	v_lshl_add_u64 v[0:1], v[72:73], 0, v[0:1]
	global_store_dword v[0:1], v2, off
	v_cvt_pk_bf16_f32 v248, v2, v2
	global_store_short v[244:245], v248, off
	v_or_b32_e32 v0, 35, v70
	v_mad_i64_i32 v[4:5], s[14:15], v0, s82, v[68:69]
	v_mov_b64_e32 v[246:247], v[4:5]
	global_load_ushort v1, v[4:5], off
	s_waitcnt vmcnt(0)
	v_lshlrev_b32_e32 v1, 16, v1
	v_fmac_f32_e32 v3, v81, v1
	v_mul_f32_e32 v2, 0x3f3504f3, v3
	v_cmp_nlt_f32_e64 s[14:15], |v2|, 1.0
	s_and_saveexec_b64 s[36:37], s[14:15]
	s_xor_b64 s[74:75], exec, s[36:37]
	s_cbranch_execz .LBB0_562
	v_fma_f32 v1, |v2|, s94, v176
	v_fma_f32 v1, |v2|, v1, s95
	v_fma_f32 v1, |v2|, v1, s96
	v_fma_f32 v1, |v2|, v1, s97
	v_fma_f32 v1, |v2|, v1, s0
	v_fma_f32 v1, |v2|, v1, s1
	v_fma_f32 v1, |v2|, v1, |v2|
	v_mul_f32_e32 v4, 0xbfb8aa3b, v1
	v_fma_f32 v5, v1, s10, -v4
	v_rndne_f32_e32 v8, v4
	v_fmac_f32_e32 v5, 0xb2a5705f, v1
	v_sub_f32_e32 v4, v4, v8
	v_add_f32_e32 v4, v4, v5
	v_cvt_i32_f32_e32 v5, v8
	v_exp_f32_e32 v4, v4
	v_cmp_nlt_f32_e32 vcc, s11, v1
	v_ldexp_f32 v4, v4, v5
	s_nop 0
	v_cndmask_b32_e32 v4, 0, v4, vcc
	v_cmp_ngt_f32_e32 vcc, s12, v1
	s_nop 1
	v_cndmask_b32_e32 v1, v177, v4, vcc
	v_sub_f32_e32 v4, 1.0, v1
.LBB0_562:
	s_andn2_saveexec_b64 s[74:75], s[74:75]
	v_mul_f32_e32 v1, v2, v2
	v_fmamk_f32 v4, v1, 0xba1345e1, v174
	v_fmaak_f32 v4, v1, v4, 0xbcdac9b8
	v_fmaak_f32 v4, v1, v4, 0x3de703be
	v_fmaak_f32 v4, v1, v4, 0xbec09330
	v_fmaak_f32 v1, v1, v4, 0x3e0375d0
	v_fma_f32 v4, |v2|, v1, |v2|
	s_or_b64 exec, exec, s[74:75]
	v_ashrrev_i32_e32 v1, 31, v0
	v_bfi_b32 v2, s13, v4, v2
	v_mul_f32_e32 v3, 0.5, v3
	v_add_f32_e32 v2, 1.0, v2
	v_lshlrev_b64 v[0:1], 11, v[0:1]
	v_mul_f32_e32 v2, v3, v2
	v_lshl_add_u64 v[0:1], v[72:73], 0, v[0:1]
	global_store_dword v[0:1], v2, off
	v_cvt_pk_bf16_f32 v248, v2, v2
	global_store_short v[246:247], v248, off
	ds_read_b128 v[0:3], v173 offset:4352
	ds_read_b128 v[14:17], v173 offset:4416
	v_or_b32_e32 v4, 48, v70
	s_waitcnt lgkmcnt(1)
	v_mfma_f32_16x16x32_bf16 v[0:3], v[0:3], v[44:47], 0
	s_waitcnt lgkmcnt(0)
	v_mfma_f32_16x16x32_bf16 v[0:3], v[14:17], v[40:43], v[0:3]
	ds_read_b128 v[14:17], v173 offset:4480
	s_waitcnt lgkmcnt(0)
	v_mfma_f32_16x16x32_bf16 v[0:3], v[14:17], v[36:39], v[0:3]
	ds_read_b128 v[14:17], v173 offset:4544
	s_waitcnt lgkmcnt(0)
	v_mfma_f32_16x16x32_bf16 v[0:3], v[14:17], v[32:35], v[0:3]
	v_mad_i64_i32 v[14:15], s[14:15], v4, s82, v[68:69]
	v_mov_b64_e32 v[240:241], v[14:15]
	global_load_ushort v5, v[14:15], off
	s_waitcnt vmcnt(0)
	v_lshlrev_b32_e32 v5, 16, v5
	s_nop 3
	v_fma_f32 v0, v81, v5, v0
	v_mul_f32_e32 v8, 0x3f3504f3, v0
	v_cmp_nlt_f32_e64 s[14:15], |v8|, 1.0
	s_and_saveexec_b64 s[36:37], s[14:15]
	s_xor_b64 s[74:75], exec, s[36:37]
	s_cbranch_execz .LBB0_566
	v_fma_f32 v5, |v8|, s94, v176
	v_fma_f32 v5, |v8|, v5, s95
	v_fma_f32 v5, |v8|, v5, s96
	v_fma_f32 v5, |v8|, v5, s97
	v_fma_f32 v5, |v8|, v5, s0
	v_fma_f32 v5, |v8|, v5, s1
	v_fma_f32 v5, |v8|, v5, |v8|
	v_mul_f32_e32 v12, 0xbfb8aa3b, v5
	v_fma_f32 v14, v5, s10, -v12
	v_rndne_f32_e32 v15, v12
	v_fmac_f32_e32 v14, 0xb2a5705f, v5
	v_sub_f32_e32 v12, v12, v15
	v_add_f32_e32 v12, v12, v14
	v_cvt_i32_f32_e32 v14, v15
	v_exp_f32_e32 v12, v12
	v_cmp_nlt_f32_e32 vcc, s11, v5
	v_ldexp_f32 v12, v12, v14
	s_nop 0
	v_cndmask_b32_e32 v12, 0, v12, vcc
	v_cmp_ngt_f32_e32 vcc, s12, v5
	s_nop 1
	v_cndmask_b32_e32 v5, v177, v12, vcc
	v_sub_f32_e32 v12, 1.0, v5
.LBB0_566:
	s_andn2_saveexec_b64 s[74:75], s[74:75]
	v_mul_f32_e32 v5, v8, v8
	v_fmamk_f32 v12, v5, 0xba1345e1, v174
	v_fmaak_f32 v12, v5, v12, 0xbcdac9b8
	v_fmaak_f32 v12, v5, v12, 0x3de703be
	v_fmaak_f32 v12, v5, v12, 0xbec09330
	v_fmaak_f32 v5, v5, v12, 0x3e0375d0
	v_fma_f32 v12, |v8|, v5, |v8|
	s_or_b64 exec, exec, s[74:75]
	v_ashrrev_i32_e32 v5, 31, v4
	v_bfi_b32 v8, s13, v12, v8
	v_mul_f32_e32 v0, 0.5, v0
	v_add_f32_e32 v8, 1.0, v8
	v_lshlrev_b64 v[4:5], 11, v[4:5]
	v_mul_f32_e32 v0, v0, v8
	v_lshl_add_u64 v[4:5], v[72:73], 0, v[4:5]
	global_store_dword v[4:5], v0, off
	v_cvt_pk_bf16_f32 v248, v0, v0
	global_store_short v[240:241], v248, off
	v_or_b32_e32 v0, 49, v70
	v_mad_i64_i32 v[4:5], s[14:15], v0, s82, v[68:69]
	v_mov_b64_e32 v[242:243], v[4:5]
	global_load_ushort v4, v[4:5], off
	s_waitcnt vmcnt(0)
	v_lshlrev_b32_e32 v4, 16, v4
	v_fma_f32 v4, v81, v4, v1
	v_mul_f32_e32 v5, 0x3f3504f3, v4
	v_cmp_nlt_f32_e64 s[14:15], |v5|, 1.0
	s_and_saveexec_b64 s[36:37], s[14:15]
	s_xor_b64 s[74:75], exec, s[36:37]
	s_cbranch_execz .LBB0_570
	v_fma_f32 v1, |v5|, s94, v176
	v_fma_f32 v1, |v5|, v1, s95
	v_fma_f32 v1, |v5|, v1, s96
	v_fma_f32 v1, |v5|, v1, s97
	v_fma_f32 v1, |v5|, v1, s0
	v_fma_f32 v1, |v5|, v1, s1
	v_fma_f32 v1, |v5|, v1, |v5|
	v_mul_f32_e32 v8, 0xbfb8aa3b, v1
	v_fma_f32 v12, v1, s10, -v8
	v_rndne_f32_e32 v14, v8
	v_fmac_f32_e32 v12, 0xb2a5705f, v1
	v_sub_f32_e32 v8, v8, v14
	v_add_f32_e32 v8, v8, v12
	v_cvt_i32_f32_e32 v12, v14
	v_exp_f32_e32 v8, v8
	v_cmp_nlt_f32_e32 vcc, s11, v1
	v_ldexp_f32 v8, v8, v12
	s_nop 0
	v_cndmask_b32_e32 v8, 0, v8, vcc
	v_cmp_ngt_f32_e32 vcc, s12, v1
	s_nop 1
	v_cndmask_b32_e32 v1, v177, v8, vcc
	v_sub_f32_e32 v8, 1.0, v1
.LBB0_570:
	s_andn2_saveexec_b64 s[74:75], s[74:75]
	v_mul_f32_e32 v1, v5, v5
	v_fmamk_f32 v8, v1, 0xba1345e1, v174
	v_fmaak_f32 v8, v1, v8, 0xbcdac9b8
	v_fmaak_f32 v8, v1, v8, 0x3de703be
	v_fmaak_f32 v8, v1, v8, 0xbec09330
	v_fmaak_f32 v1, v1, v8, 0x3e0375d0
	v_fma_f32 v8, |v5|, v1, |v5|
	s_or_b64 exec, exec, s[74:75]
	v_ashrrev_i32_e32 v1, 31, v0
	v_bfi_b32 v5, s13, v8, v5
	v_mul_f32_e32 v4, 0.5, v4
	v_add_f32_e32 v5, 1.0, v5
	v_lshlrev_b64 v[0:1], 11, v[0:1]
	v_mul_f32_e32 v4, v4, v5
	v_lshl_add_u64 v[0:1], v[72:73], 0, v[0:1]
	global_store_dword v[0:1], v4, off
	v_cvt_pk_bf16_f32 v248, v4, v4
	global_store_short v[242:243], v248, off
	v_or_b32_e32 v0, 50, v70
	v_mad_i64_i32 v[4:5], s[14:15], v0, s82, v[68:69]
	v_mov_b64_e32 v[244:245], v[4:5]
	global_load_ushort v1, v[4:5], off
	s_waitcnt vmcnt(0)
	v_lshlrev_b32_e32 v1, 16, v1
	v_fma_f32 v2, v81, v1, v2
	v_mul_f32_e32 v5, 0x3f3504f3, v2
	v_cmp_nlt_f32_e64 s[14:15], |v5|, 1.0
	s_and_saveexec_b64 s[36:37], s[14:15]
	s_xor_b64 s[74:75], exec, s[36:37]
	s_cbranch_execz .LBB0_574
	v_fma_f32 v1, |v5|, s94, v176
	v_fma_f32 v1, |v5|, v1, s95
	v_fma_f32 v1, |v5|, v1, s96
	v_fma_f32 v1, |v5|, v1, s97
	v_fma_f32 v1, |v5|, v1, s0
	v_fma_f32 v1, |v5|, v1, s1
	v_fma_f32 v1, |v5|, v1, |v5|
	v_mul_f32_e32 v4, 0xbfb8aa3b, v1
	v_fma_f32 v8, v1, s10, -v4
	v_rndne_f32_e32 v12, v4
	v_fmac_f32_e32 v8, 0xb2a5705f, v1
	v_sub_f32_e32 v4, v4, v12
	v_add_f32_e32 v4, v4, v8
	v_cvt_i32_f32_e32 v8, v12
	v_exp_f32_e32 v4, v4
	v_cmp_nlt_f32_e32 vcc, s11, v1
	v_ldexp_f32 v4, v4, v8
	s_nop 0
	v_cndmask_b32_e32 v4, 0, v4, vcc
	v_cmp_ngt_f32_e32 vcc, s12, v1
	s_nop 1
	v_cndmask_b32_e32 v1, v177, v4, vcc
	v_sub_f32_e32 v8, 1.0, v1
.LBB0_574:
	s_andn2_saveexec_b64 s[74:75], s[74:75]
	v_mul_f32_e32 v1, v5, v5
	v_fmamk_f32 v4, v1, 0xba1345e1, v174
	v_fmaak_f32 v4, v1, v4, 0xbcdac9b8
	v_fmaak_f32 v4, v1, v4, 0x3de703be
	v_fmaak_f32 v4, v1, v4, 0xbec09330
	v_fmaak_f32 v1, v1, v4, 0x3e0375d0
	v_fma_f32 v8, |v5|, v1, |v5|
	s_or_b64 exec, exec, s[74:75]
	v_or_b32_e32 v4, 51, v70
	v_mad_i64_i32 v[14:15], s[14:15], v4, s82, v[68:69]
	v_mov_b64_e32 v[246:247], v[14:15]
	global_load_ushort v12, v[14:15], off
	v_ashrrev_i32_e32 v1, 31, v0
	v_bfi_b32 v5, s13, v8, v5
	v_mul_f32_e32 v2, 0.5, v2
	v_add_f32_e32 v5, 1.0, v5
	v_lshlrev_b64 v[0:1], 11, v[0:1]
	v_mul_f32_e32 v2, v2, v5
	v_lshl_add_u64 v[0:1], v[72:73], 0, v[0:1]
	global_store_dword v[0:1], v2, off
	v_cvt_pk_bf16_f32 v248, v2, v2
	global_store_short v[244:245], v248, off
	s_waitcnt vmcnt(1)
	v_lshlrev_b32_e32 v0, 16, v12
	v_fmac_f32_e32 v3, v81, v0
	v_mul_f32_e32 v0, 0x3f3504f3, v3
	v_cmp_nlt_f32_e64 s[14:15], |v0|, 1.0
	s_and_saveexec_b64 s[36:37], s[14:15]
	s_xor_b64 s[74:75], exec, s[36:37]
	s_cbranch_execz .LBB0_578
	v_fma_f32 v1, |v0|, s94, v176
	v_fma_f32 v1, |v0|, v1, s95
	v_fma_f32 v1, |v0|, v1, s96
	v_fma_f32 v1, |v0|, v1, s97
	v_fma_f32 v1, |v0|, v1, s0
	v_fma_f32 v1, |v0|, v1, s1
	v_fma_f32 v1, |v0|, v1, |v0|
	v_mul_f32_e32 v2, 0xbfb8aa3b, v1
	v_fma_f32 v5, v1, s10, -v2
	v_rndne_f32_e32 v8, v2
	v_fmac_f32_e32 v5, 0xb2a5705f, v1
	v_sub_f32_e32 v2, v2, v8
	v_add_f32_e32 v2, v2, v5
	v_cvt_i32_f32_e32 v5, v8
	v_exp_f32_e32 v2, v2
	v_cmp_nlt_f32_e32 vcc, s11, v1
	v_ldexp_f32 v2, v2, v5
	s_nop 0
	v_cndmask_b32_e32 v2, 0, v2, vcc
	v_cmp_ngt_f32_e32 vcc, s12, v1
	s_nop 1
	v_cndmask_b32_e32 v1, v177, v2, vcc
	v_sub_f32_e32 v1, 1.0, v1
.LBB0_578:
	s_andn2_saveexec_b64 s[74:75], s[74:75]
	v_mul_f32_e32 v1, v0, v0
	v_fmamk_f32 v2, v1, 0xba1345e1, v174
	v_fmaak_f32 v2, v1, v2, 0xbcdac9b8
	v_fmaak_f32 v2, v1, v2, 0x3de703be
	v_fmaak_f32 v2, v1, v2, 0xbec09330
	v_fmaak_f32 v1, v1, v2, 0x3e0375d0
	v_fma_f32 v1, |v0|, v1, |v0|
	s_or_b64 exec, exec, s[74:75]
	v_bfi_b32 v0, s13, v1, v0
	v_ashrrev_i32_e32 v5, 31, v4
	v_mul_f32_e32 v2, 0.5, v3
	v_add_f32_e32 v0, 1.0, v0
	v_mul_f32_e32 v2, v2, v0
	v_lshlrev_b64 v[0:1], 11, v[4:5]
	v_cmp_eq_u32_e32 vcc, 31, v75
	v_lshl_add_u64 v[0:1], v[72:73], 0, v[0:1]
	s_and_b64 s[14:15], vcc, s[4:5]
	global_store_dword v[0:1], v2, off
	v_cvt_pk_bf16_f32 v248, v2, v2
	global_store_short v[246:247], v248, off
	s_and_saveexec_b64 s[36:37], s[14:15]
	s_xor_b64 s[74:75], exec, s[36:37]
	s_cbranch_execz .LBB0_466
	v_mul_f32_e32 v2, v80, v61
	v_cndmask_b32_e64 v0, v56, v58, s[4:5]
	v_fma_f32 v2, v79, v60, -v2
	v_add_f32_e32 v8, v0, v2
	v_mul_f32_e32 v0, v80, v60
	v_cndmask_b32_e64 v1, v57, v59, s[4:5]
	v_fmac_f32_e32 v0, v79, v61
	v_mul_f32_e32 v2, v78, v13
	v_add_f32_e32 v12, v1, v0
	v_cndmask_b32_e64 v0, v6, v9, s[4:5]
	v_fma_f32 v2, v77, v11, -v2
	v_add_f32_e32 v6, v0, v2
	v_mul_f32_e32 v0, v78, v11
	v_cndmask_b32_e64 v1, v7, v10, s[4:5]
	v_fmac_f32_e32 v0, v77, v13
	v_add_f32_e32 v7, v1, v0
	v_or_b32_e32 v0, v74, v76
	v_ashrrev_i32_e32 v1, 31, v0
	v_lshlrev_b64 v[0:1], 2, v[0:1]
	v_lshl_add_u64 v[2:3], s[56:57], 0, v[0:1]
	v_lshlrev_b32_e32 v112, 2, v96
	v_lshl_add_u64 v[4:5], v[2:3], 0, v[112:113]
	global_store_dword v[4:5], v8, off
	v_lshlrev_b32_e32 v4, 2, v124
	v_mov_b32_e32 v5, v113
	v_lshl_add_u64 v[2:3], v[2:3], 0, v[4:5]
	v_lshl_add_u64 v[0:1], s[58:59], 0, v[0:1]
	global_store_dword v[2:3], v6, off
	v_lshl_add_u64 v[2:3], v[0:1], 0, v[112:113]
	v_lshl_add_u64 v[0:1], v[0:1], 0, v[4:5]
	global_store_dword v[2:3], v12, off
	global_store_dword v[0:1], v7, off
	s_branch .LBB0_466

.LBB0_665:
	s_and_b64 vcc, exec, s[10:11]
	s_cbranch_vccz .LBB0_646
	s_ashr_i32 s10, s22, 31
	s_lshr_b32 s10, s10, 30
	s_add_i32 s11, s22, s10
	s_lshl_b32 s10, s11, 5
	s_and_b32 s10, s10, 0xffffff80
	v_add_u32_e32 v0, s10, v105
	v_ashrrev_i32_e32 v1, 31, v0
	v_lshlrev_b64 v[0:1], 11, v[0:1]
	v_lshl_add_u64 v[74:75], v[68:69], 0, v[0:1]
	s_and_b32 s11, s11, 0x1fffffc
	s_sub_i32 s11, s22, s11
	s_lshl_b32 s11, s11, 7
	v_add_u32_e32 v0, s11, v105
	v_ashrrev_i32_e32 v1, 31, v0
	v_lshlrev_b64 v[0:1], 10, v[0:1]
	v_lshl_add_u64 v[76:77], v[70:71], 0, v[0:1]
	v_readlane_b32 s98, v238, 32
	v_readlane_b32 s99, v238, 33
	v_readfirstlane_b32 s100, v70
	v_readfirstlane_b32 s101, v71
	s_mul_i32 s12, s10, 0x1200
	s_add_u32 s98, s98, s12
	s_addc_u32 s99, s99, 0
	s_lshl_b32 s12, s11, 10
	s_add_u32 s100, s100, s12
	s_addc_u32 s101, s101, 0
	v_lshrrev_b32_e32 v246, 3, v100
	v_and_b32_e32 v247, 7, v100
	v_bfe_u32 v244, v100, 4, 3
	v_xor_b32_e32 v244, v244, v247
	v_lshlrev_b32_e32 v244, 4, v244
	v_lshl_or_b32 v195, v246, 7, v244
	v_lshlrev_b32_e32 v245, 4, v247
	v_mul_u32_u24_e32 v116, 0x1200, v246
	v_add_u32_e32 v116, v116, v245
	v_add_u32_e32 v122, 0x24000, v116
	v_add_u32_e32 v123, 0x48000, v116
	v_add_u32_e32 v124, 0x6c000, v116
	v_mul_u32_u24_e32 v150, 0x400, v246
	v_add_u32_e32 v150, v150, v245
	v_add_u32_e32 v151, 0x8000, v150
	v_add_u32_e32 v153, 0x10000, v150
	v_add_u32_e32 v194, 0x18000, v150
	v_and_b32_e32 v244, 15, v100
	v_bfe_u32 v245, v100, 4, 2
	v_bfe_u32 v246, v100, 1, 3
	v_xor_b32_e32 v247, v245, v246
	v_lshlrev_b32_e32 v247, 4, v247
	v_lshl_or_b32 v247, v244, 7, v247
	v_bfe_u32 v246, v100, 7, 1
	v_lshl_add_u32 v239, v246, 13, v247
	v_xor_b32_e32 v240, 64, v239
	v_bfe_u32 v246, v100, 6, 1
	v_lshl_add_u32 v241, v246, 13, v247
	v_add_u32_e32 v241, 0x4000, v241
	v_xor_b32_e32 v242, 64, v241
	v_bfe_u32 v247, v100, 7, 1
	v_lshlrev_b32_e32 v247, 6, v247
	v_lshl_add_u32 v247, v245, 2, v247
	v_mul_u32_u24_e32 v247, 0x84, v247
	v_lshl_add_u32 v247, v246, 6, v247
	v_add_u32_e32 v247, v247, v244
	v_lshlrev_b32_e32 v243, 2, v247
	global_load_dwordx4 v[178:181], v116, s[98:99]
	global_load_dwordx4 v[182:185], v122, s[98:99]
	global_load_dwordx4 v[186:189], v123, s[98:99]
	global_load_dwordx4 v[190:193], v124, s[98:99]
	global_load_dwordx4 v[220:223], v150, s[100:101]
	global_load_dwordx4 v[224:227], v151, s[100:101]
	global_load_dwordx4 v[228:231], v153, s[100:101]
	global_load_dwordx4 v[232:235], v194, s[100:101]
	v_readlane_b32 s52, v238, 32
	v_readlane_b32 s53, v238, 33
	v_readlane_b32 s54, v238, 34
	v_readlane_b32 s55, v238, 35
	v_readlane_b32 s56, v238, 36
	v_readlane_b32 s57, v238, 37
	v_readlane_b32 s58, v238, 38
	v_readlane_b32 s59, v238, 39
	v_readlane_b32 s60, v238, 40
	v_readlane_b32 s61, v238, 41
	v_readlane_b32 s62, v238, 42
	v_readlane_b32 s63, v238, 43
	v_readlane_b32 s64, v238, 44
	v_readlane_b32 s65, v238, 45
	v_readlane_b32 s66, v238, 46
	v_readlane_b32 s67, v238, 47
	s_mov_b32 s14, 0
	v_add_u32_e32 v66, v81, v148
	s_barrier
	s_waitcnt vmcnt(0)
	ds_write_b128 v195, v[178:181]
	ds_write_b128 v195, v[182:185] offset:4096
	ds_write_b128 v195, v[186:189] offset:8192
	ds_write_b128 v195, v[190:193] offset:12288
	ds_write_b128 v195, v[220:223] offset:16384
	ds_write_b128 v195, v[224:227] offset:20480
	ds_write_b128 v195, v[228:231] offset:24576
	ds_write_b128 v195, v[232:235] offset:28672
	global_load_dwordx4 v[178:181], v116, s[98:99] offset:128
	global_load_dwordx4 v[182:185], v122, s[98:99] offset:128
	global_load_dwordx4 v[186:189], v123, s[98:99] offset:128
	global_load_dwordx4 v[190:193], v124, s[98:99] offset:128
	global_load_dwordx4 v[220:223], v150, s[100:101] offset:128
	global_load_dwordx4 v[224:227], v151, s[100:101] offset:128
	global_load_dwordx4 v[228:231], v153, s[100:101] offset:128
	global_load_dwordx4 v[232:235], v194, s[100:101] offset:128
	s_waitcnt lgkmcnt(0)
	s_barrier
	ds_read_b128 v[112:115], v239
	ds_read_b128 v[134:137], v241
	ds_read_b128 v[138:141], v241 offset:2048
	ds_read_b128 v[142:145], v241 offset:4096
	ds_read_b128 v[154:157], v241 offset:6144
	ds_read_b128 v[118:121], v239 offset:2048
	ds_read_b128 v[126:129], v239 offset:4096
	ds_read_b128 v[130:133], v239 offset:6144
	s_waitcnt lgkmcnt(6)
	v_mfma_f32_16x16x32_bf16 v[0:3], v[112:115], v[134:137], 0
	ds_read_b128 v[158:161], v240
	s_waitcnt lgkmcnt(6)
	v_mfma_f32_16x16x32_bf16 v[4:7], v[112:115], v[138:141], 0
	ds_read_b128 v[166:169], v242
	s_waitcnt lgkmcnt(6)
	v_mfma_f32_16x16x32_bf16 v[8:11], v[112:115], v[142:145], 0
	ds_read_b128 v[170:173], v242 offset:2048
	s_waitcnt lgkmcnt(6)
	v_mfma_f32_16x16x32_bf16 v[12:15], v[112:115], v[154:157], 0
	ds_read_b128 v[174:177], v242 offset:4096
	s_waitcnt lgkmcnt(6)
	v_mfma_f32_16x16x32_bf16 v[16:19], v[118:121], v[134:137], 0
	ds_read_b128 v[252:255], v242 offset:6144
	v_mfma_f32_16x16x32_bf16 v[20:23], v[118:121], v[138:141], 0
	ds_read_b128 v[162:165], v240 offset:2048
	v_mfma_f32_16x16x32_bf16 v[24:27], v[118:121], v[142:145], 0
	ds_read_b128 v[244:247], v240 offset:4096
	v_mfma_f32_16x16x32_bf16 v[28:31], v[118:121], v[154:157], 0
	ds_read_b128 v[248:251], v240 offset:6144
	s_waitcnt lgkmcnt(9)
	v_mfma_f32_16x16x32_bf16 v[32:35], v[126:129], v[134:137], 0
	v_mfma_f32_16x16x32_bf16 v[36:39], v[126:129], v[138:141], 0
	v_mfma_f32_16x16x32_bf16 v[40:43], v[126:129], v[142:145], 0
	v_mfma_f32_16x16x32_bf16 v[44:47], v[126:129], v[154:157], 0
	s_waitcnt lgkmcnt(8)
	v_mfma_f32_16x16x32_bf16 v[48:51], v[130:133], v[134:137], 0
	v_mfma_f32_16x16x32_bf16 v[52:55], v[130:133], v[138:141], 0
	v_mfma_f32_16x16x32_bf16 v[56:59], v[130:133], v[142:145], 0
	v_mfma_f32_16x16x32_bf16 v[60:63], v[130:133], v[154:157], 0
	s_waitcnt lgkmcnt(6)
	v_mfma_f32_16x16x32_bf16 v[0:3], v[158:161], v[166:169], v[0:3]
	s_waitcnt vmcnt(0)
	ds_write_b128 v195, v[178:181] offset:32768
	s_waitcnt lgkmcnt(6)
	v_mfma_f32_16x16x32_bf16 v[4:7], v[158:161], v[170:173], v[4:7]
	ds_write_b128 v195, v[182:185] offset:36864
	s_waitcnt lgkmcnt(6)
	v_mfma_f32_16x16x32_bf16 v[8:11], v[158:161], v[174:177], v[8:11]
	ds_write_b128 v195, v[186:189] offset:40960
	s_waitcnt lgkmcnt(6)
	v_mfma_f32_16x16x32_bf16 v[12:15], v[158:161], v[252:255], v[12:15]
	ds_write_b128 v195, v[190:193] offset:45056
	s_waitcnt lgkmcnt(6)
	v_mfma_f32_16x16x32_bf16 v[16:19], v[162:165], v[166:169], v[16:19]
	ds_write_b128 v195, v[220:223] offset:49152
	v_mfma_f32_16x16x32_bf16 v[20:23], v[162:165], v[170:173], v[20:23]
	ds_write_b128 v195, v[224:227] offset:53248
	v_mfma_f32_16x16x32_bf16 v[24:27], v[162:165], v[174:177], v[24:27]
	ds_write_b128 v195, v[228:231] offset:57344
	v_mfma_f32_16x16x32_bf16 v[28:31], v[162:165], v[252:255], v[28:31]
	ds_write_b128 v195, v[232:235] offset:61440
	s_waitcnt lgkmcnt(9)
	v_mfma_f32_16x16x32_bf16 v[32:35], v[244:247], v[166:169], v[32:35]
	global_load_dwordx4 v[178:181], v116, s[98:99] offset:256
	v_mfma_f32_16x16x32_bf16 v[36:39], v[244:247], v[170:173], v[36:39]
	global_load_dwordx4 v[182:185], v122, s[98:99] offset:256
	v_mfma_f32_16x16x32_bf16 v[40:43], v[244:247], v[174:177], v[40:43]
	global_load_dwordx4 v[186:189], v123, s[98:99] offset:256
	v_mfma_f32_16x16x32_bf16 v[44:47], v[244:247], v[252:255], v[44:47]
	global_load_dwordx4 v[190:193], v124, s[98:99] offset:256
	s_waitcnt lgkmcnt(8)
	v_mfma_f32_16x16x32_bf16 v[48:51], v[248:251], v[166:169], v[48:51]
	global_load_dwordx4 v[220:223], v150, s[100:101] offset:256
	v_mfma_f32_16x16x32_bf16 v[52:55], v[248:251], v[170:173], v[52:55]
	global_load_dwordx4 v[224:227], v151, s[100:101] offset:256
	v_mfma_f32_16x16x32_bf16 v[56:59], v[248:251], v[174:177], v[56:59]
	global_load_dwordx4 v[228:231], v153, s[100:101] offset:256
	v_mfma_f32_16x16x32_bf16 v[60:63], v[248:251], v[252:255], v[60:63]
	global_load_dwordx4 v[232:235], v194, s[100:101] offset:256
	s_waitcnt lgkmcnt(0)
	s_barrier
	ds_read_b128 v[112:115], v239 offset:32768
	ds_read_b128 v[134:137], v241 offset:32768
	ds_read_b128 v[138:141], v241 offset:34816
	ds_read_b128 v[142:145], v241 offset:36864
	ds_read_b128 v[154:157], v241 offset:38912
	ds_read_b128 v[118:121], v239 offset:34816
	ds_read_b128 v[126:129], v239 offset:36864
	ds_read_b128 v[130:133], v239 offset:38912
	s_waitcnt lgkmcnt(6)
	v_mfma_f32_16x16x32_bf16 v[0:3], v[112:115], v[134:137], v[0:3]
	ds_read_b128 v[158:161], v240 offset:32768
	s_waitcnt lgkmcnt(6)
	v_mfma_f32_16x16x32_bf16 v[4:7], v[112:115], v[138:141], v[4:7]
	ds_read_b128 v[166:169], v242 offset:32768
	s_waitcnt lgkmcnt(6)
	v_mfma_f32_16x16x32_bf16 v[8:11], v[112:115], v[142:145], v[8:11]
	ds_read_b128 v[170:173], v242 offset:34816
	s_waitcnt lgkmcnt(6)
	v_mfma_f32_16x16x32_bf16 v[12:15], v[112:115], v[154:157], v[12:15]
	ds_read_b128 v[174:177], v242 offset:36864
	s_waitcnt lgkmcnt(6)
	v_mfma_f32_16x16x32_bf16 v[16:19], v[118:121], v[134:137], v[16:19]
	ds_read_b128 v[252:255], v242 offset:38912
	v_mfma_f32_16x16x32_bf16 v[20:23], v[118:121], v[138:141], v[20:23]
	ds_read_b128 v[162:165], v240 offset:34816
	v_mfma_f32_16x16x32_bf16 v[24:27], v[118:121], v[142:145], v[24:27]
	ds_read_b128 v[244:247], v240 offset:36864
	v_mfma_f32_16x16x32_bf16 v[28:31], v[118:121], v[154:157], v[28:31]
	ds_read_b128 v[248:251], v240 offset:38912
	s_waitcnt lgkmcnt(9)
	v_mfma_f32_16x16x32_bf16 v[32:35], v[126:129], v[134:137], v[32:35]
	v_mfma_f32_16x16x32_bf16 v[36:39], v[126:129], v[138:141], v[36:39]
	v_mfma_f32_16x16x32_bf16 v[40:43], v[126:129], v[142:145], v[40:43]
	v_mfma_f32_16x16x32_bf16 v[44:47], v[126:129], v[154:157], v[44:47]
	s_waitcnt lgkmcnt(8)
	v_mfma_f32_16x16x32_bf16 v[48:51], v[130:133], v[134:137], v[48:51]
	v_mfma_f32_16x16x32_bf16 v[52:55], v[130:133], v[138:141], v[52:55]
	v_mfma_f32_16x16x32_bf16 v[56:59], v[130:133], v[142:145], v[56:59]
	v_mfma_f32_16x16x32_bf16 v[60:63], v[130:133], v[154:157], v[60:63]
	s_waitcnt lgkmcnt(6)
	v_mfma_f32_16x16x32_bf16 v[0:3], v[158:161], v[166:169], v[0:3]
	s_waitcnt vmcnt(0)
	ds_write_b128 v195, v[178:181]
	s_waitcnt lgkmcnt(6)
	v_mfma_f32_16x16x32_bf16 v[4:7], v[158:161], v[170:173], v[4:7]
	ds_write_b128 v195, v[182:185] offset:4096
	s_waitcnt lgkmcnt(6)
	v_mfma_f32_16x16x32_bf16 v[8:11], v[158:161], v[174:177], v[8:11]
	ds_write_b128 v195, v[186:189] offset:8192
	s_waitcnt lgkmcnt(6)
	v_mfma_f32_16x16x32_bf16 v[12:15], v[158:161], v[252:255], v[12:15]
	ds_write_b128 v195, v[190:193] offset:12288
	s_waitcnt lgkmcnt(6)
	v_mfma_f32_16x16x32_bf16 v[16:19], v[162:165], v[166:169], v[16:19]
	ds_write_b128 v195, v[220:223] offset:16384
	v_mfma_f32_16x16x32_bf16 v[20:23], v[162:165], v[170:173], v[20:23]
	ds_write_b128 v195, v[224:227] offset:20480
	v_mfma_f32_16x16x32_bf16 v[24:27], v[162:165], v[174:177], v[24:27]
	ds_write_b128 v195, v[228:231] offset:24576
	v_mfma_f32_16x16x32_bf16 v[28:31], v[162:165], v[252:255], v[28:31]
	ds_write_b128 v195, v[232:235] offset:28672
	s_waitcnt lgkmcnt(9)
	v_mfma_f32_16x16x32_bf16 v[32:35], v[244:247], v[166:169], v[32:35]
	global_load_dwordx4 v[178:181], v116, s[98:99] offset:384
	v_mfma_f32_16x16x32_bf16 v[36:39], v[244:247], v[170:173], v[36:39]
	global_load_dwordx4 v[182:185], v122, s[98:99] offset:384
	v_mfma_f32_16x16x32_bf16 v[40:43], v[244:247], v[174:177], v[40:43]
	global_load_dwordx4 v[186:189], v123, s[98:99] offset:384
	v_mfma_f32_16x16x32_bf16 v[44:47], v[244:247], v[252:255], v[44:47]
	global_load_dwordx4 v[190:193], v124, s[98:99] offset:384
	s_waitcnt lgkmcnt(8)
	v_mfma_f32_16x16x32_bf16 v[48:51], v[248:251], v[166:169], v[48:51]
	global_load_dwordx4 v[220:223], v150, s[100:101] offset:384
	v_mfma_f32_16x16x32_bf16 v[52:55], v[248:251], v[170:173], v[52:55]
	global_load_dwordx4 v[224:227], v151, s[100:101] offset:384
	v_mfma_f32_16x16x32_bf16 v[56:59], v[248:251], v[174:177], v[56:59]
	global_load_dwordx4 v[228:231], v153, s[100:101] offset:384
	v_mfma_f32_16x16x32_bf16 v[60:63], v[248:251], v[252:255], v[60:63]
	global_load_dwordx4 v[232:235], v194, s[100:101] offset:384
	s_waitcnt lgkmcnt(0)
	s_barrier
	ds_read_b128 v[112:115], v239
	ds_read_b128 v[134:137], v241
	ds_read_b128 v[138:141], v241 offset:2048
	ds_read_b128 v[142:145], v241 offset:4096
	ds_read_b128 v[154:157], v241 offset:6144
	ds_read_b128 v[118:121], v239 offset:2048
	ds_read_b128 v[126:129], v239 offset:4096
	ds_read_b128 v[130:133], v239 offset:6144
	s_waitcnt lgkmcnt(6)
	v_mfma_f32_16x16x32_bf16 v[0:3], v[112:115], v[134:137], v[0:3]
	ds_read_b128 v[158:161], v240
	s_waitcnt lgkmcnt(6)
	v_mfma_f32_16x16x32_bf16 v[4:7], v[112:115], v[138:141], v[4:7]
	ds_read_b128 v[166:169], v242
	s_waitcnt lgkmcnt(6)
	v_mfma_f32_16x16x32_bf16 v[8:11], v[112:115], v[142:145], v[8:11]
	ds_read_b128 v[170:173], v242 offset:2048
	s_waitcnt lgkmcnt(6)
	v_mfma_f32_16x16x32_bf16 v[12:15], v[112:115], v[154:157], v[12:15]
	ds_read_b128 v[174:177], v242 offset:4096
	s_waitcnt lgkmcnt(6)
	v_mfma_f32_16x16x32_bf16 v[16:19], v[118:121], v[134:137], v[16:19]
	ds_read_b128 v[252:255], v242 offset:6144
	v_mfma_f32_16x16x32_bf16 v[20:23], v[118:121], v[138:141], v[20:23]
	ds_read_b128 v[162:165], v240 offset:2048
	v_mfma_f32_16x16x32_bf16 v[24:27], v[118:121], v[142:145], v[24:27]
	ds_read_b128 v[244:247], v240 offset:4096
	v_mfma_f32_16x16x32_bf16 v[28:31], v[118:121], v[154:157], v[28:31]
	ds_read_b128 v[248:251], v240 offset:6144
	s_waitcnt lgkmcnt(9)
	v_mfma_f32_16x16x32_bf16 v[32:35], v[126:129], v[134:137], v[32:35]
	v_mfma_f32_16x16x32_bf16 v[36:39], v[126:129], v[138:141], v[36:39]
	v_mfma_f32_16x16x32_bf16 v[40:43], v[126:129], v[142:145], v[40:43]
	v_mfma_f32_16x16x32_bf16 v[44:47], v[126:129], v[154:157], v[44:47]
	s_waitcnt lgkmcnt(8)
	v_mfma_f32_16x16x32_bf16 v[48:51], v[130:133], v[134:137], v[48:51]
	v_mfma_f32_16x16x32_bf16 v[52:55], v[130:133], v[138:141], v[52:55]
	v_mfma_f32_16x16x32_bf16 v[56:59], v[130:133], v[142:145], v[56:59]
	v_mfma_f32_16x16x32_bf16 v[60:63], v[130:133], v[154:157], v[60:63]
	s_waitcnt lgkmcnt(6)
	v_mfma_f32_16x16x32_bf16 v[0:3], v[158:161], v[166:169], v[0:3]
	s_waitcnt vmcnt(0)
	ds_write_b128 v195, v[178:181] offset:32768
	s_waitcnt lgkmcnt(6)
	v_mfma_f32_16x16x32_bf16 v[4:7], v[158:161], v[170:173], v[4:7]
	ds_write_b128 v195, v[182:185] offset:36864
	s_waitcnt lgkmcnt(6)
	v_mfma_f32_16x16x32_bf16 v[8:11], v[158:161], v[174:177], v[8:11]
	ds_write_b128 v195, v[186:189] offset:40960
	s_waitcnt lgkmcnt(6)
	v_mfma_f32_16x16x32_bf16 v[12:15], v[158:161], v[252:255], v[12:15]
	ds_write_b128 v195, v[190:193] offset:45056
	s_waitcnt lgkmcnt(6)
	v_mfma_f32_16x16x32_bf16 v[16:19], v[162:165], v[166:169], v[16:19]
	ds_write_b128 v195, v[220:223] offset:49152
	v_mfma_f32_16x16x32_bf16 v[20:23], v[162:165], v[170:173], v[20:23]
	ds_write_b128 v195, v[224:227] offset:53248
	v_mfma_f32_16x16x32_bf16 v[24:27], v[162:165], v[174:177], v[24:27]
	ds_write_b128 v195, v[228:231] offset:57344
	v_mfma_f32_16x16x32_bf16 v[28:31], v[162:165], v[252:255], v[28:31]
	ds_write_b128 v195, v[232:235] offset:61440
	s_waitcnt lgkmcnt(9)
	v_mfma_f32_16x16x32_bf16 v[32:35], v[244:247], v[166:169], v[32:35]
	global_load_dwordx4 v[178:181], v116, s[98:99] offset:512
	v_mfma_f32_16x16x32_bf16 v[36:39], v[244:247], v[170:173], v[36:39]
	global_load_dwordx4 v[182:185], v122, s[98:99] offset:512
	v_mfma_f32_16x16x32_bf16 v[40:43], v[244:247], v[174:177], v[40:43]
	global_load_dwordx4 v[186:189], v123, s[98:99] offset:512
	v_mfma_f32_16x16x32_bf16 v[44:47], v[244:247], v[252:255], v[44:47]
	global_load_dwordx4 v[190:193], v124, s[98:99] offset:512
	s_waitcnt lgkmcnt(8)
	v_mfma_f32_16x16x32_bf16 v[48:51], v[248:251], v[166:169], v[48:51]
	global_load_dwordx4 v[220:223], v150, s[100:101] offset:512
	v_mfma_f32_16x16x32_bf16 v[52:55], v[248:251], v[170:173], v[52:55]
	global_load_dwordx4 v[224:227], v151, s[100:101] offset:512
	v_mfma_f32_16x16x32_bf16 v[56:59], v[248:251], v[174:177], v[56:59]
	global_load_dwordx4 v[228:231], v153, s[100:101] offset:512
	v_mfma_f32_16x16x32_bf16 v[60:63], v[248:251], v[252:255], v[60:63]
	global_load_dwordx4 v[232:235], v194, s[100:101] offset:512
	s_waitcnt lgkmcnt(0)
	s_barrier
	ds_read_b128 v[112:115], v239 offset:32768
	ds_read_b128 v[134:137], v241 offset:32768
	ds_read_b128 v[138:141], v241 offset:34816
	ds_read_b128 v[142:145], v241 offset:36864
	ds_read_b128 v[154:157], v241 offset:38912
	ds_read_b128 v[118:121], v239 offset:34816
	ds_read_b128 v[126:129], v239 offset:36864
	ds_read_b128 v[130:133], v239 offset:38912
	s_waitcnt lgkmcnt(6)
	v_mfma_f32_16x16x32_bf16 v[0:3], v[112:115], v[134:137], v[0:3]
	ds_read_b128 v[158:161], v240 offset:32768
	s_waitcnt lgkmcnt(6)
	v_mfma_f32_16x16x32_bf16 v[4:7], v[112:115], v[138:141], v[4:7]
	ds_read_b128 v[166:169], v242 offset:32768
	s_waitcnt lgkmcnt(6)
	v_mfma_f32_16x16x32_bf16 v[8:11], v[112:115], v[142:145], v[8:11]
	ds_read_b128 v[170:173], v242 offset:34816
	s_waitcnt lgkmcnt(6)
	v_mfma_f32_16x16x32_bf16 v[12:15], v[112:115], v[154:157], v[12:15]
	ds_read_b128 v[174:177], v242 offset:36864
	s_waitcnt lgkmcnt(6)
	v_mfma_f32_16x16x32_bf16 v[16:19], v[118:121], v[134:137], v[16:19]
	ds_read_b128 v[252:255], v242 offset:38912
	v_mfma_f32_16x16x32_bf16 v[20:23], v[118:121], v[138:141], v[20:23]
	ds_read_b128 v[162:165], v240 offset:34816
	v_mfma_f32_16x16x32_bf16 v[24:27], v[118:121], v[142:145], v[24:27]
	ds_read_b128 v[244:247], v240 offset:36864
	v_mfma_f32_16x16x32_bf16 v[28:31], v[118:121], v[154:157], v[28:31]
	ds_read_b128 v[248:251], v240 offset:38912
	s_waitcnt lgkmcnt(9)
	v_mfma_f32_16x16x32_bf16 v[32:35], v[126:129], v[134:137], v[32:35]
	v_mfma_f32_16x16x32_bf16 v[36:39], v[126:129], v[138:141], v[36:39]
	v_mfma_f32_16x16x32_bf16 v[40:43], v[126:129], v[142:145], v[40:43]
	v_mfma_f32_16x16x32_bf16 v[44:47], v[126:129], v[154:157], v[44:47]
	s_waitcnt lgkmcnt(8)
	v_mfma_f32_16x16x32_bf16 v[48:51], v[130:133], v[134:137], v[48:51]
	v_mfma_f32_16x16x32_bf16 v[52:55], v[130:133], v[138:141], v[52:55]
	v_mfma_f32_16x16x32_bf16 v[56:59], v[130:133], v[142:145], v[56:59]
	v_mfma_f32_16x16x32_bf16 v[60:63], v[130:133], v[154:157], v[60:63]
	s_waitcnt lgkmcnt(6)
	v_mfma_f32_16x16x32_bf16 v[0:3], v[158:161], v[166:169], v[0:3]
	s_waitcnt vmcnt(0)
	ds_write_b128 v195, v[178:181]
	s_waitcnt lgkmcnt(6)
	v_mfma_f32_16x16x32_bf16 v[4:7], v[158:161], v[170:173], v[4:7]
	ds_write_b128 v195, v[182:185] offset:4096
	s_waitcnt lgkmcnt(6)
	v_mfma_f32_16x16x32_bf16 v[8:11], v[158:161], v[174:177], v[8:11]
	ds_write_b128 v195, v[186:189] offset:8192
	s_waitcnt lgkmcnt(6)
	v_mfma_f32_16x16x32_bf16 v[12:15], v[158:161], v[252:255], v[12:15]
	ds_write_b128 v195, v[190:193] offset:12288
	s_waitcnt lgkmcnt(6)
	v_mfma_f32_16x16x32_bf16 v[16:19], v[162:165], v[166:169], v[16:19]
	ds_write_b128 v195, v[220:223] offset:16384
	v_mfma_f32_16x16x32_bf16 v[20:23], v[162:165], v[170:173], v[20:23]
	ds_write_b128 v195, v[224:227] offset:20480
	v_mfma_f32_16x16x32_bf16 v[24:27], v[162:165], v[174:177], v[24:27]
	ds_write_b128 v195, v[228:231] offset:24576
	v_mfma_f32_16x16x32_bf16 v[28:31], v[162:165], v[252:255], v[28:31]
	ds_write_b128 v195, v[232:235] offset:28672
	s_waitcnt lgkmcnt(9)
	v_mfma_f32_16x16x32_bf16 v[32:35], v[244:247], v[166:169], v[32:35]
	global_load_dwordx4 v[178:181], v116, s[98:99] offset:640
	v_mfma_f32_16x16x32_bf16 v[36:39], v[244:247], v[170:173], v[36:39]
	global_load_dwordx4 v[182:185], v122, s[98:99] offset:640
	v_mfma_f32_16x16x32_bf16 v[40:43], v[244:247], v[174:177], v[40:43]
	global_load_dwordx4 v[186:189], v123, s[98:99] offset:640
	v_mfma_f32_16x16x32_bf16 v[44:47], v[244:247], v[252:255], v[44:47]
	global_load_dwordx4 v[190:193], v124, s[98:99] offset:640
	s_waitcnt lgkmcnt(8)
	v_mfma_f32_16x16x32_bf16 v[48:51], v[248:251], v[166:169], v[48:51]
	global_load_dwordx4 v[220:223], v150, s[100:101] offset:640
	v_mfma_f32_16x16x32_bf16 v[52:55], v[248:251], v[170:173], v[52:55]
	global_load_dwordx4 v[224:227], v151, s[100:101] offset:640
	v_mfma_f32_16x16x32_bf16 v[56:59], v[248:251], v[174:177], v[56:59]
	global_load_dwordx4 v[228:231], v153, s[100:101] offset:640
	v_mfma_f32_16x16x32_bf16 v[60:63], v[248:251], v[252:255], v[60:63]
	global_load_dwordx4 v[232:235], v194, s[100:101] offset:640
	s_waitcnt lgkmcnt(0)
	s_barrier
	ds_read_b128 v[112:115], v239
	ds_read_b128 v[134:137], v241
	ds_read_b128 v[138:141], v241 offset:2048
	ds_read_b128 v[142:145], v241 offset:4096
	ds_read_b128 v[154:157], v241 offset:6144
	ds_read_b128 v[118:121], v239 offset:2048
	ds_read_b128 v[126:129], v239 offset:4096
	ds_read_b128 v[130:133], v239 offset:6144
	s_waitcnt lgkmcnt(6)
	v_mfma_f32_16x16x32_bf16 v[0:3], v[112:115], v[134:137], v[0:3]
	ds_read_b128 v[158:161], v240
	s_waitcnt lgkmcnt(6)
	v_mfma_f32_16x16x32_bf16 v[4:7], v[112:115], v[138:141], v[4:7]
	ds_read_b128 v[166:169], v242
	s_waitcnt lgkmcnt(6)
	v_mfma_f32_16x16x32_bf16 v[8:11], v[112:115], v[142:145], v[8:11]
	ds_read_b128 v[170:173], v242 offset:2048
	s_waitcnt lgkmcnt(6)
	v_mfma_f32_16x16x32_bf16 v[12:15], v[112:115], v[154:157], v[12:15]
	ds_read_b128 v[174:177], v242 offset:4096
	s_waitcnt lgkmcnt(6)
	v_mfma_f32_16x16x32_bf16 v[16:19], v[118:121], v[134:137], v[16:19]
	ds_read_b128 v[252:255], v242 offset:6144
	v_mfma_f32_16x16x32_bf16 v[20:23], v[118:121], v[138:141], v[20:23]
	ds_read_b128 v[162:165], v240 offset:2048
	v_mfma_f32_16x16x32_bf16 v[24:27], v[118:121], v[142:145], v[24:27]
	ds_read_b128 v[244:247], v240 offset:4096
	v_mfma_f32_16x16x32_bf16 v[28:31], v[118:121], v[154:157], v[28:31]
	ds_read_b128 v[248:251], v240 offset:6144
	s_waitcnt lgkmcnt(9)
	v_mfma_f32_16x16x32_bf16 v[32:35], v[126:129], v[134:137], v[32:35]
	v_mfma_f32_16x16x32_bf16 v[36:39], v[126:129], v[138:141], v[36:39]
	v_mfma_f32_16x16x32_bf16 v[40:43], v[126:129], v[142:145], v[40:43]
	v_mfma_f32_16x16x32_bf16 v[44:47], v[126:129], v[154:157], v[44:47]
	s_waitcnt lgkmcnt(8)
	v_mfma_f32_16x16x32_bf16 v[48:51], v[130:133], v[134:137], v[48:51]
	v_mfma_f32_16x16x32_bf16 v[52:55], v[130:133], v[138:141], v[52:55]
	v_mfma_f32_16x16x32_bf16 v[56:59], v[130:133], v[142:145], v[56:59]
	v_mfma_f32_16x16x32_bf16 v[60:63], v[130:133], v[154:157], v[60:63]
	s_waitcnt lgkmcnt(6)
	v_mfma_f32_16x16x32_bf16 v[0:3], v[158:161], v[166:169], v[0:3]
	s_waitcnt vmcnt(0)
	ds_write_b128 v195, v[178:181] offset:32768
	s_waitcnt lgkmcnt(6)
	v_mfma_f32_16x16x32_bf16 v[4:7], v[158:161], v[170:173], v[4:7]
	ds_write_b128 v195, v[182:185] offset:36864
	s_waitcnt lgkmcnt(6)
	v_mfma_f32_16x16x32_bf16 v[8:11], v[158:161], v[174:177], v[8:11]
	ds_write_b128 v195, v[186:189] offset:40960
	s_waitcnt lgkmcnt(6)
	v_mfma_f32_16x16x32_bf16 v[12:15], v[158:161], v[252:255], v[12:15]
	ds_write_b128 v195, v[190:193] offset:45056
	s_waitcnt lgkmcnt(6)
	v_mfma_f32_16x16x32_bf16 v[16:19], v[162:165], v[166:169], v[16:19]
	ds_write_b128 v195, v[220:223] offset:49152
	v_mfma_f32_16x16x32_bf16 v[20:23], v[162:165], v[170:173], v[20:23]
	ds_write_b128 v195, v[224:227] offset:53248
	v_mfma_f32_16x16x32_bf16 v[24:27], v[162:165], v[174:177], v[24:27]
	ds_write_b128 v195, v[228:231] offset:57344
	v_mfma_f32_16x16x32_bf16 v[28:31], v[162:165], v[252:255], v[28:31]
	ds_write_b128 v195, v[232:235] offset:61440
	s_waitcnt lgkmcnt(9)
	v_mfma_f32_16x16x32_bf16 v[32:35], v[244:247], v[166:169], v[32:35]
	global_load_dwordx4 v[178:181], v116, s[98:99] offset:768
	v_mfma_f32_16x16x32_bf16 v[36:39], v[244:247], v[170:173], v[36:39]
	global_load_dwordx4 v[182:185], v122, s[98:99] offset:768
	v_mfma_f32_16x16x32_bf16 v[40:43], v[244:247], v[174:177], v[40:43]
	global_load_dwordx4 v[186:189], v123, s[98:99] offset:768
	v_mfma_f32_16x16x32_bf16 v[44:47], v[244:247], v[252:255], v[44:47]
	global_load_dwordx4 v[190:193], v124, s[98:99] offset:768
	s_waitcnt lgkmcnt(8)
	v_mfma_f32_16x16x32_bf16 v[48:51], v[248:251], v[166:169], v[48:51]
	global_load_dwordx4 v[220:223], v150, s[100:101] offset:768
	v_mfma_f32_16x16x32_bf16 v[52:55], v[248:251], v[170:173], v[52:55]
	global_load_dwordx4 v[224:227], v151, s[100:101] offset:768
	v_mfma_f32_16x16x32_bf16 v[56:59], v[248:251], v[174:177], v[56:59]
	global_load_dwordx4 v[228:231], v153, s[100:101] offset:768
	v_mfma_f32_16x16x32_bf16 v[60:63], v[248:251], v[252:255], v[60:63]
	global_load_dwordx4 v[232:235], v194, s[100:101] offset:768
	s_waitcnt lgkmcnt(0)
	s_barrier
	ds_read_b128 v[112:115], v239 offset:32768
	ds_read_b128 v[134:137], v241 offset:32768
	ds_read_b128 v[138:141], v241 offset:34816
	ds_read_b128 v[142:145], v241 offset:36864
	ds_read_b128 v[154:157], v241 offset:38912
	ds_read_b128 v[118:121], v239 offset:34816
	ds_read_b128 v[126:129], v239 offset:36864
	ds_read_b128 v[130:133], v239 offset:38912
	s_waitcnt lgkmcnt(6)
	v_mfma_f32_16x16x32_bf16 v[0:3], v[112:115], v[134:137], v[0:3]
	ds_read_b128 v[158:161], v240 offset:32768
	s_waitcnt lgkmcnt(6)
	v_mfma_f32_16x16x32_bf16 v[4:7], v[112:115], v[138:141], v[4:7]
	ds_read_b128 v[166:169], v242 offset:32768
	s_waitcnt lgkmcnt(6)
	v_mfma_f32_16x16x32_bf16 v[8:11], v[112:115], v[142:145], v[8:11]
	ds_read_b128 v[170:173], v242 offset:34816
	s_waitcnt lgkmcnt(6)
	v_mfma_f32_16x16x32_bf16 v[12:15], v[112:115], v[154:157], v[12:15]
	ds_read_b128 v[174:177], v242 offset:36864
	s_waitcnt lgkmcnt(6)
	v_mfma_f32_16x16x32_bf16 v[16:19], v[118:121], v[134:137], v[16:19]
	ds_read_b128 v[252:255], v242 offset:38912
	v_mfma_f32_16x16x32_bf16 v[20:23], v[118:121], v[138:141], v[20:23]
	ds_read_b128 v[162:165], v240 offset:34816
	v_mfma_f32_16x16x32_bf16 v[24:27], v[118:121], v[142:145], v[24:27]
	ds_read_b128 v[244:247], v240 offset:36864
	v_mfma_f32_16x16x32_bf16 v[28:31], v[118:121], v[154:157], v[28:31]
	ds_read_b128 v[248:251], v240 offset:38912
	s_waitcnt lgkmcnt(9)
	v_mfma_f32_16x16x32_bf16 v[32:35], v[126:129], v[134:137], v[32:35]
	v_mfma_f32_16x16x32_bf16 v[36:39], v[126:129], v[138:141], v[36:39]
	v_mfma_f32_16x16x32_bf16 v[40:43], v[126:129], v[142:145], v[40:43]
	v_mfma_f32_16x16x32_bf16 v[44:47], v[126:129], v[154:157], v[44:47]
	s_waitcnt lgkmcnt(8)
	v_mfma_f32_16x16x32_bf16 v[48:51], v[130:133], v[134:137], v[48:51]
	v_mfma_f32_16x16x32_bf16 v[52:55], v[130:133], v[138:141], v[52:55]
	v_mfma_f32_16x16x32_bf16 v[56:59], v[130:133], v[142:145], v[56:59]
	v_mfma_f32_16x16x32_bf16 v[60:63], v[130:133], v[154:157], v[60:63]
	s_waitcnt lgkmcnt(6)
	v_mfma_f32_16x16x32_bf16 v[0:3], v[158:161], v[166:169], v[0:3]
	s_waitcnt vmcnt(0)
	ds_write_b128 v195, v[178:181]
	s_waitcnt lgkmcnt(6)
	v_mfma_f32_16x16x32_bf16 v[4:7], v[158:161], v[170:173], v[4:7]
	ds_write_b128 v195, v[182:185] offset:4096
	s_waitcnt lgkmcnt(6)
	v_mfma_f32_16x16x32_bf16 v[8:11], v[158:161], v[174:177], v[8:11]
	ds_write_b128 v195, v[186:189] offset:8192
	s_waitcnt lgkmcnt(6)
	v_mfma_f32_16x16x32_bf16 v[12:15], v[158:161], v[252:255], v[12:15]
	ds_write_b128 v195, v[190:193] offset:12288
	s_waitcnt lgkmcnt(6)
	v_mfma_f32_16x16x32_bf16 v[16:19], v[162:165], v[166:169], v[16:19]
	ds_write_b128 v195, v[220:223] offset:16384
	v_mfma_f32_16x16x32_bf16 v[20:23], v[162:165], v[170:173], v[20:23]
	ds_write_b128 v195, v[224:227] offset:20480
	v_mfma_f32_16x16x32_bf16 v[24:27], v[162:165], v[174:177], v[24:27]
	ds_write_b128 v195, v[228:231] offset:24576
	v_mfma_f32_16x16x32_bf16 v[28:31], v[162:165], v[252:255], v[28:31]
	ds_write_b128 v195, v[232:235] offset:28672
	s_waitcnt lgkmcnt(9)
	v_mfma_f32_16x16x32_bf16 v[32:35], v[244:247], v[166:169], v[32:35]
	global_load_dwordx4 v[178:181], v116, s[98:99] offset:896
	v_mfma_f32_16x16x32_bf16 v[36:39], v[244:247], v[170:173], v[36:39]
	global_load_dwordx4 v[182:185], v122, s[98:99] offset:896
	v_mfma_f32_16x16x32_bf16 v[40:43], v[244:247], v[174:177], v[40:43]
	global_load_dwordx4 v[186:189], v123, s[98:99] offset:896
	v_mfma_f32_16x16x32_bf16 v[44:47], v[244:247], v[252:255], v[44:47]
	global_load_dwordx4 v[190:193], v124, s[98:99] offset:896
	s_waitcnt lgkmcnt(8)
	v_mfma_f32_16x16x32_bf16 v[48:51], v[248:251], v[166:169], v[48:51]
	global_load_dwordx4 v[220:223], v150, s[100:101] offset:896
	v_mfma_f32_16x16x32_bf16 v[52:55], v[248:251], v[170:173], v[52:55]
	global_load_dwordx4 v[224:227], v151, s[100:101] offset:896
	v_mfma_f32_16x16x32_bf16 v[56:59], v[248:251], v[174:177], v[56:59]
	global_load_dwordx4 v[228:231], v153, s[100:101] offset:896
	v_mfma_f32_16x16x32_bf16 v[60:63], v[248:251], v[252:255], v[60:63]
	global_load_dwordx4 v[232:235], v194, s[100:101] offset:896
	s_waitcnt lgkmcnt(0)
	s_barrier
	ds_read_b128 v[112:115], v239
	ds_read_b128 v[134:137], v241
	ds_read_b128 v[138:141], v241 offset:2048
	ds_read_b128 v[142:145], v241 offset:4096
	ds_read_b128 v[154:157], v241 offset:6144
	ds_read_b128 v[118:121], v239 offset:2048
	ds_read_b128 v[126:129], v239 offset:4096
	ds_read_b128 v[130:133], v239 offset:6144
	s_waitcnt lgkmcnt(6)
	v_mfma_f32_16x16x32_bf16 v[0:3], v[112:115], v[134:137], v[0:3]
	ds_read_b128 v[158:161], v240
	s_waitcnt lgkmcnt(6)
	v_mfma_f32_16x16x32_bf16 v[4:7], v[112:115], v[138:141], v[4:7]
	ds_read_b128 v[166:169], v242
	s_waitcnt lgkmcnt(6)
	v_mfma_f32_16x16x32_bf16 v[8:11], v[112:115], v[142:145], v[8:11]
	ds_read_b128 v[170:173], v242 offset:2048
	s_waitcnt lgkmcnt(6)
	v_mfma_f32_16x16x32_bf16 v[12:15], v[112:115], v[154:157], v[12:15]
	ds_read_b128 v[174:177], v242 offset:4096
	s_waitcnt lgkmcnt(6)
	v_mfma_f32_16x16x32_bf16 v[16:19], v[118:121], v[134:137], v[16:19]
	ds_read_b128 v[252:255], v242 offset:6144
	v_mfma_f32_16x16x32_bf16 v[20:23], v[118:121], v[138:141], v[20:23]
	ds_read_b128 v[162:165], v240 offset:2048
	v_mfma_f32_16x16x32_bf16 v[24:27], v[118:121], v[142:145], v[24:27]
	ds_read_b128 v[244:247], v240 offset:4096
	v_mfma_f32_16x16x32_bf16 v[28:31], v[118:121], v[154:157], v[28:31]
	ds_read_b128 v[248:251], v240 offset:6144
	s_waitcnt lgkmcnt(9)
	v_mfma_f32_16x16x32_bf16 v[32:35], v[126:129], v[134:137], v[32:35]
	v_mfma_f32_16x16x32_bf16 v[36:39], v[126:129], v[138:141], v[36:39]
	v_mfma_f32_16x16x32_bf16 v[40:43], v[126:129], v[142:145], v[40:43]
	v_mfma_f32_16x16x32_bf16 v[44:47], v[126:129], v[154:157], v[44:47]
	s_waitcnt lgkmcnt(8)
	v_mfma_f32_16x16x32_bf16 v[48:51], v[130:133], v[134:137], v[48:51]
	v_mfma_f32_16x16x32_bf16 v[52:55], v[130:133], v[138:141], v[52:55]
	v_mfma_f32_16x16x32_bf16 v[56:59], v[130:133], v[142:145], v[56:59]
	v_mfma_f32_16x16x32_bf16 v[60:63], v[130:133], v[154:157], v[60:63]
	s_waitcnt lgkmcnt(6)
	v_mfma_f32_16x16x32_bf16 v[0:3], v[158:161], v[166:169], v[0:3]
	s_waitcnt vmcnt(0)
	ds_write_b128 v195, v[178:181] offset:32768
	s_waitcnt lgkmcnt(6)
	v_mfma_f32_16x16x32_bf16 v[4:7], v[158:161], v[170:173], v[4:7]
	ds_write_b128 v195, v[182:185] offset:36864
	s_waitcnt lgkmcnt(6)
	v_mfma_f32_16x16x32_bf16 v[8:11], v[158:161], v[174:177], v[8:11]
	ds_write_b128 v195, v[186:189] offset:40960
	s_waitcnt lgkmcnt(6)
	v_mfma_f32_16x16x32_bf16 v[12:15], v[158:161], v[252:255], v[12:15]
	ds_write_b128 v195, v[190:193] offset:45056
	s_waitcnt lgkmcnt(6)
	v_mfma_f32_16x16x32_bf16 v[16:19], v[162:165], v[166:169], v[16:19]
	ds_write_b128 v195, v[220:223] offset:49152
	v_mfma_f32_16x16x32_bf16 v[20:23], v[162:165], v[170:173], v[20:23]
	ds_write_b128 v195, v[224:227] offset:53248
	v_mfma_f32_16x16x32_bf16 v[24:27], v[162:165], v[174:177], v[24:27]
	ds_write_b128 v195, v[228:231] offset:57344
	v_mfma_f32_16x16x32_bf16 v[28:31], v[162:165], v[252:255], v[28:31]
	ds_write_b128 v195, v[232:235] offset:61440
	s_waitcnt lgkmcnt(9)
	v_mfma_f32_16x16x32_bf16 v[32:35], v[244:247], v[166:169], v[32:35]
	v_mfma_f32_16x16x32_bf16 v[36:39], v[244:247], v[170:173], v[36:39]
	v_mfma_f32_16x16x32_bf16 v[40:43], v[244:247], v[174:177], v[40:43]
	v_mfma_f32_16x16x32_bf16 v[44:47], v[244:247], v[252:255], v[44:47]
	s_waitcnt lgkmcnt(8)
	v_mfma_f32_16x16x32_bf16 v[48:51], v[248:251], v[166:169], v[48:51]
	v_mfma_f32_16x16x32_bf16 v[52:55], v[248:251], v[170:173], v[52:55]
	v_mfma_f32_16x16x32_bf16 v[56:59], v[248:251], v[174:177], v[56:59]
	v_mfma_f32_16x16x32_bf16 v[60:63], v[248:251], v[252:255], v[60:63]
	s_waitcnt lgkmcnt(0)
	s_barrier
	ds_read_b128 v[112:115], v239 offset:32768
	ds_read_b128 v[134:137], v241 offset:32768
	ds_read_b128 v[138:141], v241 offset:34816
	ds_read_b128 v[142:145], v241 offset:36864
	ds_read_b128 v[154:157], v241 offset:38912
	ds_read_b128 v[118:121], v239 offset:34816
	ds_read_b128 v[126:129], v239 offset:36864
	ds_read_b128 v[130:133], v239 offset:38912
	s_waitcnt lgkmcnt(6)
	v_mfma_f32_16x16x32_bf16 v[0:3], v[112:115], v[134:137], v[0:3]
	ds_read_b128 v[158:161], v240 offset:32768
	s_waitcnt lgkmcnt(6)
	v_mfma_f32_16x16x32_bf16 v[4:7], v[112:115], v[138:141], v[4:7]
	ds_read_b128 v[166:169], v242 offset:32768
	s_waitcnt lgkmcnt(6)
	v_mfma_f32_16x16x32_bf16 v[8:11], v[112:115], v[142:145], v[8:11]
	ds_read_b128 v[170:173], v242 offset:34816
	s_waitcnt lgkmcnt(6)
	v_mfma_f32_16x16x32_bf16 v[12:15], v[112:115], v[154:157], v[12:15]
	ds_read_b128 v[174:177], v242 offset:36864
	s_waitcnt lgkmcnt(6)
	v_mfma_f32_16x16x32_bf16 v[16:19], v[118:121], v[134:137], v[16:19]
	ds_read_b128 v[252:255], v242 offset:38912
	v_mfma_f32_16x16x32_bf16 v[20:23], v[118:121], v[138:141], v[20:23]
	ds_read_b128 v[162:165], v240 offset:34816
	v_mfma_f32_16x16x32_bf16 v[24:27], v[118:121], v[142:145], v[24:27]
	ds_read_b128 v[244:247], v240 offset:36864
	v_mfma_f32_16x16x32_bf16 v[28:31], v[118:121], v[154:157], v[28:31]
	ds_read_b128 v[248:251], v240 offset:38912
	s_waitcnt lgkmcnt(9)
	v_mfma_f32_16x16x32_bf16 v[32:35], v[126:129], v[134:137], v[32:35]
	v_mfma_f32_16x16x32_bf16 v[36:39], v[126:129], v[138:141], v[36:39]
	v_mfma_f32_16x16x32_bf16 v[40:43], v[126:129], v[142:145], v[40:43]
	v_mfma_f32_16x16x32_bf16 v[44:47], v[126:129], v[154:157], v[44:47]
	s_waitcnt lgkmcnt(8)
	v_mfma_f32_16x16x32_bf16 v[48:51], v[130:133], v[134:137], v[48:51]
	v_mfma_f32_16x16x32_bf16 v[52:55], v[130:133], v[138:141], v[52:55]
	v_mfma_f32_16x16x32_bf16 v[56:59], v[130:133], v[142:145], v[56:59]
	v_mfma_f32_16x16x32_bf16 v[60:63], v[130:133], v[154:157], v[60:63]
	s_waitcnt lgkmcnt(6)
	v_mfma_f32_16x16x32_bf16 v[0:3], v[158:161], v[166:169], v[0:3]
	s_waitcnt lgkmcnt(5)
	v_mfma_f32_16x16x32_bf16 v[4:7], v[158:161], v[170:173], v[4:7]
	s_waitcnt lgkmcnt(4)
	v_mfma_f32_16x16x32_bf16 v[8:11], v[158:161], v[174:177], v[8:11]
	s_waitcnt lgkmcnt(3)
	v_mfma_f32_16x16x32_bf16 v[12:15], v[158:161], v[252:255], v[12:15]
	s_waitcnt lgkmcnt(2)
	v_mfma_f32_16x16x32_bf16 v[16:19], v[162:165], v[166:169], v[16:19]
	v_mfma_f32_16x16x32_bf16 v[20:23], v[162:165], v[170:173], v[20:23]
	v_mfma_f32_16x16x32_bf16 v[24:27], v[162:165], v[174:177], v[24:27]
	v_mfma_f32_16x16x32_bf16 v[28:31], v[162:165], v[252:255], v[28:31]
	s_waitcnt lgkmcnt(1)
	v_mfma_f32_16x16x32_bf16 v[32:35], v[244:247], v[166:169], v[32:35]
	v_mfma_f32_16x16x32_bf16 v[36:39], v[244:247], v[170:173], v[36:39]
	v_mfma_f32_16x16x32_bf16 v[40:43], v[244:247], v[174:177], v[40:43]
	v_mfma_f32_16x16x32_bf16 v[44:47], v[244:247], v[252:255], v[44:47]
	s_waitcnt lgkmcnt(0)
	v_mfma_f32_16x16x32_bf16 v[48:51], v[248:251], v[166:169], v[48:51]
	v_mfma_f32_16x16x32_bf16 v[52:55], v[248:251], v[170:173], v[52:55]
	v_mfma_f32_16x16x32_bf16 v[56:59], v[248:251], v[174:177], v[56:59]
	v_mfma_f32_16x16x32_bf16 v[60:63], v[248:251], v[252:255], v[60:63]
	s_waitcnt lgkmcnt(0)
	s_barrier
	s_nop 15
	ds_write_b32 v243, v0
	ds_write_b32 v243, v1 offset:528
	ds_write_b32 v243, v2 offset:1056
	ds_write_b32 v243, v3 offset:1584
	ds_write_b32 v243, v4 offset:64
	ds_write_b32 v243, v5 offset:592
	ds_write_b32 v243, v6 offset:1120
	ds_write_b32 v243, v7 offset:1648
	ds_write_b32 v243, v8 offset:128
	ds_write_b32 v243, v9 offset:656
	ds_write_b32 v243, v10 offset:1184
	ds_write_b32 v243, v11 offset:1712
	ds_write_b32 v243, v12 offset:192
	ds_write_b32 v243, v13 offset:720
	ds_write_b32 v243, v14 offset:1248
	ds_write_b32 v243, v15 offset:1776
	ds_write_b32 v243, v16 offset:8448
	ds_write_b32 v243, v17 offset:8976
	ds_write_b32 v243, v18 offset:9504
	ds_write_b32 v243, v19 offset:10032
	ds_write_b32 v243, v20 offset:8512
	ds_write_b32 v243, v21 offset:9040
	ds_write_b32 v243, v22 offset:9568
	ds_write_b32 v243, v23 offset:10096
	ds_write_b32 v243, v24 offset:8576
	ds_write_b32 v243, v25 offset:9104
	ds_write_b32 v243, v26 offset:9632
	ds_write_b32 v243, v27 offset:10160
	ds_write_b32 v243, v28 offset:8640
	ds_write_b32 v243, v29 offset:9168
	ds_write_b32 v243, v30 offset:9696
	ds_write_b32 v243, v31 offset:10224
	ds_write_b32 v243, v32 offset:16896
	ds_write_b32 v243, v33 offset:17424
	ds_write_b32 v243, v34 offset:17952
	ds_write_b32 v243, v35 offset:18480
	ds_write_b32 v243, v36 offset:16960
	ds_write_b32 v243, v37 offset:17488
	ds_write_b32 v243, v38 offset:18016
	ds_write_b32 v243, v39 offset:18544
	ds_write_b32 v243, v40 offset:17024
	ds_write_b32 v243, v41 offset:17552
	ds_write_b32 v243, v42 offset:18080
	ds_write_b32 v243, v43 offset:18608
	ds_write_b32 v243, v44 offset:17088
	ds_write_b32 v243, v45 offset:17616
	ds_write_b32 v243, v46 offset:18144
	ds_write_b32 v243, v47 offset:18672
	ds_write_b32 v243, v48 offset:25344
	ds_write_b32 v243, v49 offset:25872
	ds_write_b32 v243, v50 offset:26400
	ds_write_b32 v243, v51 offset:26928
	ds_write_b32 v243, v52 offset:25408
	ds_write_b32 v243, v53 offset:25936
	ds_write_b32 v243, v54 offset:26464
	ds_write_b32 v243, v55 offset:26992
	ds_write_b32 v243, v56 offset:25472
	ds_write_b32 v243, v57 offset:26000
	ds_write_b32 v243, v58 offset:26528
	ds_write_b32 v243, v59 offset:27056
	ds_write_b32 v243, v60 offset:25536
	ds_write_b32 v243, v61 offset:26064
	ds_write_b32 v243, v62 offset:26592
	ds_write_b32 v243, v63 offset:27120
	v_or_b32_e32 v0, s11, v82
	v_ashrrev_i32_e32 v1, 31, v0
	v_lshlrev_b64 v[2:3], 2, v[0:1]
	v_lshl_add_u64 v[8:9], s[62:63], 0, v[2:3]
	v_readlane_b32 s52, v236, 32
	v_readlane_b32 s66, v236, 46
	v_readlane_b32 s67, v236, 47
	v_lshl_add_u64 v[12:13], v[0:1], 1, s[50:51]
	v_or_b32_e32 v14, s10, v65
	v_lshl_add_u64 v[10:11], s[66:67], 0, v[2:3]
	v_or_b32_e32 v16, s10, v88
	v_or_b32_e32 v18, s10, v91
	v_or_b32_e32 v20, s10, v147
	s_waitcnt lgkmcnt(0)
	s_barrier
	v_readlane_b32 s53, v236, 33
	v_readlane_b32 s54, v236, 34
	v_readlane_b32 s55, v236, 35
	v_readlane_b32 s56, v236, 36
	v_readlane_b32 s57, v236, 37
	v_readlane_b32 s58, v236, 38
	v_readlane_b32 s59, v236, 39
	v_readlane_b32 s60, v236, 40
	v_readlane_b32 s61, v236, 41
	v_readlane_b32 s62, v236, 42
	v_readlane_b32 s63, v236, 43
	v_readlane_b32 s64, v236, 44
	v_readlane_b32 s65, v236, 45
